# v9 + gate/up and down K-loop load segments without VALU (saddr LDS-DMA, persistent ds_read base) + 8 idle slots at the head of every load segment so the partner's MFMA stream starts unobstructed
# speedup vs baseline: 1.0040x; 1.0040x over previous
.LBB0_697:
	s_add_u32 s24, s4, 0xfff00080
	s_addc_u32 s25, s5, -1
	s_add_i32 s33, 0, 0x10000
	s_cmp_eq_u32 s49, 60
	s_cselect_b32 s27, s19, s25
	s_cselect_b32 s26, s45, s24
	v_add_u32_e32 v142, s33, v162
	s_cselect_b32 s25, s17, s48
	s_cselect_b32 s24, s46, s47
	s_add_i32 s52, 0, 0x14000
	ds_read_b128 v[146:149], v142
	ds_read_b128 v[150:153], v142 offset:1024
	ds_read_b128 v[154:157], v142 offset:2048
	ds_read_b128 v[158:161], v142 offset:3072
	v_add_u32_e32 v142, s52, v162
	ds_read_b128 v[164:167], v142
	ds_read_b128 v[168:171], v142 offset:1024
	ds_read_b128 v[172:175], v142 offset:2048
	ds_read_b128 v[176:179], v142 offset:3072
	v_lshl_add_u64 v[142:143], s[4:5], 0, v[140:141]
	s_add_i32 m0, s35, 0xc000
	ds_read_b128 v[196:199], v163
	ds_read_b128 v[200:203], v163 offset:1024
	ds_read_b128 v[204:207], v163 offset:2048
	ds_read_b128 v[208:211], v163 offset:3072
	ds_read_b128 v[212:215], v163 offset:4096
	ds_read_b128 v[216:219], v163 offset:5120
	ds_read_b128 v[220:223], v163 offset:6144
	ds_read_b128 v[232:235], v163 offset:7168
	global_load_lds_dwordx4 v[142:143], off
	v_lshl_add_u64 v[142:143], s[4:5], 0, v[138:139]
	s_add_i32 m0, s35, 0xe000
	s_nop 0
	global_load_lds_dwordx4 v[142:143], off
	s_waitcnt vmcnt(8)
	s_waitcnt lgkmcnt(0)
	s_setprio 1
	s_barrier
	v_mfma_f32_16x16x32_bf16 v[124:127], v[146:149], v[196:199], v[124:127]
	v_mfma_f32_16x16x32_bf16 v[120:123], v[154:157], v[196:199], v[120:123]
	v_mfma_f32_16x16x32_bf16 v[108:111], v[146:149], v[204:207], v[108:111]
	v_mfma_f32_16x16x32_bf16 v[104:107], v[154:157], v[204:207], v[104:107]
	v_mfma_f32_16x16x32_bf16 v[92:95], v[146:149], v[212:215], v[92:95]
	v_mfma_f32_16x16x32_bf16 v[88:91], v[154:157], v[212:215], v[88:91]
	v_mfma_f32_16x16x32_bf16 v[76:79], v[146:149], v[220:223], v[76:79]
	v_mfma_f32_16x16x32_bf16 v[72:75], v[154:157], v[220:223], v[72:75]
	v_mfma_f32_16x16x32_bf16 v[124:127], v[150:153], v[200:203], v[124:127]
	v_mfma_f32_16x16x32_bf16 v[120:123], v[158:161], v[200:203], v[120:123]
	v_mfma_f32_16x16x32_bf16 v[108:111], v[150:153], v[208:211], v[108:111]
	v_mfma_f32_16x16x32_bf16 v[104:107], v[158:161], v[208:211], v[104:107]
	v_mfma_f32_16x16x32_bf16 v[92:95], v[150:153], v[216:219], v[92:95]
	v_mfma_f32_16x16x32_bf16 v[88:91], v[158:161], v[216:219], v[88:91]
	v_mfma_f32_16x16x32_bf16 v[76:79], v[150:153], v[232:235], v[76:79]
	v_mfma_f32_16x16x32_bf16 v[72:75], v[158:161], v[232:235], v[72:75]
	v_mfma_f32_16x16x32_bf16 v[116:119], v[164:167], v[196:199], v[116:119]
	v_mfma_f32_16x16x32_bf16 v[112:115], v[172:175], v[196:199], v[112:115]
	v_mfma_f32_16x16x32_bf16 v[100:103], v[164:167], v[204:207], v[100:103]
	v_mfma_f32_16x16x32_bf16 v[96:99], v[172:175], v[204:207], v[96:99]
	v_mfma_f32_16x16x32_bf16 v[84:87], v[164:167], v[212:215], v[84:87]
	v_mfma_f32_16x16x32_bf16 v[80:83], v[172:175], v[212:215], v[80:83]
	v_mfma_f32_16x16x32_bf16 v[68:71], v[164:167], v[220:223], v[68:71]
	v_mfma_f32_16x16x32_bf16 v[64:67], v[172:175], v[220:223], v[64:67]
	v_mfma_f32_16x16x32_bf16 v[116:119], v[168:171], v[200:203], v[116:119]
	v_mfma_f32_16x16x32_bf16 v[112:115], v[176:179], v[200:203], v[112:115]
	v_mfma_f32_16x16x32_bf16 v[100:103], v[168:171], v[208:211], v[100:103]
	v_mfma_f32_16x16x32_bf16 v[96:99], v[176:179], v[208:211], v[96:99]
	v_mfma_f32_16x16x32_bf16 v[84:87], v[168:171], v[216:219], v[84:87]
	v_mfma_f32_16x16x32_bf16 v[80:83], v[176:179], v[216:219], v[80:83]
	v_mfma_f32_16x16x32_bf16 v[68:71], v[168:171], v[232:235], v[68:71]
	v_mfma_f32_16x16x32_bf16 v[64:67], v[176:179], v[232:235], v[64:67]
	s_barrier
	s_setprio 0
	s_nop 7
	s_add_i32 s33, s33, s34
	v_lshl_add_u64 v[142:143], s[24:25], 0, v[132:133]
	s_mov_b32 m0, s33
	ds_read_b128 v[196:199], v163 offset:16384
	ds_read_b128 v[200:203], v163 offset:17408
	ds_read_b128 v[204:207], v163 offset:18432
	ds_read_b128 v[208:211], v163 offset:19456
	ds_read_b128 v[212:215], v163 offset:20480
	ds_read_b128 v[216:219], v163 offset:21504
	ds_read_b128 v[220:223], v163 offset:22528
	ds_read_b128 v[232:235], v163 offset:23552
	global_load_lds_dwordx4 v[142:143], off
	s_add_i32 m0, s33, 0x2000
	s_add_u32 s50, s24, 0x100000
	v_lshl_add_u64 v[180:181], s[24:25], 0, v[128:129]
	s_addc_u32 s51, s25, 0
	s_add_i32 s33, s52, s34
	global_load_lds_dwordx4 v[180:181], off
	v_lshl_add_u64 v[182:183], s[50:51], 0, v[132:133]
	s_mov_b32 m0, s33
	v_lshl_add_u64 v[188:189], s[26:27], 0, v[130:131]
	global_load_lds_dwordx4 v[182:183], off
	v_lshl_add_u64 v[182:183], s[50:51], 0, v[128:129]
	s_add_i32 m0, s33, 0x2000
	s_nop 0
	global_load_lds_dwordx4 v[182:183], off
	v_lshl_add_u64 v[182:183], s[26:27], 0, v[134:135]
	s_mov_b32 m0, s35
	s_nop 0
	global_load_lds_dwordx4 v[182:183], off
	s_mov_b32 m0, s36
	s_nop 0
	global_load_lds_dwordx4 v[188:189], off
	s_waitcnt vmcnt(8)
	s_waitcnt lgkmcnt(0)
	s_setprio 1
	s_barrier
	v_mfma_f32_16x16x32_bf16 v[60:63], v[146:149], v[196:199], v[60:63]
	v_mfma_f32_16x16x32_bf16 v[56:59], v[154:157], v[196:199], v[56:59]
	v_mfma_f32_16x16x32_bf16 v[44:47], v[146:149], v[204:207], v[44:47]
	v_mfma_f32_16x16x32_bf16 v[40:43], v[154:157], v[204:207], v[40:43]
	v_mfma_f32_16x16x32_bf16 v[28:31], v[146:149], v[212:215], v[28:31]
	v_mfma_f32_16x16x32_bf16 v[24:27], v[154:157], v[212:215], v[24:27]
	v_mfma_f32_16x16x32_bf16 v[12:15], v[146:149], v[220:223], v[12:15]
	v_mfma_f32_16x16x32_bf16 v[8:11], v[154:157], v[220:223], v[8:11]
	v_mfma_f32_16x16x32_bf16 v[60:63], v[150:153], v[200:203], v[60:63]
	v_mfma_f32_16x16x32_bf16 v[56:59], v[158:161], v[200:203], v[56:59]
	v_mfma_f32_16x16x32_bf16 v[44:47], v[150:153], v[208:211], v[44:47]
	v_mfma_f32_16x16x32_bf16 v[40:43], v[158:161], v[208:211], v[40:43]
	v_mfma_f32_16x16x32_bf16 v[28:31], v[150:153], v[216:219], v[28:31]
	v_mfma_f32_16x16x32_bf16 v[24:27], v[158:161], v[216:219], v[24:27]
	v_mfma_f32_16x16x32_bf16 v[12:15], v[150:153], v[232:235], v[12:15]
	v_mfma_f32_16x16x32_bf16 v[8:11], v[158:161], v[232:235], v[8:11]
	v_mfma_f32_16x16x32_bf16 v[52:55], v[164:167], v[196:199], v[52:55]
	v_mfma_f32_16x16x32_bf16 v[48:51], v[172:175], v[196:199], v[48:51]
	v_mfma_f32_16x16x32_bf16 v[36:39], v[164:167], v[204:207], v[36:39]
	v_mfma_f32_16x16x32_bf16 v[32:35], v[172:175], v[204:207], v[32:35]
	v_mfma_f32_16x16x32_bf16 v[20:23], v[164:167], v[212:215], v[20:23]
	v_mfma_f32_16x16x32_bf16 v[16:19], v[172:175], v[212:215], v[16:19]
	v_mfma_f32_16x16x32_bf16 v[4:7], v[164:167], v[220:223], v[4:7]
	v_mfma_f32_16x16x32_bf16 v[0:3], v[172:175], v[220:223], v[0:3]
	v_mfma_f32_16x16x32_bf16 v[52:55], v[168:171], v[200:203], v[52:55]
	v_mfma_f32_16x16x32_bf16 v[48:51], v[176:179], v[200:203], v[48:51]
	v_mfma_f32_16x16x32_bf16 v[36:39], v[168:171], v[208:211], v[36:39]
	v_mfma_f32_16x16x32_bf16 v[32:35], v[176:179], v[208:211], v[32:35]
	v_mfma_f32_16x16x32_bf16 v[20:23], v[168:171], v[216:219], v[20:23]
	v_mfma_f32_16x16x32_bf16 v[16:19], v[176:179], v[216:219], v[16:19]
	v_mfma_f32_16x16x32_bf16 v[4:7], v[168:171], v[232:235], v[4:7]
	v_mfma_f32_16x16x32_bf16 v[0:3], v[176:179], v[232:235], v[0:3]
	s_barrier
	s_setprio 0
	s_nop 7
	s_add_i32 s33, 0, 0x18000
	v_add_u32_e32 v144, s33, v162
	s_add_i32 s50, 0, 0x1c000
	ds_read_b128 v[146:149], v144
	ds_read_b128 v[150:153], v144 offset:1024
	ds_read_b128 v[154:157], v144 offset:2048
	ds_read_b128 v[158:161], v144 offset:3072
	v_add_u32_e32 v144, s50, v162
	ds_read_b128 v[164:167], v144
	ds_read_b128 v[168:171], v144 offset:1024
	ds_read_b128 v[172:175], v144 offset:2048
	ds_read_b128 v[176:179], v144 offset:3072
	s_add_u32 s26, s26, 0x100000
	s_addc_u32 s27, s27, 0
	s_mov_b32 m0, s37
	v_lshl_add_u64 v[190:191], s[26:27], 0, v[134:135]
	ds_read_b128 v[196:199], v163 offset:32768
	ds_read_b128 v[200:203], v163 offset:33792
	ds_read_b128 v[204:207], v163 offset:34816
	ds_read_b128 v[208:211], v163 offset:35840
	ds_read_b128 v[212:215], v163 offset:36864
	ds_read_b128 v[216:219], v163 offset:37888
	ds_read_b128 v[220:223], v163 offset:38912
	ds_read_b128 v[232:235], v163 offset:39936
	global_load_lds_dwordx4 v[190:191], off
	v_lshl_add_u64 v[190:191], s[26:27], 0, v[130:131]
	s_mov_b32 m0, s38
	s_nop 0
	global_load_lds_dwordx4 v[190:191], off
	s_waitcnt vmcnt(8)
	s_waitcnt lgkmcnt(0)
	s_setprio 1
	s_barrier
	v_mfma_f32_16x16x32_bf16 v[124:127], v[146:149], v[196:199], v[124:127]
	v_mfma_f32_16x16x32_bf16 v[120:123], v[154:157], v[196:199], v[120:123]
	v_mfma_f32_16x16x32_bf16 v[108:111], v[146:149], v[204:207], v[108:111]
	v_mfma_f32_16x16x32_bf16 v[104:107], v[154:157], v[204:207], v[104:107]
	v_mfma_f32_16x16x32_bf16 v[92:95], v[146:149], v[212:215], v[92:95]
	v_mfma_f32_16x16x32_bf16 v[88:91], v[154:157], v[212:215], v[88:91]
	v_mfma_f32_16x16x32_bf16 v[76:79], v[146:149], v[220:223], v[76:79]
	v_mfma_f32_16x16x32_bf16 v[72:75], v[154:157], v[220:223], v[72:75]
	v_mfma_f32_16x16x32_bf16 v[124:127], v[150:153], v[200:203], v[124:127]
	v_mfma_f32_16x16x32_bf16 v[120:123], v[158:161], v[200:203], v[120:123]
	v_mfma_f32_16x16x32_bf16 v[108:111], v[150:153], v[208:211], v[108:111]
	v_mfma_f32_16x16x32_bf16 v[104:107], v[158:161], v[208:211], v[104:107]
	v_mfma_f32_16x16x32_bf16 v[92:95], v[150:153], v[216:219], v[92:95]
	v_mfma_f32_16x16x32_bf16 v[88:91], v[158:161], v[216:219], v[88:91]
	v_mfma_f32_16x16x32_bf16 v[76:79], v[150:153], v[232:235], v[76:79]
	v_mfma_f32_16x16x32_bf16 v[72:75], v[158:161], v[232:235], v[72:75]
	v_mfma_f32_16x16x32_bf16 v[116:119], v[164:167], v[196:199], v[116:119]
	v_mfma_f32_16x16x32_bf16 v[112:115], v[172:175], v[196:199], v[112:115]
	v_mfma_f32_16x16x32_bf16 v[100:103], v[164:167], v[204:207], v[100:103]
	v_mfma_f32_16x16x32_bf16 v[96:99], v[172:175], v[204:207], v[96:99]
	v_mfma_f32_16x16x32_bf16 v[84:87], v[164:167], v[212:215], v[84:87]
	v_mfma_f32_16x16x32_bf16 v[80:83], v[172:175], v[212:215], v[80:83]
	v_mfma_f32_16x16x32_bf16 v[68:71], v[164:167], v[220:223], v[68:71]
	v_mfma_f32_16x16x32_bf16 v[64:67], v[172:175], v[220:223], v[64:67]
	v_mfma_f32_16x16x32_bf16 v[116:119], v[168:171], v[200:203], v[116:119]
	v_mfma_f32_16x16x32_bf16 v[112:115], v[176:179], v[200:203], v[112:115]
	v_mfma_f32_16x16x32_bf16 v[100:103], v[168:171], v[208:211], v[100:103]
	v_mfma_f32_16x16x32_bf16 v[96:99], v[176:179], v[208:211], v[96:99]
	v_mfma_f32_16x16x32_bf16 v[84:87], v[168:171], v[216:219], v[84:87]
	v_mfma_f32_16x16x32_bf16 v[80:83], v[176:179], v[216:219], v[80:83]
	v_mfma_f32_16x16x32_bf16 v[68:71], v[168:171], v[232:235], v[68:71]
	v_mfma_f32_16x16x32_bf16 v[64:67], v[176:179], v[232:235], v[64:67]
	s_barrier
	s_setprio 0
	s_nop 7
	s_add_i32 s26, s33, s34
	v_lshl_add_u64 v[142:143], v[142:143], 0, s[88:89]
	s_mov_b32 m0, s26
	ds_read_b128 v[196:199], v163 offset:49152
	ds_read_b128 v[200:203], v163 offset:50176
	ds_read_b128 v[204:207], v163 offset:51200
	ds_read_b128 v[208:211], v163 offset:52224
	ds_read_b128 v[212:215], v163 offset:53248
	ds_read_b128 v[216:219], v163 offset:54272
	ds_read_b128 v[220:223], v163 offset:55296
	ds_read_b128 v[232:235], v163 offset:56320
	global_load_lds_dwordx4 v[142:143], off
	s_add_i32 m0, s26, 0x2000
	s_add_u32 s24, s24, 0x100080
	v_lshl_add_u64 v[142:143], v[180:181], 0, s[88:89]
	s_addc_u32 s25, s25, 0
	s_add_i32 s26, s50, s34
	global_load_lds_dwordx4 v[142:143], off
	v_lshl_add_u64 v[142:143], s[24:25], 0, v[132:133]
	s_mov_b32 m0, s26
	s_nop 0
	global_load_lds_dwordx4 v[142:143], off
	v_lshl_add_u64 v[142:143], s[24:25], 0, v[128:129]
	s_add_i32 m0, s26, 0x2000
	s_nop 0
	global_load_lds_dwordx4 v[142:143], off
	v_lshl_add_u64 v[142:143], v[182:183], 0, s[88:89]
	s_mov_b32 m0, s40
	s_nop 0
	global_load_lds_dwordx4 v[142:143], off
	v_lshl_add_u64 v[142:143], v[188:189], 0, s[88:89]
	s_mov_b32 m0, s41
	s_nop 0
	global_load_lds_dwordx4 v[142:143], off
	s_waitcnt vmcnt(8)
	s_waitcnt lgkmcnt(0)
	s_setprio 1
	s_barrier
	v_mfma_f32_16x16x32_bf16 v[60:63], v[146:149], v[196:199], v[60:63]
	v_mfma_f32_16x16x32_bf16 v[56:59], v[154:157], v[196:199], v[56:59]
	v_mfma_f32_16x16x32_bf16 v[44:47], v[146:149], v[204:207], v[44:47]
	v_mfma_f32_16x16x32_bf16 v[40:43], v[154:157], v[204:207], v[40:43]
	v_mfma_f32_16x16x32_bf16 v[28:31], v[146:149], v[212:215], v[28:31]
	v_mfma_f32_16x16x32_bf16 v[24:27], v[154:157], v[212:215], v[24:27]
	v_mfma_f32_16x16x32_bf16 v[12:15], v[146:149], v[220:223], v[12:15]
	v_mfma_f32_16x16x32_bf16 v[8:11], v[154:157], v[220:223], v[8:11]
	v_mfma_f32_16x16x32_bf16 v[60:63], v[150:153], v[200:203], v[60:63]
	v_mfma_f32_16x16x32_bf16 v[56:59], v[158:161], v[200:203], v[56:59]
	v_mfma_f32_16x16x32_bf16 v[44:47], v[150:153], v[208:211], v[44:47]
	v_mfma_f32_16x16x32_bf16 v[40:43], v[158:161], v[208:211], v[40:43]
	v_mfma_f32_16x16x32_bf16 v[28:31], v[150:153], v[216:219], v[28:31]
	v_mfma_f32_16x16x32_bf16 v[24:27], v[158:161], v[216:219], v[24:27]
	v_mfma_f32_16x16x32_bf16 v[12:15], v[150:153], v[232:235], v[12:15]
	v_mfma_f32_16x16x32_bf16 v[8:11], v[158:161], v[232:235], v[8:11]
	v_mfma_f32_16x16x32_bf16 v[52:55], v[164:167], v[196:199], v[52:55]
	v_mfma_f32_16x16x32_bf16 v[48:51], v[172:175], v[196:199], v[48:51]
	v_mfma_f32_16x16x32_bf16 v[36:39], v[164:167], v[204:207], v[36:39]
	v_mfma_f32_16x16x32_bf16 v[32:35], v[172:175], v[204:207], v[32:35]
	v_mfma_f32_16x16x32_bf16 v[20:23], v[164:167], v[212:215], v[20:23]
	v_mfma_f32_16x16x32_bf16 v[16:19], v[172:175], v[212:215], v[16:19]
	v_mfma_f32_16x16x32_bf16 v[4:7], v[164:167], v[220:223], v[4:7]
	v_mfma_f32_16x16x32_bf16 v[0:3], v[172:175], v[220:223], v[0:3]
	v_mfma_f32_16x16x32_bf16 v[52:55], v[168:171], v[200:203], v[52:55]
	v_mfma_f32_16x16x32_bf16 v[48:51], v[176:179], v[200:203], v[48:51]
	v_mfma_f32_16x16x32_bf16 v[36:39], v[168:171], v[208:211], v[36:39]
	v_mfma_f32_16x16x32_bf16 v[32:35], v[176:179], v[208:211], v[32:35]
	v_mfma_f32_16x16x32_bf16 v[20:23], v[168:171], v[216:219], v[20:23]
	v_mfma_f32_16x16x32_bf16 v[16:19], v[176:179], v[216:219], v[16:19]
	v_mfma_f32_16x16x32_bf16 v[4:7], v[168:171], v[232:235], v[4:7]
	v_mfma_f32_16x16x32_bf16 v[0:3], v[176:179], v[232:235], v[0:3]
	s_barrier
	s_setprio 0
	s_nop 7
	s_add_i32 s49, s49, 2
	s_add_u32 s47, s47, 0x100
	s_addc_u32 s48, s48, 0
	s_add_u32 s4, s4, 0x100
	s_addc_u32 s5, s5, 0
	s_cmp_gt_u32 s49, 61
	s_cbranch_scc0 .LBB0_697
	s_and_b64 vcc, exec, s[14:15]
	s_cbranch_vccz .LBB0_700
	s_barrier

.LBB0_835:
	s_add_u32 s22, s20, 0xfff80080
	s_addc_u32 s23, s21, -1
	s_add_i32 s33, 0, 0x10000
	s_cmp_eq_u32 s46, 60
	s_cselect_b32 s25, s17, s23
	s_cselect_b32 s24, s16, s22
	s_cselect_b32 s23, s13, s45
	s_cselect_b32 s22, s15, s44
	s_add_i32 s47, 0, 0x14000
	v_add_u32_e32 v52, s33, v163
	v_add_u32_e32 v160, s47, v163
	ds_read_b128 v[32:35], v52
	ds_read_b128 v[36:39], v52 offset:1024
	ds_read_b128 v[48:51], v52 offset:2048
	ds_read_b128 v[52:55], v52 offset:3072
	ds_read_b128 v[156:159], v160
	ds_read_b128 v[166:169], v160 offset:1024
	ds_read_b128 v[170:173], v160 offset:2048
	ds_read_b128 v[174:177], v160 offset:3072
	v_lshl_add_u64 v[160:161], s[20:21], 0, v[154:155]
	s_add_i32 m0, s31, 0xc000
	ds_read_b128 v[196:199], v165
	ds_read_b128 v[200:203], v165 offset:1024
	ds_read_b128 v[204:207], v165 offset:2048
	ds_read_b128 v[208:211], v165 offset:3072
	ds_read_b128 v[212:215], v165 offset:4096
	ds_read_b128 v[216:219], v165 offset:5120
	ds_read_b128 v[220:223], v165 offset:6144
	ds_read_b128 v[232:235], v165 offset:7168
	global_load_lds_dwordx4 v[160:161], off
	v_lshl_add_u64 v[160:161], s[20:21], 0, v[152:153]
	s_add_i32 m0, s31, 0xe000
	s_nop 0
	global_load_lds_dwordx4 v[160:161], off
	s_waitcnt vmcnt(8)
	s_waitcnt lgkmcnt(0)
	s_setprio 1
	s_barrier
	v_mfma_f32_16x16x32_bf16 v[140:143], v[32:35], v[196:199], v[140:143]
	v_mfma_f32_16x16x32_bf16 v[136:139], v[48:51], v[196:199], v[136:139]
	v_mfma_f32_16x16x32_bf16 v[124:127], v[32:35], v[204:207], v[124:127]
	v_mfma_f32_16x16x32_bf16 v[120:123], v[48:51], v[204:207], v[120:123]
	v_mfma_f32_16x16x32_bf16 v[108:111], v[32:35], v[212:215], v[108:111]
	v_mfma_f32_16x16x32_bf16 v[104:107], v[48:51], v[212:215], v[104:107]
	v_mfma_f32_16x16x32_bf16 v[92:95], v[32:35], v[220:223], v[92:95]
	v_mfma_f32_16x16x32_bf16 v[88:91], v[48:51], v[220:223], v[88:91]
	v_mfma_f32_16x16x32_bf16 v[140:143], v[36:39], v[200:203], v[140:143]
	v_mfma_f32_16x16x32_bf16 v[136:139], v[52:55], v[200:203], v[136:139]
	v_mfma_f32_16x16x32_bf16 v[124:127], v[36:39], v[208:211], v[124:127]
	v_mfma_f32_16x16x32_bf16 v[120:123], v[52:55], v[208:211], v[120:123]
	v_mfma_f32_16x16x32_bf16 v[108:111], v[36:39], v[216:219], v[108:111]
	v_mfma_f32_16x16x32_bf16 v[104:107], v[52:55], v[216:219], v[104:107]
	v_mfma_f32_16x16x32_bf16 v[92:95], v[36:39], v[232:235], v[92:95]
	v_mfma_f32_16x16x32_bf16 v[88:91], v[52:55], v[232:235], v[88:91]
	v_mfma_f32_16x16x32_bf16 v[132:135], v[156:159], v[196:199], v[132:135]
	v_mfma_f32_16x16x32_bf16 v[128:131], v[170:173], v[196:199], v[128:131]
	v_mfma_f32_16x16x32_bf16 v[116:119], v[156:159], v[204:207], v[116:119]
	v_mfma_f32_16x16x32_bf16 v[112:115], v[170:173], v[204:207], v[112:115]
	v_mfma_f32_16x16x32_bf16 v[100:103], v[156:159], v[212:215], v[100:103]
	v_mfma_f32_16x16x32_bf16 v[96:99], v[170:173], v[212:215], v[96:99]
	v_mfma_f32_16x16x32_bf16 v[84:87], v[156:159], v[220:223], v[84:87]
	v_mfma_f32_16x16x32_bf16 v[80:83], v[170:173], v[220:223], v[80:83]
	v_mfma_f32_16x16x32_bf16 v[132:135], v[166:169], v[200:203], v[132:135]
	v_mfma_f32_16x16x32_bf16 v[128:131], v[174:177], v[200:203], v[128:131]
	v_mfma_f32_16x16x32_bf16 v[116:119], v[166:169], v[208:211], v[116:119]
	v_mfma_f32_16x16x32_bf16 v[112:115], v[174:177], v[208:211], v[112:115]
	v_mfma_f32_16x16x32_bf16 v[100:103], v[166:169], v[216:219], v[100:103]
	v_mfma_f32_16x16x32_bf16 v[96:99], v[174:177], v[216:219], v[96:99]
	v_mfma_f32_16x16x32_bf16 v[84:87], v[166:169], v[232:235], v[84:87]
	v_mfma_f32_16x16x32_bf16 v[80:83], v[174:177], v[232:235], v[80:83]
	s_barrier
	s_setprio 0
	s_nop 7
	s_add_i32 s33, s33, s30
	v_lshl_add_u64 v[160:161], s[22:23], 0, v[144:145]
	s_mov_b32 m0, s33
	ds_read_b128 v[196:199], v165 offset:16384
	ds_read_b128 v[200:203], v165 offset:17408
	ds_read_b128 v[204:207], v165 offset:18432
	ds_read_b128 v[208:211], v165 offset:19456
	ds_read_b128 v[212:215], v165 offset:20480
	ds_read_b128 v[216:219], v165 offset:21504
	ds_read_b128 v[220:223], v165 offset:22528
	ds_read_b128 v[232:235], v165 offset:23552
	global_load_lds_dwordx4 v[160:161], off
	s_add_i32 m0, s33, 0x2000
	s_add_u32 s48, s22, 0x100000
	v_lshl_add_u64 v[178:179], s[22:23], 0, v[146:147]
	s_addc_u32 s49, s23, 0
	s_add_i32 s33, s47, s30
	global_load_lds_dwordx4 v[178:179], off
	v_lshl_add_u64 v[180:181], s[48:49], 0, v[144:145]
	s_mov_b32 m0, s33
	v_lshl_add_u64 v[182:183], s[24:25], 0, v[148:149]
	global_load_lds_dwordx4 v[180:181], off
	v_lshl_add_u64 v[180:181], s[48:49], 0, v[146:147]
	s_add_i32 m0, s33, 0x2000
	s_nop 0
	global_load_lds_dwordx4 v[180:181], off
	v_lshl_add_u64 v[180:181], s[24:25], 0, v[150:151]
	s_mov_b32 m0, s31
	s_nop 0
	global_load_lds_dwordx4 v[180:181], off
	s_mov_b32 m0, s34
	s_nop 0
	global_load_lds_dwordx4 v[182:183], off
	s_waitcnt vmcnt(8)
	s_waitcnt lgkmcnt(0)
	s_setprio 1
	s_barrier
	v_mfma_f32_16x16x32_bf16 v[76:79], v[32:35], v[196:199], v[76:79]
	v_mfma_f32_16x16x32_bf16 v[72:75], v[48:51], v[196:199], v[72:75]
	v_mfma_f32_16x16x32_bf16 v[60:63], v[32:35], v[204:207], v[60:63]
	v_mfma_f32_16x16x32_bf16 v[56:59], v[48:51], v[204:207], v[56:59]
	v_mfma_f32_16x16x32_bf16 v[28:31], v[32:35], v[212:215], v[28:31]
	v_mfma_f32_16x16x32_bf16 v[24:27], v[48:51], v[212:215], v[24:27]
	v_mfma_f32_16x16x32_bf16 v[12:15], v[32:35], v[220:223], v[12:15]
	v_mfma_f32_16x16x32_bf16 v[8:11], v[48:51], v[220:223], v[8:11]
	v_mfma_f32_16x16x32_bf16 v[76:79], v[36:39], v[200:203], v[76:79]
	v_mfma_f32_16x16x32_bf16 v[72:75], v[52:55], v[200:203], v[72:75]
	v_mfma_f32_16x16x32_bf16 v[60:63], v[36:39], v[208:211], v[60:63]
	v_mfma_f32_16x16x32_bf16 v[56:59], v[52:55], v[208:211], v[56:59]
	v_mfma_f32_16x16x32_bf16 v[28:31], v[36:39], v[216:219], v[28:31]
	v_mfma_f32_16x16x32_bf16 v[24:27], v[52:55], v[216:219], v[24:27]
	v_mfma_f32_16x16x32_bf16 v[12:15], v[36:39], v[232:235], v[12:15]
	v_mfma_f32_16x16x32_bf16 v[8:11], v[52:55], v[232:235], v[8:11]
	v_mfma_f32_16x16x32_bf16 v[44:47], v[156:159], v[204:207], v[44:47]
	v_mfma_f32_16x16x32_bf16 v[40:43], v[170:173], v[204:207], v[40:43]
	v_mfma_f32_16x16x32_bf16 v[20:23], v[156:159], v[212:215], v[20:23]
	v_mfma_f32_16x16x32_bf16 v[16:19], v[170:173], v[212:215], v[16:19]
	v_mfma_f32_16x16x32_bf16 v[4:7], v[156:159], v[220:223], v[4:7]
	v_mfma_f32_16x16x32_bf16 v[0:3], v[170:173], v[220:223], v[0:3]
	v_mfma_f32_16x16x32_bf16 v[32:35], v[156:159], v[196:199], v[68:71]
	v_mfma_f32_16x16x32_bf16 v[36:39], v[170:173], v[196:199], v[64:67]
	v_mfma_f32_16x16x32_bf16 v[44:47], v[166:169], v[208:211], v[44:47]
	v_mfma_f32_16x16x32_bf16 v[40:43], v[174:177], v[208:211], v[40:43]
	v_mfma_f32_16x16x32_bf16 v[20:23], v[166:169], v[216:219], v[20:23]
	v_mfma_f32_16x16x32_bf16 v[16:19], v[174:177], v[216:219], v[16:19]
	v_mfma_f32_16x16x32_bf16 v[4:7], v[166:169], v[232:235], v[4:7]
	v_mfma_f32_16x16x32_bf16 v[0:3], v[174:177], v[232:235], v[0:3]
	v_mfma_f32_16x16x32_bf16 v[32:35], v[166:169], v[200:203], v[32:35]
	v_mfma_f32_16x16x32_bf16 v[36:39], v[174:177], v[200:203], v[36:39]
	s_barrier
	s_setprio 0
	s_nop 7
	s_add_i32 s33, 0, 0x18000
	s_add_i32 s47, 0, 0x1c000
	v_add_u32_e32 v68, s33, v163
	v_add_u32_e32 v174, s47, v163
	ds_read_b128 v[48:51], v68
	ds_read_b128 v[52:55], v68 offset:1024
	ds_read_b128 v[64:67], v68 offset:2048
	ds_read_b128 v[68:71], v68 offset:3072
	ds_read_b128 v[156:159], v174
	ds_read_b128 v[166:169], v174 offset:1024
	ds_read_b128 v[170:173], v174 offset:2048
	ds_read_b128 v[174:177], v174 offset:3072
	s_add_u32 s24, s24, 0x80000
	s_addc_u32 s25, s25, 0
	s_mov_b32 m0, s35
	v_lshl_add_u64 v[188:189], s[24:25], 0, v[150:151]
	ds_read_b128 v[196:199], v165 offset:32768
	ds_read_b128 v[200:203], v165 offset:33792
	ds_read_b128 v[204:207], v165 offset:34816
	ds_read_b128 v[208:211], v165 offset:35840
	ds_read_b128 v[212:215], v165 offset:36864
	ds_read_b128 v[216:219], v165 offset:37888
	ds_read_b128 v[220:223], v165 offset:38912
	ds_read_b128 v[232:235], v165 offset:39936
	global_load_lds_dwordx4 v[188:189], off
	v_lshl_add_u64 v[188:189], s[24:25], 0, v[148:149]
	s_mov_b32 m0, s36
	s_nop 0
	global_load_lds_dwordx4 v[188:189], off
	s_waitcnt vmcnt(8)
	s_waitcnt lgkmcnt(0)
	s_setprio 1
	s_barrier
	v_mfma_f32_16x16x32_bf16 v[140:143], v[48:51], v[196:199], v[140:143]
	v_mfma_f32_16x16x32_bf16 v[136:139], v[64:67], v[196:199], v[136:139]
	v_mfma_f32_16x16x32_bf16 v[124:127], v[48:51], v[204:207], v[124:127]
	v_mfma_f32_16x16x32_bf16 v[120:123], v[64:67], v[204:207], v[120:123]
	v_mfma_f32_16x16x32_bf16 v[108:111], v[48:51], v[212:215], v[108:111]
	v_mfma_f32_16x16x32_bf16 v[104:107], v[64:67], v[212:215], v[104:107]
	v_mfma_f32_16x16x32_bf16 v[92:95], v[48:51], v[220:223], v[92:95]
	v_mfma_f32_16x16x32_bf16 v[88:91], v[64:67], v[220:223], v[88:91]
	v_mfma_f32_16x16x32_bf16 v[140:143], v[52:55], v[200:203], v[140:143]
	v_mfma_f32_16x16x32_bf16 v[136:139], v[68:71], v[200:203], v[136:139]
	v_mfma_f32_16x16x32_bf16 v[124:127], v[52:55], v[208:211], v[124:127]
	v_mfma_f32_16x16x32_bf16 v[120:123], v[68:71], v[208:211], v[120:123]
	v_mfma_f32_16x16x32_bf16 v[108:111], v[52:55], v[216:219], v[108:111]
	v_mfma_f32_16x16x32_bf16 v[104:107], v[68:71], v[216:219], v[104:107]
	v_mfma_f32_16x16x32_bf16 v[92:95], v[52:55], v[232:235], v[92:95]
	v_mfma_f32_16x16x32_bf16 v[88:91], v[68:71], v[232:235], v[88:91]
	v_mfma_f32_16x16x32_bf16 v[132:135], v[156:159], v[196:199], v[132:135]
	v_mfma_f32_16x16x32_bf16 v[128:131], v[170:173], v[196:199], v[128:131]
	v_mfma_f32_16x16x32_bf16 v[116:119], v[156:159], v[204:207], v[116:119]
	v_mfma_f32_16x16x32_bf16 v[112:115], v[170:173], v[204:207], v[112:115]
	v_mfma_f32_16x16x32_bf16 v[100:103], v[156:159], v[212:215], v[100:103]
	v_mfma_f32_16x16x32_bf16 v[96:99], v[170:173], v[212:215], v[96:99]
	v_mfma_f32_16x16x32_bf16 v[84:87], v[156:159], v[220:223], v[84:87]
	v_mfma_f32_16x16x32_bf16 v[80:83], v[170:173], v[220:223], v[80:83]
	v_mfma_f32_16x16x32_bf16 v[132:135], v[166:169], v[200:203], v[132:135]
	v_mfma_f32_16x16x32_bf16 v[128:131], v[174:177], v[200:203], v[128:131]
	v_mfma_f32_16x16x32_bf16 v[116:119], v[166:169], v[208:211], v[116:119]
	v_mfma_f32_16x16x32_bf16 v[112:115], v[174:177], v[208:211], v[112:115]
	v_mfma_f32_16x16x32_bf16 v[100:103], v[166:169], v[216:219], v[100:103]
	v_mfma_f32_16x16x32_bf16 v[96:99], v[174:177], v[216:219], v[96:99]
	v_mfma_f32_16x16x32_bf16 v[84:87], v[166:169], v[232:235], v[84:87]
	v_mfma_f32_16x16x32_bf16 v[80:83], v[174:177], v[232:235], v[80:83]
	s_barrier
	s_setprio 0
	s_nop 7
	s_add_i32 s24, s33, s30
	v_lshl_add_u64 v[160:161], v[160:161], 0, s[88:89]
	s_mov_b32 m0, s24
	ds_read_b128 v[196:199], v165 offset:49152
	ds_read_b128 v[200:203], v165 offset:50176
	ds_read_b128 v[204:207], v165 offset:51200
	ds_read_b128 v[208:211], v165 offset:52224
	ds_read_b128 v[212:215], v165 offset:53248
	ds_read_b128 v[216:219], v165 offset:54272
	ds_read_b128 v[220:223], v165 offset:55296
	ds_read_b128 v[232:235], v165 offset:56320
	global_load_lds_dwordx4 v[160:161], off
	s_add_i32 m0, s24, 0x2000
	s_add_u32 s22, s22, 0x100080
	v_lshl_add_u64 v[160:161], v[178:179], 0, s[88:89]
	s_addc_u32 s23, s23, 0
	s_add_i32 s24, s47, s30
	global_load_lds_dwordx4 v[160:161], off
	v_lshl_add_u64 v[160:161], s[22:23], 0, v[144:145]
	s_mov_b32 m0, s24
	s_nop 0
	global_load_lds_dwordx4 v[160:161], off
	v_lshl_add_u64 v[160:161], s[22:23], 0, v[146:147]
	s_add_i32 m0, s24, 0x2000
	s_nop 0
	global_load_lds_dwordx4 v[160:161], off
	v_lshl_add_u64 v[160:161], v[180:181], 0, s[88:89]
	s_mov_b32 m0, s39
	s_nop 0
	global_load_lds_dwordx4 v[160:161], off
	v_lshl_add_u64 v[160:161], v[182:183], 0, s[88:89]
	s_mov_b32 m0, s40
	s_nop 0
	global_load_lds_dwordx4 v[160:161], off
	s_waitcnt vmcnt(8)
	s_waitcnt lgkmcnt(0)
	s_setprio 1
	s_barrier
	v_mfma_f32_16x16x32_bf16 v[76:79], v[48:51], v[196:199], v[76:79]
	v_mfma_f32_16x16x32_bf16 v[72:75], v[64:67], v[196:199], v[72:75]
	v_mfma_f32_16x16x32_bf16 v[60:63], v[48:51], v[204:207], v[60:63]
	v_mfma_f32_16x16x32_bf16 v[56:59], v[64:67], v[204:207], v[56:59]
	v_mfma_f32_16x16x32_bf16 v[28:31], v[48:51], v[212:215], v[28:31]
	v_mfma_f32_16x16x32_bf16 v[24:27], v[64:67], v[212:215], v[24:27]
	v_mfma_f32_16x16x32_bf16 v[12:15], v[48:51], v[220:223], v[12:15]
	v_mfma_f32_16x16x32_bf16 v[8:11], v[64:67], v[220:223], v[8:11]
	v_mfma_f32_16x16x32_bf16 v[76:79], v[52:55], v[200:203], v[76:79]
	v_mfma_f32_16x16x32_bf16 v[72:75], v[68:71], v[200:203], v[72:75]
	v_mfma_f32_16x16x32_bf16 v[60:63], v[52:55], v[208:211], v[60:63]
	v_mfma_f32_16x16x32_bf16 v[56:59], v[68:71], v[208:211], v[56:59]
	v_mfma_f32_16x16x32_bf16 v[28:31], v[52:55], v[216:219], v[28:31]
	v_mfma_f32_16x16x32_bf16 v[24:27], v[68:71], v[216:219], v[24:27]
	v_mfma_f32_16x16x32_bf16 v[12:15], v[52:55], v[232:235], v[12:15]
	v_mfma_f32_16x16x32_bf16 v[8:11], v[68:71], v[232:235], v[8:11]
	v_mfma_f32_16x16x32_bf16 v[32:35], v[156:159], v[196:199], v[32:35]
	v_mfma_f32_16x16x32_bf16 v[68:71], v[166:169], v[200:203], v[32:35]
	v_mfma_f32_16x16x32_bf16 v[32:35], v[170:173], v[196:199], v[36:39]
	v_mfma_f32_16x16x32_bf16 v[64:67], v[174:177], v[200:203], v[32:35]
	v_mfma_f32_16x16x32_bf16 v[32:35], v[156:159], v[204:207], v[44:47]
	v_mfma_f32_16x16x32_bf16 v[44:47], v[166:169], v[208:211], v[32:35]
	v_mfma_f32_16x16x32_bf16 v[32:35], v[170:173], v[204:207], v[40:43]
	v_mfma_f32_16x16x32_bf16 v[20:23], v[156:159], v[212:215], v[20:23]
	v_mfma_f32_16x16x32_bf16 v[16:19], v[170:173], v[212:215], v[16:19]
	v_mfma_f32_16x16x32_bf16 v[4:7], v[156:159], v[220:223], v[4:7]
	v_mfma_f32_16x16x32_bf16 v[0:3], v[170:173], v[220:223], v[0:3]
	v_mfma_f32_16x16x32_bf16 v[40:43], v[174:177], v[208:211], v[32:35]
	v_mfma_f32_16x16x32_bf16 v[20:23], v[166:169], v[216:219], v[20:23]
	v_mfma_f32_16x16x32_bf16 v[16:19], v[174:177], v[216:219], v[16:19]
	v_mfma_f32_16x16x32_bf16 v[4:7], v[166:169], v[232:235], v[4:7]
	v_mfma_f32_16x16x32_bf16 v[0:3], v[174:177], v[232:235], v[0:3]
	s_barrier
	s_setprio 0
	s_nop 7
	s_add_i32 s46, s46, 2
	s_add_u32 s44, s44, 0x100
	s_addc_u32 s45, s45, 0
	s_add_u32 s20, s20, 0x100
	s_addc_u32 s21, s21, 0
	s_cmp_gt_u32 s46, 61
	s_cbranch_scc0 .LBB0_835
	s_and_b64 vcc, exec, s[10:11]
	s_cbranch_vccz .LBB0_838
	s_barrier

.LBB0_856:
	s_add_u32 s26, s24, 0xfff00080
	s_addc_u32 s27, s25, -1
	s_add_i32 s51, 0, 0x10000
	v_add_u32_e32 v83, s51, v81
	ds_read_b128 v[76:79], v83
	ds_read_b128 v[84:87], v83 offset:1024
	ds_read_b128 v[88:91], v83 offset:2048
	ds_read_b128 v[92:95], v83 offset:3072
	s_cmp_eq_u32 s50, 60
	s_cselect_b32 s29, s19, s27
	s_cselect_b32 s28, s46, s26
	s_cselect_b32 s27, s17, s49
	s_cselect_b32 s26, s47, s48
	v_lshl_add_u64 v[128:129], s[24:25], 0, v[74:75]
	s_add_i32 m0, s35, 0xc000
	ds_read_b128 v[96:99], v82
	ds_read_b128 v[100:103], v82 offset:1024
	ds_read_b128 v[104:107], v82 offset:2048
	ds_read_b128 v[108:111], v82 offset:3072
	ds_read_b128 v[112:115], v82 offset:4096
	ds_read_b128 v[116:119], v82 offset:5120
	ds_read_b128 v[120:123], v82 offset:6144
	ds_read_b128 v[124:127], v82 offset:7168
	global_load_lds_dwordx4 v[128:129], off
	v_lshl_add_u64 v[128:129], s[24:25], 0, v[72:73]
	s_add_i32 m0, s35, 0xe000
	s_nop 0
	global_load_lds_dwordx4 v[128:129], off
	s_waitcnt vmcnt(8)
	s_waitcnt lgkmcnt(0)
	s_setprio 1
	s_barrier
	v_mfma_f32_16x16x32_bf16 v[60:63], v[76:79], v[96:99], v[60:63]
	v_mfma_f32_16x16x32_bf16 v[56:59], v[88:91], v[96:99], v[56:59]
	v_mfma_f32_16x16x32_bf16 v[52:55], v[76:79], v[104:107], v[52:55]
	v_mfma_f32_16x16x32_bf16 v[48:51], v[88:91], v[104:107], v[48:51]
	v_mfma_f32_16x16x32_bf16 v[44:47], v[76:79], v[112:115], v[44:47]
	v_mfma_f32_16x16x32_bf16 v[40:43], v[88:91], v[112:115], v[40:43]
	v_mfma_f32_16x16x32_bf16 v[36:39], v[76:79], v[120:123], v[36:39]
	v_mfma_f32_16x16x32_bf16 v[32:35], v[88:91], v[120:123], v[32:35]
	v_mfma_f32_16x16x32_bf16 v[60:63], v[84:87], v[100:103], v[60:63]
	v_mfma_f32_16x16x32_bf16 v[56:59], v[92:95], v[100:103], v[56:59]
	v_mfma_f32_16x16x32_bf16 v[52:55], v[84:87], v[108:111], v[52:55]
	v_mfma_f32_16x16x32_bf16 v[48:51], v[92:95], v[108:111], v[48:51]
	v_mfma_f32_16x16x32_bf16 v[44:47], v[84:87], v[116:119], v[44:47]
	v_mfma_f32_16x16x32_bf16 v[40:43], v[92:95], v[116:119], v[40:43]
	v_mfma_f32_16x16x32_bf16 v[36:39], v[84:87], v[124:127], v[36:39]
	v_mfma_f32_16x16x32_bf16 v[32:35], v[92:95], v[124:127], v[32:35]
	s_barrier
	s_setprio 0
	s_nop 7
	s_add_i32 s51, s51, s34
	v_lshl_add_u64 v[128:129], s[26:27], 0, v[68:69]
	s_mov_b32 m0, s51
	ds_read_b128 v[96:99], v82 offset:16384
	ds_read_b128 v[100:103], v82 offset:17408
	ds_read_b128 v[104:107], v82 offset:18432
	ds_read_b128 v[108:111], v82 offset:19456
	ds_read_b128 v[112:115], v82 offset:20480
	ds_read_b128 v[116:119], v82 offset:21504
	ds_read_b128 v[120:123], v82 offset:22528
	ds_read_b128 v[124:127], v82 offset:23552
	global_load_lds_dwordx4 v[128:129], off
	s_add_i32 m0, s51, 0x2000
	s_add_u32 s52, s26, 0x100000
	v_lshl_add_u64 v[130:131], s[26:27], 0, v[64:65]
	s_addc_u32 s53, s27, 0
	global_load_lds_dwordx4 v[130:131], off
	v_lshl_add_u64 v[132:133], s[52:53], 0, v[68:69]
	s_mov_b32 m0, s36
	v_lshl_add_u64 v[134:135], s[28:29], 0, v[66:67]
	global_load_lds_dwordx4 v[132:133], off
	v_lshl_add_u64 v[132:133], s[52:53], 0, v[64:65]
	s_mov_b32 m0, s37
	s_nop 0
	global_load_lds_dwordx4 v[132:133], off
	v_lshl_add_u64 v[132:133], s[28:29], 0, v[144:145]
	s_mov_b32 m0, s35
	s_nop 0
	global_load_lds_dwordx4 v[132:133], off
	s_mov_b32 m0, s38
	s_nop 0
	global_load_lds_dwordx4 v[134:135], off
	s_waitcnt vmcnt(8)
	s_waitcnt lgkmcnt(0)
	s_setprio 1
	s_barrier
	v_mfma_f32_16x16x32_bf16 v[28:31], v[76:79], v[96:99], v[28:31]
	v_mfma_f32_16x16x32_bf16 v[24:27], v[88:91], v[96:99], v[24:27]
	v_mfma_f32_16x16x32_bf16 v[20:23], v[76:79], v[104:107], v[20:23]
	v_mfma_f32_16x16x32_bf16 v[16:19], v[88:91], v[104:107], v[16:19]
	v_mfma_f32_16x16x32_bf16 v[12:15], v[76:79], v[112:115], v[12:15]
	v_mfma_f32_16x16x32_bf16 v[8:11], v[88:91], v[112:115], v[8:11]
	v_mfma_f32_16x16x32_bf16 v[4:7], v[76:79], v[120:123], v[4:7]
	v_mfma_f32_16x16x32_bf16 v[0:3], v[88:91], v[120:123], v[0:3]
	v_mfma_f32_16x16x32_bf16 v[28:31], v[84:87], v[100:103], v[28:31]
	v_mfma_f32_16x16x32_bf16 v[24:27], v[92:95], v[100:103], v[24:27]
	v_mfma_f32_16x16x32_bf16 v[20:23], v[84:87], v[108:111], v[20:23]
	v_mfma_f32_16x16x32_bf16 v[16:19], v[92:95], v[108:111], v[16:19]
	v_mfma_f32_16x16x32_bf16 v[12:15], v[84:87], v[116:119], v[12:15]
	v_mfma_f32_16x16x32_bf16 v[8:11], v[92:95], v[116:119], v[8:11]
	v_mfma_f32_16x16x32_bf16 v[4:7], v[84:87], v[124:127], v[4:7]
	v_mfma_f32_16x16x32_bf16 v[0:3], v[92:95], v[124:127], v[0:3]
	s_barrier
	s_setprio 0
	s_nop 7
	s_add_i32 s51, 0, 0x18000
	v_add_u32_e32 v83, s51, v81
	ds_read_b128 v[76:79], v83
	ds_read_b128 v[84:87], v83 offset:1024
	ds_read_b128 v[88:91], v83 offset:2048
	ds_read_b128 v[92:95], v83 offset:3072
	s_add_u32 s28, s28, 0x100000
	s_addc_u32 s29, s29, 0
	s_mov_b32 m0, s39
	v_lshl_add_u64 v[136:137], s[28:29], 0, v[144:145]
	ds_read_b128 v[96:99], v82 offset:32768
	ds_read_b128 v[100:103], v82 offset:33792
	ds_read_b128 v[104:107], v82 offset:34816
	ds_read_b128 v[108:111], v82 offset:35840
	ds_read_b128 v[112:115], v82 offset:36864
	ds_read_b128 v[116:119], v82 offset:37888
	ds_read_b128 v[120:123], v82 offset:38912
	ds_read_b128 v[124:127], v82 offset:39936
	global_load_lds_dwordx4 v[136:137], off
	v_lshl_add_u64 v[136:137], s[28:29], 0, v[66:67]
	s_mov_b32 m0, s40
	s_nop 0
	global_load_lds_dwordx4 v[136:137], off
	s_waitcnt vmcnt(8)
	s_waitcnt lgkmcnt(0)
	s_setprio 1
	s_barrier
	v_mfma_f32_16x16x32_bf16 v[60:63], v[76:79], v[96:99], v[60:63]
	v_mfma_f32_16x16x32_bf16 v[56:59], v[88:91], v[96:99], v[56:59]
	v_mfma_f32_16x16x32_bf16 v[52:55], v[76:79], v[104:107], v[52:55]
	v_mfma_f32_16x16x32_bf16 v[48:51], v[88:91], v[104:107], v[48:51]
	v_mfma_f32_16x16x32_bf16 v[44:47], v[76:79], v[112:115], v[44:47]
	v_mfma_f32_16x16x32_bf16 v[40:43], v[88:91], v[112:115], v[40:43]
	v_mfma_f32_16x16x32_bf16 v[36:39], v[76:79], v[120:123], v[36:39]
	v_mfma_f32_16x16x32_bf16 v[32:35], v[88:91], v[120:123], v[32:35]
	v_mfma_f32_16x16x32_bf16 v[60:63], v[84:87], v[100:103], v[60:63]
	v_mfma_f32_16x16x32_bf16 v[56:59], v[92:95], v[100:103], v[56:59]
	v_mfma_f32_16x16x32_bf16 v[52:55], v[84:87], v[108:111], v[52:55]
	v_mfma_f32_16x16x32_bf16 v[48:51], v[92:95], v[108:111], v[48:51]
	v_mfma_f32_16x16x32_bf16 v[44:47], v[84:87], v[116:119], v[44:47]
	v_mfma_f32_16x16x32_bf16 v[40:43], v[92:95], v[116:119], v[40:43]
	v_mfma_f32_16x16x32_bf16 v[36:39], v[84:87], v[124:127], v[36:39]
	v_mfma_f32_16x16x32_bf16 v[32:35], v[92:95], v[124:127], v[32:35]
	s_barrier
	s_setprio 0
	s_nop 7
	s_add_i32 s28, s51, s34
	v_lshl_add_u64 v[128:129], v[128:129], 0, s[88:89]
	s_mov_b32 m0, s28
	ds_read_b128 v[96:99], v82 offset:49152
	ds_read_b128 v[100:103], v82 offset:50176
	ds_read_b128 v[104:107], v82 offset:51200
	ds_read_b128 v[108:111], v82 offset:52224
	ds_read_b128 v[112:115], v82 offset:53248
	ds_read_b128 v[116:119], v82 offset:54272
	ds_read_b128 v[120:123], v82 offset:55296
	ds_read_b128 v[124:127], v82 offset:56320
	global_load_lds_dwordx4 v[128:129], off
	s_add_i32 m0, s28, 0x2000
	s_add_u32 s26, s26, 0x100080
	v_lshl_add_u64 v[128:129], v[130:131], 0, s[88:89]
	s_addc_u32 s27, s27, 0
	global_load_lds_dwordx4 v[128:129], off
	v_lshl_add_u64 v[128:129], s[26:27], 0, v[68:69]
	s_mov_b32 m0, s43
	s_nop 0
	global_load_lds_dwordx4 v[128:129], off
	v_lshl_add_u64 v[128:129], s[26:27], 0, v[64:65]
	s_mov_b32 m0, s44
	s_nop 0
	global_load_lds_dwordx4 v[128:129], off
	v_lshl_add_u64 v[128:129], v[132:133], 0, s[88:89]
	s_mov_b32 m0, s41
	s_nop 0
	global_load_lds_dwordx4 v[128:129], off
	v_lshl_add_u64 v[128:129], v[134:135], 0, s[88:89]
	s_mov_b32 m0, s42
	s_nop 0
	global_load_lds_dwordx4 v[128:129], off
	s_waitcnt vmcnt(8)
	s_waitcnt lgkmcnt(0)
	s_setprio 1
	s_barrier
	v_mfma_f32_16x16x32_bf16 v[28:31], v[76:79], v[96:99], v[28:31]
	v_mfma_f32_16x16x32_bf16 v[24:27], v[88:91], v[96:99], v[24:27]
	v_mfma_f32_16x16x32_bf16 v[20:23], v[76:79], v[104:107], v[20:23]
	v_mfma_f32_16x16x32_bf16 v[16:19], v[88:91], v[104:107], v[16:19]
	v_mfma_f32_16x16x32_bf16 v[12:15], v[76:79], v[112:115], v[12:15]
	v_mfma_f32_16x16x32_bf16 v[8:11], v[88:91], v[112:115], v[8:11]
	v_mfma_f32_16x16x32_bf16 v[4:7], v[76:79], v[120:123], v[4:7]
	v_mfma_f32_16x16x32_bf16 v[0:3], v[88:91], v[120:123], v[0:3]
	v_mfma_f32_16x16x32_bf16 v[28:31], v[84:87], v[100:103], v[28:31]
	v_mfma_f32_16x16x32_bf16 v[24:27], v[92:95], v[100:103], v[24:27]
	v_mfma_f32_16x16x32_bf16 v[20:23], v[84:87], v[108:111], v[20:23]
	v_mfma_f32_16x16x32_bf16 v[16:19], v[92:95], v[108:111], v[16:19]
	v_mfma_f32_16x16x32_bf16 v[12:15], v[84:87], v[116:119], v[12:15]
	v_mfma_f32_16x16x32_bf16 v[8:11], v[92:95], v[116:119], v[8:11]
	v_mfma_f32_16x16x32_bf16 v[4:7], v[84:87], v[124:127], v[4:7]
	v_mfma_f32_16x16x32_bf16 v[0:3], v[92:95], v[124:127], v[0:3]
	s_barrier
	s_setprio 0
	s_nop 7
	s_add_i32 s50, s50, 2
	s_add_u32 s48, s48, 0x100
	s_addc_u32 s49, s49, 0
	s_add_u32 s24, s24, 0x100
	s_addc_u32 s25, s25, 0
	s_cmp_gt_u32 s50, 61
	s_cbranch_scc0 .LBB0_856
	s_and_b64 vcc, exec, s[10:11]
	s_cbranch_vccz .LBB0_860
	s_barrier
	s_andn2_b64 vcc, exec, s[12:13]
	s_cbranch_vccz .LBB0_861

.LBB0_982:
	s_add_u32 s20, s18, 0xfffe0080
	s_addc_u32 s21, s19, -1
	s_add_i32 s48, 0, 0x10000
	v_add_u32_e32 v79, s48, v77
	ds_read_b128 v[80:83], v79
	ds_read_b128 v[84:87], v79 offset:1024
	ds_read_b128 v[88:91], v79 offset:2048
	ds_read_b128 v[92:95], v79 offset:3072
	s_cmp_eq_u32 s47, 4
	s_cselect_b32 s23, s11, s21
	s_cselect_b32 s22, s33, s20
	s_cselect_b32 s21, s9, s46
	s_cselect_b32 s20, s44, s45
	v_lshl_add_u64 v[128:129], s[18:19], 0, v[74:75]
	s_add_i32 m0, s29, 0xc000
	ds_read_b128 v[96:99], v78
	ds_read_b128 v[100:103], v78 offset:1024
	ds_read_b128 v[104:107], v78 offset:2048
	ds_read_b128 v[108:111], v78 offset:3072
	ds_read_b128 v[112:115], v78 offset:4096
	ds_read_b128 v[116:119], v78 offset:5120
	ds_read_b128 v[120:123], v78 offset:6144
	ds_read_b128 v[124:127], v78 offset:7168
	global_load_lds_dwordx4 v[128:129], off
	v_lshl_add_u64 v[128:129], s[18:19], 0, v[72:73]
	s_add_i32 m0, s29, 0xe000
	s_nop 0
	global_load_lds_dwordx4 v[128:129], off
	s_waitcnt vmcnt(8)
	s_waitcnt lgkmcnt(0)
	s_setprio 1
	s_barrier
	v_mfma_f32_16x16x32_bf16 v[60:63], v[80:83], v[96:99], v[60:63]
	v_mfma_f32_16x16x32_bf16 v[56:59], v[88:91], v[96:99], v[56:59]
	v_mfma_f32_16x16x32_bf16 v[52:55], v[80:83], v[104:107], v[52:55]
	v_mfma_f32_16x16x32_bf16 v[48:51], v[88:91], v[104:107], v[48:51]
	v_mfma_f32_16x16x32_bf16 v[44:47], v[80:83], v[112:115], v[44:47]
	v_mfma_f32_16x16x32_bf16 v[40:43], v[88:91], v[112:115], v[40:43]
	v_mfma_f32_16x16x32_bf16 v[36:39], v[80:83], v[120:123], v[36:39]
	v_mfma_f32_16x16x32_bf16 v[32:35], v[88:91], v[120:123], v[32:35]
	v_mfma_f32_16x16x32_bf16 v[60:63], v[84:87], v[100:103], v[60:63]
	v_mfma_f32_16x16x32_bf16 v[56:59], v[92:95], v[100:103], v[56:59]
	v_mfma_f32_16x16x32_bf16 v[52:55], v[84:87], v[108:111], v[52:55]
	v_mfma_f32_16x16x32_bf16 v[48:51], v[92:95], v[108:111], v[48:51]
	v_mfma_f32_16x16x32_bf16 v[44:47], v[84:87], v[116:119], v[44:47]
	v_mfma_f32_16x16x32_bf16 v[40:43], v[92:95], v[116:119], v[40:43]
	v_mfma_f32_16x16x32_bf16 v[36:39], v[84:87], v[124:127], v[36:39]
	v_mfma_f32_16x16x32_bf16 v[32:35], v[92:95], v[124:127], v[32:35]
	s_barrier
	s_setprio 0
	s_nop 7
	s_add_i32 s48, s48, s28
	v_lshl_add_u64 v[128:129], s[20:21], 0, v[68:69]
	s_mov_b32 m0, s48
	ds_read_b128 v[96:99], v78 offset:16384
	ds_read_b128 v[100:103], v78 offset:17408
	ds_read_b128 v[104:107], v78 offset:18432
	ds_read_b128 v[108:111], v78 offset:19456
	ds_read_b128 v[112:115], v78 offset:20480
	ds_read_b128 v[116:119], v78 offset:21504
	ds_read_b128 v[120:123], v78 offset:22528
	ds_read_b128 v[124:127], v78 offset:23552
	global_load_lds_dwordx4 v[128:129], off
	s_add_i32 m0, s48, 0x2000
	s_add_u32 s48, s20, 0x20000
	v_lshl_add_u64 v[130:131], s[20:21], 0, v[64:65]
	s_addc_u32 s49, s21, 0
	global_load_lds_dwordx4 v[130:131], off
	v_lshl_add_u64 v[132:133], s[48:49], 0, v[68:69]
	s_mov_b32 m0, s30
	v_lshl_add_u64 v[134:135], s[22:23], 0, v[66:67]
	global_load_lds_dwordx4 v[132:133], off
	v_lshl_add_u64 v[132:133], s[48:49], 0, v[64:65]
	s_mov_b32 m0, s31
	s_nop 0
	global_load_lds_dwordx4 v[132:133], off
	v_lshl_add_u64 v[132:133], s[22:23], 0, v[70:71]
	s_mov_b32 m0, s29
	s_nop 0
	global_load_lds_dwordx4 v[132:133], off
	s_mov_b32 m0, s34
	s_nop 0
	global_load_lds_dwordx4 v[134:135], off
	s_waitcnt vmcnt(8)
	s_waitcnt lgkmcnt(0)
	s_setprio 1
	s_barrier
	v_mfma_f32_16x16x32_bf16 v[28:31], v[80:83], v[96:99], v[28:31]
	v_mfma_f32_16x16x32_bf16 v[24:27], v[88:91], v[96:99], v[24:27]
	v_mfma_f32_16x16x32_bf16 v[20:23], v[80:83], v[104:107], v[20:23]
	v_mfma_f32_16x16x32_bf16 v[16:19], v[88:91], v[104:107], v[16:19]
	v_mfma_f32_16x16x32_bf16 v[12:15], v[80:83], v[112:115], v[12:15]
	v_mfma_f32_16x16x32_bf16 v[8:11], v[88:91], v[112:115], v[8:11]
	v_mfma_f32_16x16x32_bf16 v[4:7], v[80:83], v[120:123], v[4:7]
	v_mfma_f32_16x16x32_bf16 v[0:3], v[88:91], v[120:123], v[0:3]
	v_mfma_f32_16x16x32_bf16 v[28:31], v[84:87], v[100:103], v[28:31]
	v_mfma_f32_16x16x32_bf16 v[24:27], v[92:95], v[100:103], v[24:27]
	v_mfma_f32_16x16x32_bf16 v[20:23], v[84:87], v[108:111], v[20:23]
	v_mfma_f32_16x16x32_bf16 v[16:19], v[92:95], v[108:111], v[16:19]
	v_mfma_f32_16x16x32_bf16 v[12:15], v[84:87], v[116:119], v[12:15]
	v_mfma_f32_16x16x32_bf16 v[8:11], v[92:95], v[116:119], v[8:11]
	v_mfma_f32_16x16x32_bf16 v[4:7], v[84:87], v[124:127], v[4:7]
	v_mfma_f32_16x16x32_bf16 v[0:3], v[92:95], v[124:127], v[0:3]
	s_barrier
	s_setprio 0
	s_nop 7
	s_add_i32 s48, 0, 0x18000
	v_add_u32_e32 v79, s48, v77
	ds_read_b128 v[80:83], v79
	ds_read_b128 v[84:87], v79 offset:1024
	ds_read_b128 v[88:91], v79 offset:2048
	ds_read_b128 v[92:95], v79 offset:3072
	s_add_u32 s22, s22, 0x20000
	s_addc_u32 s23, s23, 0
	s_mov_b32 m0, s35
	v_lshl_add_u64 v[136:137], s[22:23], 0, v[70:71]
	ds_read_b128 v[96:99], v78 offset:32768
	ds_read_b128 v[100:103], v78 offset:33792
	ds_read_b128 v[104:107], v78 offset:34816
	ds_read_b128 v[108:111], v78 offset:35840
	ds_read_b128 v[112:115], v78 offset:36864
	ds_read_b128 v[116:119], v78 offset:37888
	ds_read_b128 v[120:123], v78 offset:38912
	ds_read_b128 v[124:127], v78 offset:39936
	global_load_lds_dwordx4 v[136:137], off
	v_lshl_add_u64 v[136:137], s[22:23], 0, v[66:67]
	s_mov_b32 m0, s36
	s_nop 0
	global_load_lds_dwordx4 v[136:137], off
	s_waitcnt vmcnt(8)
	s_waitcnt lgkmcnt(0)
	s_setprio 1
	s_barrier
	v_mfma_f32_16x16x32_bf16 v[60:63], v[80:83], v[96:99], v[60:63]
	v_mfma_f32_16x16x32_bf16 v[56:59], v[88:91], v[96:99], v[56:59]
	v_mfma_f32_16x16x32_bf16 v[52:55], v[80:83], v[104:107], v[52:55]
	v_mfma_f32_16x16x32_bf16 v[48:51], v[88:91], v[104:107], v[48:51]
	v_mfma_f32_16x16x32_bf16 v[44:47], v[80:83], v[112:115], v[44:47]
	v_mfma_f32_16x16x32_bf16 v[40:43], v[88:91], v[112:115], v[40:43]
	v_mfma_f32_16x16x32_bf16 v[36:39], v[80:83], v[120:123], v[36:39]
	v_mfma_f32_16x16x32_bf16 v[32:35], v[88:91], v[120:123], v[32:35]
	v_mfma_f32_16x16x32_bf16 v[60:63], v[84:87], v[100:103], v[60:63]
	v_mfma_f32_16x16x32_bf16 v[56:59], v[92:95], v[100:103], v[56:59]
	v_mfma_f32_16x16x32_bf16 v[52:55], v[84:87], v[108:111], v[52:55]
	v_mfma_f32_16x16x32_bf16 v[48:51], v[92:95], v[108:111], v[48:51]
	v_mfma_f32_16x16x32_bf16 v[44:47], v[84:87], v[116:119], v[44:47]
	v_mfma_f32_16x16x32_bf16 v[40:43], v[92:95], v[116:119], v[40:43]
	v_mfma_f32_16x16x32_bf16 v[36:39], v[84:87], v[124:127], v[36:39]
	v_mfma_f32_16x16x32_bf16 v[32:35], v[92:95], v[124:127], v[32:35]
	s_barrier
	s_setprio 0
	s_nop 7
	s_add_i32 s22, s48, s28
	v_lshl_add_u64 v[128:129], v[128:129], 0, s[88:89]
	s_mov_b32 m0, s22
	ds_read_b128 v[96:99], v78 offset:49152
	ds_read_b128 v[100:103], v78 offset:50176
	ds_read_b128 v[104:107], v78 offset:51200
	ds_read_b128 v[108:111], v78 offset:52224
	ds_read_b128 v[112:115], v78 offset:53248
	ds_read_b128 v[116:119], v78 offset:54272
	ds_read_b128 v[120:123], v78 offset:55296
	ds_read_b128 v[124:127], v78 offset:56320
	global_load_lds_dwordx4 v[128:129], off
	s_add_i32 m0, s22, 0x2000
	s_add_u32 s20, s20, 0x20080
	v_lshl_add_u64 v[128:129], v[130:131], 0, s[88:89]
	s_addc_u32 s21, s21, 0
	global_load_lds_dwordx4 v[128:129], off
	v_lshl_add_u64 v[128:129], s[20:21], 0, v[68:69]
	s_mov_b32 m0, s41
	s_nop 0
	global_load_lds_dwordx4 v[128:129], off
	v_lshl_add_u64 v[128:129], s[20:21], 0, v[64:65]
	s_mov_b32 m0, s42
	s_nop 0
	global_load_lds_dwordx4 v[128:129], off
	v_lshl_add_u64 v[128:129], v[132:133], 0, s[88:89]
	s_mov_b32 m0, s39
	s_nop 0
	global_load_lds_dwordx4 v[128:129], off
	v_lshl_add_u64 v[128:129], v[134:135], 0, s[88:89]
	s_mov_b32 m0, s40
	s_nop 0
	global_load_lds_dwordx4 v[128:129], off
	s_waitcnt vmcnt(8)
	s_waitcnt lgkmcnt(0)
	s_setprio 1
	s_barrier
	v_mfma_f32_16x16x32_bf16 v[28:31], v[80:83], v[96:99], v[28:31]
	v_mfma_f32_16x16x32_bf16 v[24:27], v[88:91], v[96:99], v[24:27]
	v_mfma_f32_16x16x32_bf16 v[20:23], v[80:83], v[104:107], v[20:23]
	v_mfma_f32_16x16x32_bf16 v[16:19], v[88:91], v[104:107], v[16:19]
	v_mfma_f32_16x16x32_bf16 v[12:15], v[80:83], v[112:115], v[12:15]
	v_mfma_f32_16x16x32_bf16 v[8:11], v[88:91], v[112:115], v[8:11]
	v_mfma_f32_16x16x32_bf16 v[4:7], v[80:83], v[120:123], v[4:7]
	v_mfma_f32_16x16x32_bf16 v[0:3], v[88:91], v[120:123], v[0:3]
	v_mfma_f32_16x16x32_bf16 v[28:31], v[84:87], v[100:103], v[28:31]
	v_mfma_f32_16x16x32_bf16 v[24:27], v[92:95], v[100:103], v[24:27]
	v_mfma_f32_16x16x32_bf16 v[20:23], v[84:87], v[108:111], v[20:23]
	v_mfma_f32_16x16x32_bf16 v[16:19], v[92:95], v[108:111], v[16:19]
	v_mfma_f32_16x16x32_bf16 v[12:15], v[84:87], v[116:119], v[12:15]
	v_mfma_f32_16x16x32_bf16 v[8:11], v[92:95], v[116:119], v[8:11]
	v_mfma_f32_16x16x32_bf16 v[4:7], v[84:87], v[124:127], v[4:7]
	v_mfma_f32_16x16x32_bf16 v[0:3], v[92:95], v[124:127], v[0:3]
	s_barrier
	s_setprio 0
	s_nop 7
	s_add_i32 s47, s47, 2
	s_add_u32 s45, s45, 0x100
	s_addc_u32 s46, s46, 0
	s_add_u32 s18, s18, 0x100
	s_addc_u32 s19, s19, 0
	s_cmp_gt_u32 s47, 5
	s_cbranch_scc0 .LBB0_982
	s_and_b64 vcc, exec, s[4:5]
	v_readlane_b32 s44, v251, 59
	v_readlane_b32 s45, v251, 60
	s_cbranch_vccz .LBB0_985
	s_barrier

.LBB0_1509:
	s_add_u32 s26, s24, 0xfff00080
	s_addc_u32 s27, s25, -1
	s_add_i32 s33, 0, 0x10000
	s_cmp_eq_u32 s51, 60
	s_cselect_b32 s29, s17, s27
	s_cselect_b32 s28, s47, s26
	s_cselect_b32 s27, s19, s50
	s_cselect_b32 s26, s48, s49
	s_add_i32 s54, 0, 0x14000
	v_add_u32_e32 v156, s33, v143
	v_add_u32_e32 v172, s54, v143
	ds_read_b128 v[138:141], v156
	ds_read_b128 v[148:151], v156 offset:1024
	ds_read_b128 v[152:155], v156 offset:2048
	ds_read_b128 v[156:159], v156 offset:3072
	ds_read_b128 v[160:163], v172
	ds_read_b128 v[164:167], v172 offset:1024
	ds_read_b128 v[168:171], v172 offset:2048
	ds_read_b128 v[172:175], v172 offset:3072
	v_lshl_add_u64 v[188:189], s[24:25], 0, v[136:137]
	s_add_i32 m0, s37, 0xc000
	ds_read_b128 v[176:179], v147
	ds_read_b128 v[180:183], v147 offset:1024
	ds_read_b128 v[196:199], v147 offset:2048
	ds_read_b128 v[200:203], v147 offset:3072
	ds_read_b128 v[204:207], v147 offset:4096
	ds_read_b128 v[208:211], v147 offset:5120
	ds_read_b128 v[212:215], v147 offset:6144
	ds_read_b128 v[216:219], v147 offset:7168
	global_load_lds_dwordx4 v[188:189], off
	v_lshl_add_u64 v[188:189], s[24:25], 0, v[134:135]
	s_add_i32 m0, s37, 0xe000
	s_nop 0
	global_load_lds_dwordx4 v[188:189], off
	s_waitcnt vmcnt(8)
	s_waitcnt lgkmcnt(0)
	s_setprio 1
	s_barrier
	v_mfma_f32_16x16x32_bf16 v[124:127], v[138:141], v[176:179], v[124:127]
	v_mfma_f32_16x16x32_bf16 v[120:123], v[152:155], v[176:179], v[120:123]
	v_mfma_f32_16x16x32_bf16 v[108:111], v[138:141], v[196:199], v[108:111]
	v_mfma_f32_16x16x32_bf16 v[104:107], v[152:155], v[196:199], v[104:107]
	v_mfma_f32_16x16x32_bf16 v[92:95], v[138:141], v[204:207], v[92:95]
	v_mfma_f32_16x16x32_bf16 v[88:91], v[152:155], v[204:207], v[88:91]
	v_mfma_f32_16x16x32_bf16 v[76:79], v[138:141], v[212:215], v[76:79]
	v_mfma_f32_16x16x32_bf16 v[72:75], v[152:155], v[212:215], v[72:75]
	v_mfma_f32_16x16x32_bf16 v[124:127], v[148:151], v[180:183], v[124:127]
	v_mfma_f32_16x16x32_bf16 v[120:123], v[156:159], v[180:183], v[120:123]
	v_mfma_f32_16x16x32_bf16 v[108:111], v[148:151], v[200:203], v[108:111]
	v_mfma_f32_16x16x32_bf16 v[104:107], v[156:159], v[200:203], v[104:107]
	v_mfma_f32_16x16x32_bf16 v[92:95], v[148:151], v[208:211], v[92:95]
	v_mfma_f32_16x16x32_bf16 v[88:91], v[156:159], v[208:211], v[88:91]
	v_mfma_f32_16x16x32_bf16 v[76:79], v[148:151], v[216:219], v[76:79]
	v_mfma_f32_16x16x32_bf16 v[72:75], v[156:159], v[216:219], v[72:75]
	v_mfma_f32_16x16x32_bf16 v[116:119], v[160:163], v[176:179], v[116:119]
	v_mfma_f32_16x16x32_bf16 v[112:115], v[168:171], v[176:179], v[112:115]
	v_mfma_f32_16x16x32_bf16 v[100:103], v[160:163], v[196:199], v[100:103]
	v_mfma_f32_16x16x32_bf16 v[96:99], v[168:171], v[196:199], v[96:99]
	v_mfma_f32_16x16x32_bf16 v[84:87], v[160:163], v[204:207], v[84:87]
	v_mfma_f32_16x16x32_bf16 v[80:83], v[168:171], v[204:207], v[80:83]
	v_mfma_f32_16x16x32_bf16 v[68:71], v[160:163], v[212:215], v[68:71]
	v_mfma_f32_16x16x32_bf16 v[64:67], v[168:171], v[212:215], v[64:67]
	v_mfma_f32_16x16x32_bf16 v[116:119], v[164:167], v[180:183], v[116:119]
	v_mfma_f32_16x16x32_bf16 v[112:115], v[172:175], v[180:183], v[112:115]
	v_mfma_f32_16x16x32_bf16 v[100:103], v[164:167], v[200:203], v[100:103]
	v_mfma_f32_16x16x32_bf16 v[96:99], v[172:175], v[200:203], v[96:99]
	v_mfma_f32_16x16x32_bf16 v[84:87], v[164:167], v[208:211], v[84:87]
	v_mfma_f32_16x16x32_bf16 v[80:83], v[172:175], v[208:211], v[80:83]
	v_mfma_f32_16x16x32_bf16 v[68:71], v[164:167], v[216:219], v[68:71]
	v_mfma_f32_16x16x32_bf16 v[64:67], v[172:175], v[216:219], v[64:67]
	s_barrier
	s_setprio 0
	s_nop 7
	s_add_i32 s33, s33, s36
	v_lshl_add_u64 v[188:189], s[26:27], 0, v[144:145]
	s_mov_b32 m0, s33
	ds_read_b128 v[176:179], v147 offset:16384
	ds_read_b128 v[180:183], v147 offset:17408
	ds_read_b128 v[196:199], v147 offset:18432
	ds_read_b128 v[200:203], v147 offset:19456
	ds_read_b128 v[204:207], v147 offset:20480
	ds_read_b128 v[208:211], v147 offset:21504
	ds_read_b128 v[212:215], v147 offset:22528
	ds_read_b128 v[216:219], v147 offset:23552
	global_load_lds_dwordx4 v[188:189], off
	s_add_i32 m0, s33, 0x2000
	s_add_u32 s52, s26, 0x100000
	v_lshl_add_u64 v[190:191], s[26:27], 0, v[128:129]
	s_addc_u32 s53, s27, 0
	s_add_i32 s33, s54, s36
	global_load_lds_dwordx4 v[190:191], off
	v_lshl_add_u64 v[220:221], s[52:53], 0, v[144:145]
	s_mov_b32 m0, s33
	v_lshl_add_u64 v[222:223], s[28:29], 0, v[130:131]
	global_load_lds_dwordx4 v[220:221], off
	v_lshl_add_u64 v[220:221], s[52:53], 0, v[128:129]
	s_add_i32 m0, s33, 0x2000
	s_nop 0
	global_load_lds_dwordx4 v[220:221], off
	v_lshl_add_u64 v[220:221], s[28:29], 0, v[132:133]
	s_mov_b32 m0, s37
	s_nop 0
	global_load_lds_dwordx4 v[220:221], off
	s_mov_b32 m0, s38
	s_nop 0
	global_load_lds_dwordx4 v[222:223], off
	s_waitcnt vmcnt(8)
	s_waitcnt lgkmcnt(0)
	s_setprio 1
	s_barrier
	v_mfma_f32_16x16x32_bf16 v[60:63], v[138:141], v[176:179], v[60:63]
	v_mfma_f32_16x16x32_bf16 v[56:59], v[152:155], v[176:179], v[56:59]
	v_mfma_f32_16x16x32_bf16 v[44:47], v[138:141], v[196:199], v[44:47]
	v_mfma_f32_16x16x32_bf16 v[40:43], v[152:155], v[196:199], v[40:43]
	v_mfma_f32_16x16x32_bf16 v[28:31], v[138:141], v[204:207], v[28:31]
	v_mfma_f32_16x16x32_bf16 v[24:27], v[152:155], v[204:207], v[24:27]
	v_mfma_f32_16x16x32_bf16 v[12:15], v[138:141], v[212:215], v[12:15]
	v_mfma_f32_16x16x32_bf16 v[8:11], v[152:155], v[212:215], v[8:11]
	v_mfma_f32_16x16x32_bf16 v[60:63], v[148:151], v[180:183], v[60:63]
	v_mfma_f32_16x16x32_bf16 v[56:59], v[156:159], v[180:183], v[56:59]
	v_mfma_f32_16x16x32_bf16 v[44:47], v[148:151], v[200:203], v[44:47]
	v_mfma_f32_16x16x32_bf16 v[40:43], v[156:159], v[200:203], v[40:43]
	v_mfma_f32_16x16x32_bf16 v[28:31], v[148:151], v[208:211], v[28:31]
	v_mfma_f32_16x16x32_bf16 v[24:27], v[156:159], v[208:211], v[24:27]
	v_mfma_f32_16x16x32_bf16 v[12:15], v[148:151], v[216:219], v[12:15]
	v_mfma_f32_16x16x32_bf16 v[8:11], v[156:159], v[216:219], v[8:11]
	v_mfma_f32_16x16x32_bf16 v[52:55], v[160:163], v[176:179], v[52:55]
	v_mfma_f32_16x16x32_bf16 v[48:51], v[168:171], v[176:179], v[48:51]
	v_mfma_f32_16x16x32_bf16 v[36:39], v[160:163], v[196:199], v[36:39]
	v_mfma_f32_16x16x32_bf16 v[32:35], v[168:171], v[196:199], v[32:35]
	v_mfma_f32_16x16x32_bf16 v[20:23], v[160:163], v[204:207], v[20:23]
	v_mfma_f32_16x16x32_bf16 v[16:19], v[168:171], v[204:207], v[16:19]
	v_mfma_f32_16x16x32_bf16 v[4:7], v[160:163], v[212:215], v[4:7]
	v_mfma_f32_16x16x32_bf16 v[0:3], v[168:171], v[212:215], v[0:3]
	v_mfma_f32_16x16x32_bf16 v[52:55], v[164:167], v[180:183], v[52:55]
	v_mfma_f32_16x16x32_bf16 v[48:51], v[172:175], v[180:183], v[48:51]
	v_mfma_f32_16x16x32_bf16 v[36:39], v[164:167], v[200:203], v[36:39]
	v_mfma_f32_16x16x32_bf16 v[32:35], v[172:175], v[200:203], v[32:35]
	v_mfma_f32_16x16x32_bf16 v[20:23], v[164:167], v[208:211], v[20:23]
	v_mfma_f32_16x16x32_bf16 v[16:19], v[172:175], v[208:211], v[16:19]
	v_mfma_f32_16x16x32_bf16 v[4:7], v[164:167], v[216:219], v[4:7]
	v_mfma_f32_16x16x32_bf16 v[0:3], v[172:175], v[216:219], v[0:3]
	s_barrier
	s_setprio 0
	s_nop 7
	s_add_i32 s33, 0, 0x18000
	s_add_i32 s52, 0, 0x1c000
	v_add_u32_e32 v156, s33, v143
	v_add_u32_e32 v172, s52, v143
	ds_read_b128 v[138:141], v156
	ds_read_b128 v[148:151], v156 offset:1024
	ds_read_b128 v[152:155], v156 offset:2048
	ds_read_b128 v[156:159], v156 offset:3072
	ds_read_b128 v[160:163], v172
	ds_read_b128 v[164:167], v172 offset:1024
	ds_read_b128 v[168:171], v172 offset:2048
	ds_read_b128 v[172:175], v172 offset:3072
	s_add_u32 s28, s28, 0x100000
	s_addc_u32 s29, s29, 0
	s_mov_b32 m0, s39
	v_lshl_add_u64 v[224:225], s[28:29], 0, v[132:133]
	ds_read_b128 v[176:179], v147 offset:32768
	ds_read_b128 v[180:183], v147 offset:33792
	ds_read_b128 v[196:199], v147 offset:34816
	ds_read_b128 v[200:203], v147 offset:35840
	ds_read_b128 v[204:207], v147 offset:36864
	ds_read_b128 v[208:211], v147 offset:37888
	ds_read_b128 v[212:215], v147 offset:38912
	ds_read_b128 v[216:219], v147 offset:39936
	global_load_lds_dwordx4 v[224:225], off
	v_lshl_add_u64 v[224:225], s[28:29], 0, v[130:131]
	s_mov_b32 m0, s40
	s_nop 0
	global_load_lds_dwordx4 v[224:225], off
	s_waitcnt vmcnt(8)
	s_waitcnt lgkmcnt(0)
	s_setprio 1
	s_barrier
	v_mfma_f32_16x16x32_bf16 v[124:127], v[138:141], v[176:179], v[124:127]
	v_mfma_f32_16x16x32_bf16 v[120:123], v[152:155], v[176:179], v[120:123]
	v_mfma_f32_16x16x32_bf16 v[108:111], v[138:141], v[196:199], v[108:111]
	v_mfma_f32_16x16x32_bf16 v[104:107], v[152:155], v[196:199], v[104:107]
	v_mfma_f32_16x16x32_bf16 v[92:95], v[138:141], v[204:207], v[92:95]
	v_mfma_f32_16x16x32_bf16 v[88:91], v[152:155], v[204:207], v[88:91]
	v_mfma_f32_16x16x32_bf16 v[76:79], v[138:141], v[212:215], v[76:79]
	v_mfma_f32_16x16x32_bf16 v[72:75], v[152:155], v[212:215], v[72:75]
	v_mfma_f32_16x16x32_bf16 v[124:127], v[148:151], v[180:183], v[124:127]
	v_mfma_f32_16x16x32_bf16 v[120:123], v[156:159], v[180:183], v[120:123]
	v_mfma_f32_16x16x32_bf16 v[108:111], v[148:151], v[200:203], v[108:111]
	v_mfma_f32_16x16x32_bf16 v[104:107], v[156:159], v[200:203], v[104:107]
	v_mfma_f32_16x16x32_bf16 v[92:95], v[148:151], v[208:211], v[92:95]
	v_mfma_f32_16x16x32_bf16 v[88:91], v[156:159], v[208:211], v[88:91]
	v_mfma_f32_16x16x32_bf16 v[76:79], v[148:151], v[216:219], v[76:79]
	v_mfma_f32_16x16x32_bf16 v[72:75], v[156:159], v[216:219], v[72:75]
	v_mfma_f32_16x16x32_bf16 v[116:119], v[160:163], v[176:179], v[116:119]
	v_mfma_f32_16x16x32_bf16 v[112:115], v[168:171], v[176:179], v[112:115]
	v_mfma_f32_16x16x32_bf16 v[100:103], v[160:163], v[196:199], v[100:103]
	v_mfma_f32_16x16x32_bf16 v[96:99], v[168:171], v[196:199], v[96:99]
	v_mfma_f32_16x16x32_bf16 v[84:87], v[160:163], v[204:207], v[84:87]
	v_mfma_f32_16x16x32_bf16 v[80:83], v[168:171], v[204:207], v[80:83]
	v_mfma_f32_16x16x32_bf16 v[68:71], v[160:163], v[212:215], v[68:71]
	v_mfma_f32_16x16x32_bf16 v[64:67], v[168:171], v[212:215], v[64:67]
	v_mfma_f32_16x16x32_bf16 v[116:119], v[164:167], v[180:183], v[116:119]
	v_mfma_f32_16x16x32_bf16 v[112:115], v[172:175], v[180:183], v[112:115]
	v_mfma_f32_16x16x32_bf16 v[100:103], v[164:167], v[200:203], v[100:103]
	v_mfma_f32_16x16x32_bf16 v[96:99], v[172:175], v[200:203], v[96:99]
	v_mfma_f32_16x16x32_bf16 v[84:87], v[164:167], v[208:211], v[84:87]
	v_mfma_f32_16x16x32_bf16 v[80:83], v[172:175], v[208:211], v[80:83]
	v_mfma_f32_16x16x32_bf16 v[68:71], v[164:167], v[216:219], v[68:71]
	v_mfma_f32_16x16x32_bf16 v[64:67], v[172:175], v[216:219], v[64:67]
	s_barrier
	s_setprio 0
	s_nop 7
	s_add_i32 s28, s33, s36
	v_lshl_add_u64 v[188:189], v[188:189], 0, s[88:89]
	s_mov_b32 m0, s28
	ds_read_b128 v[176:179], v147 offset:49152
	ds_read_b128 v[180:183], v147 offset:50176
	ds_read_b128 v[196:199], v147 offset:51200
	ds_read_b128 v[200:203], v147 offset:52224
	ds_read_b128 v[204:207], v147 offset:53248
	ds_read_b128 v[208:211], v147 offset:54272
	ds_read_b128 v[212:215], v147 offset:55296
	ds_read_b128 v[216:219], v147 offset:56320
	global_load_lds_dwordx4 v[188:189], off
	s_add_i32 m0, s28, 0x2000
	s_add_u32 s26, s26, 0x100080
	v_lshl_add_u64 v[188:189], v[190:191], 0, s[88:89]
	s_addc_u32 s27, s27, 0
	s_add_i32 s28, s52, s36
	global_load_lds_dwordx4 v[188:189], off
	v_lshl_add_u64 v[188:189], s[26:27], 0, v[144:145]
	s_mov_b32 m0, s28
	s_nop 0
	global_load_lds_dwordx4 v[188:189], off
	v_lshl_add_u64 v[188:189], s[26:27], 0, v[128:129]
	s_add_i32 m0, s28, 0x2000
	s_nop 0
	global_load_lds_dwordx4 v[188:189], off
	v_lshl_add_u64 v[188:189], v[220:221], 0, s[88:89]
	s_mov_b32 m0, s42
	s_nop 0
	global_load_lds_dwordx4 v[188:189], off
	v_lshl_add_u64 v[188:189], v[222:223], 0, s[88:89]
	s_mov_b32 m0, s43
	s_nop 0
	global_load_lds_dwordx4 v[188:189], off
	s_waitcnt vmcnt(8)
	s_waitcnt lgkmcnt(0)
	s_setprio 1
	s_barrier
	v_mfma_f32_16x16x32_bf16 v[60:63], v[138:141], v[176:179], v[60:63]
	v_mfma_f32_16x16x32_bf16 v[56:59], v[152:155], v[176:179], v[56:59]
	v_mfma_f32_16x16x32_bf16 v[44:47], v[138:141], v[196:199], v[44:47]
	v_mfma_f32_16x16x32_bf16 v[40:43], v[152:155], v[196:199], v[40:43]
	v_mfma_f32_16x16x32_bf16 v[28:31], v[138:141], v[204:207], v[28:31]
	v_mfma_f32_16x16x32_bf16 v[24:27], v[152:155], v[204:207], v[24:27]
	v_mfma_f32_16x16x32_bf16 v[12:15], v[138:141], v[212:215], v[12:15]
	v_mfma_f32_16x16x32_bf16 v[8:11], v[152:155], v[212:215], v[8:11]
	v_mfma_f32_16x16x32_bf16 v[60:63], v[148:151], v[180:183], v[60:63]
	v_mfma_f32_16x16x32_bf16 v[56:59], v[156:159], v[180:183], v[56:59]
	v_mfma_f32_16x16x32_bf16 v[44:47], v[148:151], v[200:203], v[44:47]
	v_mfma_f32_16x16x32_bf16 v[40:43], v[156:159], v[200:203], v[40:43]
	v_mfma_f32_16x16x32_bf16 v[28:31], v[148:151], v[208:211], v[28:31]
	v_mfma_f32_16x16x32_bf16 v[24:27], v[156:159], v[208:211], v[24:27]
	v_mfma_f32_16x16x32_bf16 v[12:15], v[148:151], v[216:219], v[12:15]
	v_mfma_f32_16x16x32_bf16 v[8:11], v[156:159], v[216:219], v[8:11]
	v_mfma_f32_16x16x32_bf16 v[52:55], v[160:163], v[176:179], v[52:55]
	v_mfma_f32_16x16x32_bf16 v[48:51], v[168:171], v[176:179], v[48:51]
	v_mfma_f32_16x16x32_bf16 v[36:39], v[160:163], v[196:199], v[36:39]
	v_mfma_f32_16x16x32_bf16 v[32:35], v[168:171], v[196:199], v[32:35]
	v_mfma_f32_16x16x32_bf16 v[20:23], v[160:163], v[204:207], v[20:23]
	v_mfma_f32_16x16x32_bf16 v[16:19], v[168:171], v[204:207], v[16:19]
	v_mfma_f32_16x16x32_bf16 v[4:7], v[160:163], v[212:215], v[4:7]
	v_mfma_f32_16x16x32_bf16 v[0:3], v[168:171], v[212:215], v[0:3]
	v_mfma_f32_16x16x32_bf16 v[52:55], v[164:167], v[180:183], v[52:55]
	v_mfma_f32_16x16x32_bf16 v[48:51], v[172:175], v[180:183], v[48:51]
	v_mfma_f32_16x16x32_bf16 v[36:39], v[164:167], v[200:203], v[36:39]
	v_mfma_f32_16x16x32_bf16 v[32:35], v[172:175], v[200:203], v[32:35]
	v_mfma_f32_16x16x32_bf16 v[20:23], v[164:167], v[208:211], v[20:23]
	v_mfma_f32_16x16x32_bf16 v[16:19], v[172:175], v[208:211], v[16:19]
	v_mfma_f32_16x16x32_bf16 v[4:7], v[164:167], v[216:219], v[4:7]
	v_mfma_f32_16x16x32_bf16 v[0:3], v[172:175], v[216:219], v[0:3]
	s_barrier
	s_setprio 0
	s_nop 7
	s_add_i32 s51, s51, 2
	s_add_u32 s49, s49, 0x100
	s_addc_u32 s50, s50, 0
	s_add_u32 s24, s24, 0x100
	s_addc_u32 s25, s25, 0
	s_cmp_gt_u32 s51, 61
	s_cbranch_scc0 .LBB0_1509
	s_and_b64 vcc, exec, s[14:15]
	s_cbranch_vccz .LBB0_1512
	s_barrier

.LBB0_1594:
	s_add_u32 s26, s6, 0xfff00080
	s_addc_u32 s27, s7, -1
	s_add_i32 s33, 0, 0x10000
	s_cmp_eq_u32 s49, 12
	s_cselect_b32 s29, s23, s27
	s_cselect_b32 s28, s22, s26
	s_cselect_b32 s27, s19, s48
	s_cselect_b32 s26, s21, s47
	s_add_i32 s52, 0, 0x14000
	v_add_u32_e32 v124, s33, v161
	v_add_u32_e32 v172, s52, v161
	ds_read_b128 v[112:115], v124
	ds_read_b128 v[116:119], v124 offset:1024
	ds_read_b128 v[120:123], v124 offset:2048
	ds_read_b128 v[124:127], v124 offset:3072
	ds_read_b128 v[156:159], v172
	ds_read_b128 v[164:167], v172 offset:1024
	ds_read_b128 v[168:171], v172 offset:2048
	ds_read_b128 v[172:175], v172 offset:3072
	v_lshl_add_u64 v[180:181], s[6:7], 0, v[154:155]
	s_add_i32 m0, s37, 0xc000
	ds_read_b128 v[176:179], v163
	ds_read_b128 v[196:199], v163 offset:1024
	ds_read_b128 v[200:203], v163 offset:2048
	ds_read_b128 v[204:207], v163 offset:3072
	ds_read_b128 v[208:211], v163 offset:4096
	ds_read_b128 v[212:215], v163 offset:5120
	ds_read_b128 v[216:219], v163 offset:6144
	ds_read_b128 v[220:223], v163 offset:7168
	global_load_lds_dwordx4 v[180:181], off
	v_lshl_add_u64 v[180:181], s[6:7], 0, v[152:153]
	s_add_i32 m0, s37, 0xe000
	s_nop 0
	global_load_lds_dwordx4 v[180:181], off
	s_waitcnt vmcnt(8)
	s_waitcnt lgkmcnt(0)
	s_setprio 1
	s_barrier
	v_mfma_f32_16x16x32_bf16 v[140:143], v[112:115], v[176:179], v[140:143]
	v_mfma_f32_16x16x32_bf16 v[136:139], v[120:123], v[176:179], v[136:139]
	v_mfma_f32_16x16x32_bf16 v[108:111], v[112:115], v[200:203], v[108:111]
	v_mfma_f32_16x16x32_bf16 v[104:107], v[120:123], v[200:203], v[104:107]
	v_mfma_f32_16x16x32_bf16 v[92:95], v[112:115], v[208:211], v[92:95]
	v_mfma_f32_16x16x32_bf16 v[88:91], v[120:123], v[208:211], v[88:91]
	v_mfma_f32_16x16x32_bf16 v[76:79], v[112:115], v[216:219], v[76:79]
	v_mfma_f32_16x16x32_bf16 v[72:75], v[120:123], v[216:219], v[72:75]
	v_mfma_f32_16x16x32_bf16 v[140:143], v[116:119], v[196:199], v[140:143]
	v_mfma_f32_16x16x32_bf16 v[136:139], v[124:127], v[196:199], v[136:139]
	v_mfma_f32_16x16x32_bf16 v[108:111], v[116:119], v[204:207], v[108:111]
	v_mfma_f32_16x16x32_bf16 v[104:107], v[124:127], v[204:207], v[104:107]
	v_mfma_f32_16x16x32_bf16 v[92:95], v[116:119], v[212:215], v[92:95]
	v_mfma_f32_16x16x32_bf16 v[88:91], v[124:127], v[212:215], v[88:91]
	v_mfma_f32_16x16x32_bf16 v[76:79], v[116:119], v[220:223], v[76:79]
	v_mfma_f32_16x16x32_bf16 v[72:75], v[124:127], v[220:223], v[72:75]
	v_mfma_f32_16x16x32_bf16 v[132:135], v[156:159], v[176:179], v[132:135]
	v_mfma_f32_16x16x32_bf16 v[128:131], v[168:171], v[176:179], v[128:131]
	v_mfma_f32_16x16x32_bf16 v[100:103], v[156:159], v[200:203], v[100:103]
	v_mfma_f32_16x16x32_bf16 v[96:99], v[168:171], v[200:203], v[96:99]
	v_mfma_f32_16x16x32_bf16 v[84:87], v[156:159], v[208:211], v[84:87]
	v_mfma_f32_16x16x32_bf16 v[80:83], v[168:171], v[208:211], v[80:83]
	v_mfma_f32_16x16x32_bf16 v[68:71], v[156:159], v[216:219], v[68:71]
	v_mfma_f32_16x16x32_bf16 v[64:67], v[168:171], v[216:219], v[64:67]
	v_mfma_f32_16x16x32_bf16 v[132:135], v[164:167], v[196:199], v[132:135]
	v_mfma_f32_16x16x32_bf16 v[128:131], v[172:175], v[196:199], v[128:131]
	v_mfma_f32_16x16x32_bf16 v[100:103], v[164:167], v[204:207], v[100:103]
	v_mfma_f32_16x16x32_bf16 v[96:99], v[172:175], v[204:207], v[96:99]
	v_mfma_f32_16x16x32_bf16 v[84:87], v[164:167], v[212:215], v[84:87]
	v_mfma_f32_16x16x32_bf16 v[80:83], v[172:175], v[212:215], v[80:83]
	v_mfma_f32_16x16x32_bf16 v[68:71], v[164:167], v[220:223], v[68:71]
	v_mfma_f32_16x16x32_bf16 v[64:67], v[172:175], v[220:223], v[64:67]
	s_barrier
	s_setprio 0
	s_nop 7
	s_add_i32 s33, s33, s36
	v_lshl_add_u64 v[180:181], s[26:27], 0, v[144:145]
	s_mov_b32 m0, s33
	ds_read_b128 v[176:179], v163 offset:16384
	ds_read_b128 v[196:199], v163 offset:17408
	ds_read_b128 v[200:203], v163 offset:18432
	ds_read_b128 v[204:207], v163 offset:19456
	ds_read_b128 v[208:211], v163 offset:20480
	ds_read_b128 v[212:215], v163 offset:21504
	ds_read_b128 v[216:219], v163 offset:22528
	ds_read_b128 v[220:223], v163 offset:23552
	global_load_lds_dwordx4 v[180:181], off
	s_add_i32 m0, s33, 0x2000
	s_add_u32 s50, s26, 0x40000
	v_lshl_add_u64 v[182:183], s[26:27], 0, v[146:147]
	s_addc_u32 s51, s27, 0
	s_add_i32 s33, s52, s36
	global_load_lds_dwordx4 v[182:183], off
	v_lshl_add_u64 v[188:189], s[50:51], 0, v[144:145]
	s_mov_b32 m0, s33
	v_lshl_add_u64 v[190:191], s[28:29], 0, v[148:149]
	global_load_lds_dwordx4 v[188:189], off
	v_lshl_add_u64 v[188:189], s[50:51], 0, v[146:147]
	s_add_i32 m0, s33, 0x2000
	s_nop 0
	global_load_lds_dwordx4 v[188:189], off
	v_lshl_add_u64 v[188:189], s[28:29], 0, v[150:151]
	s_mov_b32 m0, s37
	s_nop 0
	global_load_lds_dwordx4 v[188:189], off
	s_mov_b32 m0, s38
	s_nop 0
	global_load_lds_dwordx4 v[190:191], off
	s_waitcnt vmcnt(8)
	s_waitcnt lgkmcnt(0)
	s_setprio 1
	s_barrier
	v_mfma_f32_16x16x32_bf16 v[60:63], v[112:115], v[176:179], v[60:63]
	v_mfma_f32_16x16x32_bf16 v[56:59], v[120:123], v[176:179], v[56:59]
	v_mfma_f32_16x16x32_bf16 v[44:47], v[112:115], v[200:203], v[44:47]
	v_mfma_f32_16x16x32_bf16 v[40:43], v[120:123], v[200:203], v[40:43]
	v_mfma_f32_16x16x32_bf16 v[28:31], v[112:115], v[208:211], v[28:31]
	v_mfma_f32_16x16x32_bf16 v[24:27], v[120:123], v[208:211], v[24:27]
	v_mfma_f32_16x16x32_bf16 v[12:15], v[112:115], v[216:219], v[12:15]
	v_mfma_f32_16x16x32_bf16 v[8:11], v[120:123], v[216:219], v[8:11]
	v_mfma_f32_16x16x32_bf16 v[60:63], v[116:119], v[196:199], v[60:63]
	v_mfma_f32_16x16x32_bf16 v[56:59], v[124:127], v[196:199], v[56:59]
	v_mfma_f32_16x16x32_bf16 v[44:47], v[116:119], v[204:207], v[44:47]
	v_mfma_f32_16x16x32_bf16 v[40:43], v[124:127], v[204:207], v[40:43]
	v_mfma_f32_16x16x32_bf16 v[28:31], v[116:119], v[212:215], v[28:31]
	v_mfma_f32_16x16x32_bf16 v[24:27], v[124:127], v[212:215], v[24:27]
	v_mfma_f32_16x16x32_bf16 v[12:15], v[116:119], v[220:223], v[12:15]
	v_mfma_f32_16x16x32_bf16 v[8:11], v[124:127], v[220:223], v[8:11]
	v_mfma_f32_16x16x32_bf16 v[52:55], v[156:159], v[176:179], v[52:55]
	v_mfma_f32_16x16x32_bf16 v[48:51], v[168:171], v[176:179], v[48:51]
	v_mfma_f32_16x16x32_bf16 v[36:39], v[156:159], v[200:203], v[36:39]
	v_mfma_f32_16x16x32_bf16 v[32:35], v[168:171], v[200:203], v[32:35]
	v_mfma_f32_16x16x32_bf16 v[20:23], v[156:159], v[208:211], v[20:23]
	v_mfma_f32_16x16x32_bf16 v[16:19], v[168:171], v[208:211], v[16:19]
	v_mfma_f32_16x16x32_bf16 v[4:7], v[156:159], v[216:219], v[4:7]
	v_mfma_f32_16x16x32_bf16 v[0:3], v[168:171], v[216:219], v[0:3]
	v_mfma_f32_16x16x32_bf16 v[52:55], v[164:167], v[196:199], v[52:55]
	v_mfma_f32_16x16x32_bf16 v[48:51], v[172:175], v[196:199], v[48:51]
	v_mfma_f32_16x16x32_bf16 v[36:39], v[164:167], v[204:207], v[36:39]
	v_mfma_f32_16x16x32_bf16 v[32:35], v[172:175], v[204:207], v[32:35]
	v_mfma_f32_16x16x32_bf16 v[20:23], v[164:167], v[212:215], v[20:23]
	v_mfma_f32_16x16x32_bf16 v[16:19], v[172:175], v[212:215], v[16:19]
	v_mfma_f32_16x16x32_bf16 v[4:7], v[164:167], v[220:223], v[4:7]
	v_mfma_f32_16x16x32_bf16 v[0:3], v[172:175], v[220:223], v[0:3]
	s_barrier
	s_setprio 0
	s_nop 7
	s_add_i32 s33, 0, 0x18000
	s_add_i32 s50, 0, 0x1c000
	v_add_u32_e32 v124, s33, v161
	v_add_u32_e32 v172, s50, v161
	ds_read_b128 v[112:115], v124
	ds_read_b128 v[116:119], v124 offset:1024
	ds_read_b128 v[120:123], v124 offset:2048
	ds_read_b128 v[124:127], v124 offset:3072
	ds_read_b128 v[156:159], v172
	ds_read_b128 v[164:167], v172 offset:1024
	ds_read_b128 v[168:171], v172 offset:2048
	ds_read_b128 v[172:175], v172 offset:3072
	s_add_u32 s28, s28, 0x100000
	s_addc_u32 s29, s29, 0
	s_mov_b32 m0, s39
	v_lshl_add_u64 v[224:225], s[28:29], 0, v[150:151]
	ds_read_b128 v[176:179], v163 offset:32768
	ds_read_b128 v[196:199], v163 offset:33792
	ds_read_b128 v[200:203], v163 offset:34816
	ds_read_b128 v[204:207], v163 offset:35840
	ds_read_b128 v[208:211], v163 offset:36864
	ds_read_b128 v[212:215], v163 offset:37888
	ds_read_b128 v[216:219], v163 offset:38912
	ds_read_b128 v[220:223], v163 offset:39936
	global_load_lds_dwordx4 v[224:225], off
	v_lshl_add_u64 v[224:225], s[28:29], 0, v[148:149]
	s_mov_b32 m0, s40
	s_nop 0
	global_load_lds_dwordx4 v[224:225], off
	s_waitcnt vmcnt(8)
	s_waitcnt lgkmcnt(0)
	s_setprio 1
	s_barrier
	v_mfma_f32_16x16x32_bf16 v[140:143], v[112:115], v[176:179], v[140:143]
	v_mfma_f32_16x16x32_bf16 v[136:139], v[120:123], v[176:179], v[136:139]
	v_mfma_f32_16x16x32_bf16 v[108:111], v[112:115], v[200:203], v[108:111]
	v_mfma_f32_16x16x32_bf16 v[104:107], v[120:123], v[200:203], v[104:107]
	v_mfma_f32_16x16x32_bf16 v[92:95], v[112:115], v[208:211], v[92:95]
	v_mfma_f32_16x16x32_bf16 v[88:91], v[120:123], v[208:211], v[88:91]
	v_mfma_f32_16x16x32_bf16 v[76:79], v[112:115], v[216:219], v[76:79]
	v_mfma_f32_16x16x32_bf16 v[72:75], v[120:123], v[216:219], v[72:75]
	v_mfma_f32_16x16x32_bf16 v[140:143], v[116:119], v[196:199], v[140:143]
	v_mfma_f32_16x16x32_bf16 v[136:139], v[124:127], v[196:199], v[136:139]
	v_mfma_f32_16x16x32_bf16 v[108:111], v[116:119], v[204:207], v[108:111]
	v_mfma_f32_16x16x32_bf16 v[104:107], v[124:127], v[204:207], v[104:107]
	v_mfma_f32_16x16x32_bf16 v[92:95], v[116:119], v[212:215], v[92:95]
	v_mfma_f32_16x16x32_bf16 v[88:91], v[124:127], v[212:215], v[88:91]
	v_mfma_f32_16x16x32_bf16 v[76:79], v[116:119], v[220:223], v[76:79]
	v_mfma_f32_16x16x32_bf16 v[72:75], v[124:127], v[220:223], v[72:75]
	v_mfma_f32_16x16x32_bf16 v[132:135], v[156:159], v[176:179], v[132:135]
	v_mfma_f32_16x16x32_bf16 v[128:131], v[168:171], v[176:179], v[128:131]
	v_mfma_f32_16x16x32_bf16 v[100:103], v[156:159], v[200:203], v[100:103]
	v_mfma_f32_16x16x32_bf16 v[96:99], v[168:171], v[200:203], v[96:99]
	v_mfma_f32_16x16x32_bf16 v[84:87], v[156:159], v[208:211], v[84:87]
	v_mfma_f32_16x16x32_bf16 v[80:83], v[168:171], v[208:211], v[80:83]
	v_mfma_f32_16x16x32_bf16 v[68:71], v[156:159], v[216:219], v[68:71]
	v_mfma_f32_16x16x32_bf16 v[64:67], v[168:171], v[216:219], v[64:67]
	v_mfma_f32_16x16x32_bf16 v[132:135], v[164:167], v[196:199], v[132:135]
	v_mfma_f32_16x16x32_bf16 v[128:131], v[172:175], v[196:199], v[128:131]
	v_mfma_f32_16x16x32_bf16 v[100:103], v[164:167], v[204:207], v[100:103]
	v_mfma_f32_16x16x32_bf16 v[96:99], v[172:175], v[204:207], v[96:99]
	v_mfma_f32_16x16x32_bf16 v[84:87], v[164:167], v[212:215], v[84:87]
	v_mfma_f32_16x16x32_bf16 v[80:83], v[172:175], v[212:215], v[80:83]
	v_mfma_f32_16x16x32_bf16 v[68:71], v[164:167], v[220:223], v[68:71]
	v_mfma_f32_16x16x32_bf16 v[64:67], v[172:175], v[220:223], v[64:67]
	s_barrier
	s_setprio 0
	s_nop 7
	s_add_i32 s28, s33, s36
	v_lshl_add_u64 v[180:181], v[180:181], 0, s[88:89]
	s_mov_b32 m0, s28
	ds_read_b128 v[176:179], v163 offset:49152
	ds_read_b128 v[196:199], v163 offset:50176
	ds_read_b128 v[200:203], v163 offset:51200
	ds_read_b128 v[204:207], v163 offset:52224
	ds_read_b128 v[208:211], v163 offset:53248
	ds_read_b128 v[212:215], v163 offset:54272
	ds_read_b128 v[216:219], v163 offset:55296
	ds_read_b128 v[220:223], v163 offset:56320
	global_load_lds_dwordx4 v[180:181], off
	s_add_i32 m0, s28, 0x2000
	s_add_u32 s26, s26, 0x40080
	v_lshl_add_u64 v[180:181], v[182:183], 0, s[88:89]
	s_addc_u32 s27, s27, 0
	s_add_i32 s28, s50, s36
	global_load_lds_dwordx4 v[180:181], off
	v_lshl_add_u64 v[180:181], s[26:27], 0, v[144:145]
	s_mov_b32 m0, s28
	s_nop 0
	global_load_lds_dwordx4 v[180:181], off
	v_lshl_add_u64 v[180:181], s[26:27], 0, v[146:147]
	s_add_i32 m0, s28, 0x2000
	s_nop 0
	global_load_lds_dwordx4 v[180:181], off
	v_lshl_add_u64 v[180:181], v[188:189], 0, s[88:89]
	s_mov_b32 m0, s42
	s_nop 0
	global_load_lds_dwordx4 v[180:181], off
	v_lshl_add_u64 v[180:181], v[190:191], 0, s[88:89]
	s_mov_b32 m0, s43
	s_nop 0
	global_load_lds_dwordx4 v[180:181], off
	s_waitcnt vmcnt(8)
	s_waitcnt lgkmcnt(0)
	s_setprio 1
	s_barrier
	v_mfma_f32_16x16x32_bf16 v[60:63], v[112:115], v[176:179], v[60:63]
	v_mfma_f32_16x16x32_bf16 v[56:59], v[120:123], v[176:179], v[56:59]
	v_mfma_f32_16x16x32_bf16 v[44:47], v[112:115], v[200:203], v[44:47]
	v_mfma_f32_16x16x32_bf16 v[40:43], v[120:123], v[200:203], v[40:43]
	v_mfma_f32_16x16x32_bf16 v[28:31], v[112:115], v[208:211], v[28:31]
	v_mfma_f32_16x16x32_bf16 v[24:27], v[120:123], v[208:211], v[24:27]
	v_mfma_f32_16x16x32_bf16 v[12:15], v[112:115], v[216:219], v[12:15]
	v_mfma_f32_16x16x32_bf16 v[8:11], v[120:123], v[216:219], v[8:11]
	v_mfma_f32_16x16x32_bf16 v[60:63], v[116:119], v[196:199], v[60:63]
	v_mfma_f32_16x16x32_bf16 v[56:59], v[124:127], v[196:199], v[56:59]
	v_mfma_f32_16x16x32_bf16 v[44:47], v[116:119], v[204:207], v[44:47]
	v_mfma_f32_16x16x32_bf16 v[40:43], v[124:127], v[204:207], v[40:43]
	v_mfma_f32_16x16x32_bf16 v[28:31], v[116:119], v[212:215], v[28:31]
	v_mfma_f32_16x16x32_bf16 v[24:27], v[124:127], v[212:215], v[24:27]
	v_mfma_f32_16x16x32_bf16 v[12:15], v[116:119], v[220:223], v[12:15]
	v_mfma_f32_16x16x32_bf16 v[8:11], v[124:127], v[220:223], v[8:11]
	v_mfma_f32_16x16x32_bf16 v[52:55], v[156:159], v[176:179], v[52:55]
	v_mfma_f32_16x16x32_bf16 v[48:51], v[168:171], v[176:179], v[48:51]
	v_mfma_f32_16x16x32_bf16 v[36:39], v[156:159], v[200:203], v[36:39]
	v_mfma_f32_16x16x32_bf16 v[32:35], v[168:171], v[200:203], v[32:35]
	v_mfma_f32_16x16x32_bf16 v[20:23], v[156:159], v[208:211], v[20:23]
	v_mfma_f32_16x16x32_bf16 v[16:19], v[168:171], v[208:211], v[16:19]
	v_mfma_f32_16x16x32_bf16 v[4:7], v[156:159], v[216:219], v[4:7]
	v_mfma_f32_16x16x32_bf16 v[0:3], v[168:171], v[216:219], v[0:3]
	v_mfma_f32_16x16x32_bf16 v[52:55], v[164:167], v[196:199], v[52:55]
	v_mfma_f32_16x16x32_bf16 v[48:51], v[172:175], v[196:199], v[48:51]
	v_mfma_f32_16x16x32_bf16 v[36:39], v[164:167], v[204:207], v[36:39]
	v_mfma_f32_16x16x32_bf16 v[32:35], v[172:175], v[204:207], v[32:35]
	v_mfma_f32_16x16x32_bf16 v[20:23], v[164:167], v[212:215], v[20:23]
	v_mfma_f32_16x16x32_bf16 v[16:19], v[172:175], v[212:215], v[16:19]
	v_mfma_f32_16x16x32_bf16 v[4:7], v[164:167], v[220:223], v[4:7]
	v_mfma_f32_16x16x32_bf16 v[0:3], v[172:175], v[220:223], v[0:3]
	s_barrier
	s_setprio 0
	s_nop 7
	s_add_i32 s49, s49, 2
	s_add_u32 s47, s47, 0x100
	s_addc_u32 s48, s48, 0
	s_add_u32 s6, s6, 0x100
	s_addc_u32 s7, s7, 0
	s_cmp_gt_u32 s49, 13
	s_cbranch_scc0 .LBB0_1594
	s_and_b64 vcc, exec, s[16:17]
	s_cbranch_vccz .LBB0_1597
	s_barrier

.LBB0_1758:
	s_add_u32 s10, s24, 0xfff00080
	s_addc_u32 s11, s25, -1
	s_add_i32 s33, 0, 0x10000
	s_cmp_eq_u32 s50, 60
	s_cselect_b32 s29, s19, s11
	s_cselect_b32 s28, s46, s10
	s_cselect_b32 s27, s17, s49
	s_cselect_b32 s26, s47, s48
	s_add_i32 s10, 0, 0x14000
	v_add_u32_e32 v156, s33, v143
	v_add_u32_e32 v172, s10, v143
	ds_read_b128 v[138:141], v156
	ds_read_b128 v[148:151], v156 offset:1024
	ds_read_b128 v[152:155], v156 offset:2048
	ds_read_b128 v[156:159], v156 offset:3072
	ds_read_b128 v[160:163], v172
	ds_read_b128 v[164:167], v172 offset:1024
	ds_read_b128 v[168:171], v172 offset:2048
	ds_read_b128 v[172:175], v172 offset:3072
	v_lshl_add_u64 v[188:189], s[24:25], 0, v[136:137]
	s_add_i32 m0, s37, 0xc000
	ds_read_b128 v[176:179], v147
	ds_read_b128 v[180:183], v147 offset:1024
	ds_read_b128 v[196:199], v147 offset:2048
	ds_read_b128 v[200:203], v147 offset:3072
	ds_read_b128 v[204:207], v147 offset:4096
	ds_read_b128 v[208:211], v147 offset:5120
	ds_read_b128 v[212:215], v147 offset:6144
	ds_read_b128 v[216:219], v147 offset:7168
	global_load_lds_dwordx4 v[188:189], off
	v_lshl_add_u64 v[188:189], s[24:25], 0, v[134:135]
	s_add_i32 m0, s37, 0xe000
	s_nop 0
	global_load_lds_dwordx4 v[188:189], off
	s_waitcnt vmcnt(8)
	s_waitcnt lgkmcnt(0)
	s_setprio 1
	s_barrier
	v_mfma_f32_16x16x32_bf16 v[124:127], v[138:141], v[176:179], v[124:127]
	v_mfma_f32_16x16x32_bf16 v[120:123], v[152:155], v[176:179], v[120:123]
	v_mfma_f32_16x16x32_bf16 v[108:111], v[138:141], v[196:199], v[108:111]
	v_mfma_f32_16x16x32_bf16 v[104:107], v[152:155], v[196:199], v[104:107]
	v_mfma_f32_16x16x32_bf16 v[92:95], v[138:141], v[204:207], v[92:95]
	v_mfma_f32_16x16x32_bf16 v[88:91], v[152:155], v[204:207], v[88:91]
	v_mfma_f32_16x16x32_bf16 v[76:79], v[138:141], v[212:215], v[76:79]
	v_mfma_f32_16x16x32_bf16 v[72:75], v[152:155], v[212:215], v[72:75]
	v_mfma_f32_16x16x32_bf16 v[124:127], v[148:151], v[180:183], v[124:127]
	v_mfma_f32_16x16x32_bf16 v[120:123], v[156:159], v[180:183], v[120:123]
	v_mfma_f32_16x16x32_bf16 v[108:111], v[148:151], v[200:203], v[108:111]
	v_mfma_f32_16x16x32_bf16 v[104:107], v[156:159], v[200:203], v[104:107]
	v_mfma_f32_16x16x32_bf16 v[92:95], v[148:151], v[208:211], v[92:95]
	v_mfma_f32_16x16x32_bf16 v[88:91], v[156:159], v[208:211], v[88:91]
	v_mfma_f32_16x16x32_bf16 v[76:79], v[148:151], v[216:219], v[76:79]
	v_mfma_f32_16x16x32_bf16 v[72:75], v[156:159], v[216:219], v[72:75]
	v_mfma_f32_16x16x32_bf16 v[116:119], v[160:163], v[176:179], v[116:119]
	v_mfma_f32_16x16x32_bf16 v[112:115], v[168:171], v[176:179], v[112:115]
	v_mfma_f32_16x16x32_bf16 v[100:103], v[160:163], v[196:199], v[100:103]
	v_mfma_f32_16x16x32_bf16 v[96:99], v[168:171], v[196:199], v[96:99]
	v_mfma_f32_16x16x32_bf16 v[84:87], v[160:163], v[204:207], v[84:87]
	v_mfma_f32_16x16x32_bf16 v[80:83], v[168:171], v[204:207], v[80:83]
	v_mfma_f32_16x16x32_bf16 v[68:71], v[160:163], v[212:215], v[68:71]
	v_mfma_f32_16x16x32_bf16 v[64:67], v[168:171], v[212:215], v[64:67]
	v_mfma_f32_16x16x32_bf16 v[116:119], v[164:167], v[180:183], v[116:119]
	v_mfma_f32_16x16x32_bf16 v[112:115], v[172:175], v[180:183], v[112:115]
	v_mfma_f32_16x16x32_bf16 v[100:103], v[164:167], v[200:203], v[100:103]
	v_mfma_f32_16x16x32_bf16 v[96:99], v[172:175], v[200:203], v[96:99]
	v_mfma_f32_16x16x32_bf16 v[84:87], v[164:167], v[208:211], v[84:87]
	v_mfma_f32_16x16x32_bf16 v[80:83], v[172:175], v[208:211], v[80:83]
	v_mfma_f32_16x16x32_bf16 v[68:71], v[164:167], v[216:219], v[68:71]
	v_mfma_f32_16x16x32_bf16 v[64:67], v[172:175], v[216:219], v[64:67]
	s_barrier
	s_setprio 0
	s_nop 7
	s_add_i32 s11, s33, s36
	v_lshl_add_u64 v[188:189], s[26:27], 0, v[144:145]
	s_mov_b32 m0, s11
	ds_read_b128 v[176:179], v147 offset:16384
	ds_read_b128 v[180:183], v147 offset:17408
	ds_read_b128 v[196:199], v147 offset:18432
	ds_read_b128 v[200:203], v147 offset:19456
	ds_read_b128 v[204:207], v147 offset:20480
	ds_read_b128 v[208:211], v147 offset:21504
	ds_read_b128 v[212:215], v147 offset:22528
	ds_read_b128 v[216:219], v147 offset:23552
	global_load_lds_dwordx4 v[188:189], off
	s_add_i32 m0, s11, 0x2000
	s_add_u32 s52, s26, 0x100000
	v_lshl_add_u64 v[190:191], s[26:27], 0, v[128:129]
	s_addc_u32 s53, s27, 0
	s_add_i32 s10, s10, s36
	global_load_lds_dwordx4 v[190:191], off
	v_lshl_add_u64 v[220:221], s[52:53], 0, v[144:145]
	s_mov_b32 m0, s10
	v_lshl_add_u64 v[222:223], s[28:29], 0, v[130:131]
	global_load_lds_dwordx4 v[220:221], off
	v_lshl_add_u64 v[220:221], s[52:53], 0, v[128:129]
	s_add_i32 m0, s10, 0x2000
	s_nop 0
	global_load_lds_dwordx4 v[220:221], off
	v_lshl_add_u64 v[220:221], s[28:29], 0, v[132:133]
	s_mov_b32 m0, s37
	s_nop 0
	global_load_lds_dwordx4 v[220:221], off
	s_mov_b32 m0, s38
	s_nop 0
	global_load_lds_dwordx4 v[222:223], off
	s_waitcnt vmcnt(8)
	s_waitcnt lgkmcnt(0)
	s_setprio 1
	s_barrier
	v_mfma_f32_16x16x32_bf16 v[60:63], v[138:141], v[176:179], v[60:63]
	v_mfma_f32_16x16x32_bf16 v[56:59], v[152:155], v[176:179], v[56:59]
	v_mfma_f32_16x16x32_bf16 v[44:47], v[138:141], v[196:199], v[44:47]
	v_mfma_f32_16x16x32_bf16 v[40:43], v[152:155], v[196:199], v[40:43]
	v_mfma_f32_16x16x32_bf16 v[28:31], v[138:141], v[204:207], v[28:31]
	v_mfma_f32_16x16x32_bf16 v[24:27], v[152:155], v[204:207], v[24:27]
	v_mfma_f32_16x16x32_bf16 v[12:15], v[138:141], v[212:215], v[12:15]
	v_mfma_f32_16x16x32_bf16 v[8:11], v[152:155], v[212:215], v[8:11]
	v_mfma_f32_16x16x32_bf16 v[60:63], v[148:151], v[180:183], v[60:63]
	v_mfma_f32_16x16x32_bf16 v[56:59], v[156:159], v[180:183], v[56:59]
	v_mfma_f32_16x16x32_bf16 v[44:47], v[148:151], v[200:203], v[44:47]
	v_mfma_f32_16x16x32_bf16 v[40:43], v[156:159], v[200:203], v[40:43]
	v_mfma_f32_16x16x32_bf16 v[28:31], v[148:151], v[208:211], v[28:31]
	v_mfma_f32_16x16x32_bf16 v[24:27], v[156:159], v[208:211], v[24:27]
	v_mfma_f32_16x16x32_bf16 v[12:15], v[148:151], v[216:219], v[12:15]
	v_mfma_f32_16x16x32_bf16 v[8:11], v[156:159], v[216:219], v[8:11]
	v_mfma_f32_16x16x32_bf16 v[52:55], v[160:163], v[176:179], v[52:55]
	v_mfma_f32_16x16x32_bf16 v[48:51], v[168:171], v[176:179], v[48:51]
	v_mfma_f32_16x16x32_bf16 v[36:39], v[160:163], v[196:199], v[36:39]
	v_mfma_f32_16x16x32_bf16 v[32:35], v[168:171], v[196:199], v[32:35]
	v_mfma_f32_16x16x32_bf16 v[20:23], v[160:163], v[204:207], v[20:23]
	v_mfma_f32_16x16x32_bf16 v[16:19], v[168:171], v[204:207], v[16:19]
	v_mfma_f32_16x16x32_bf16 v[4:7], v[160:163], v[212:215], v[4:7]
	v_mfma_f32_16x16x32_bf16 v[0:3], v[168:171], v[212:215], v[0:3]
	v_mfma_f32_16x16x32_bf16 v[52:55], v[164:167], v[180:183], v[52:55]
	v_mfma_f32_16x16x32_bf16 v[48:51], v[172:175], v[180:183], v[48:51]
	v_mfma_f32_16x16x32_bf16 v[36:39], v[164:167], v[200:203], v[36:39]
	v_mfma_f32_16x16x32_bf16 v[32:35], v[172:175], v[200:203], v[32:35]
	v_mfma_f32_16x16x32_bf16 v[20:23], v[164:167], v[208:211], v[20:23]
	v_mfma_f32_16x16x32_bf16 v[16:19], v[172:175], v[208:211], v[16:19]
	v_mfma_f32_16x16x32_bf16 v[4:7], v[164:167], v[216:219], v[4:7]
	v_mfma_f32_16x16x32_bf16 v[0:3], v[172:175], v[216:219], v[0:3]
	s_barrier
	s_setprio 0
	s_nop 7
	s_add_i32 s10, 0, 0x18000
	s_add_i32 s11, 0, 0x1c000
	v_add_u32_e32 v156, s10, v143
	v_add_u32_e32 v172, s11, v143
	ds_read_b128 v[138:141], v156
	ds_read_b128 v[148:151], v156 offset:1024
	ds_read_b128 v[152:155], v156 offset:2048
	ds_read_b128 v[156:159], v156 offset:3072
	ds_read_b128 v[160:163], v172
	ds_read_b128 v[164:167], v172 offset:1024
	ds_read_b128 v[168:171], v172 offset:2048
	ds_read_b128 v[172:175], v172 offset:3072
	s_add_u32 s28, s28, 0x100000
	s_addc_u32 s29, s29, 0
	s_mov_b32 m0, s39
	v_lshl_add_u64 v[224:225], s[28:29], 0, v[132:133]
	ds_read_b128 v[176:179], v147 offset:32768
	ds_read_b128 v[180:183], v147 offset:33792
	ds_read_b128 v[196:199], v147 offset:34816
	ds_read_b128 v[200:203], v147 offset:35840
	ds_read_b128 v[204:207], v147 offset:36864
	ds_read_b128 v[208:211], v147 offset:37888
	ds_read_b128 v[212:215], v147 offset:38912
	ds_read_b128 v[216:219], v147 offset:39936
	global_load_lds_dwordx4 v[224:225], off
	v_lshl_add_u64 v[224:225], s[28:29], 0, v[130:131]
	s_mov_b32 m0, s40
	s_nop 0
	global_load_lds_dwordx4 v[224:225], off
	s_waitcnt vmcnt(8)
	s_waitcnt lgkmcnt(0)
	s_setprio 1
	s_barrier
	v_mfma_f32_16x16x32_bf16 v[124:127], v[138:141], v[176:179], v[124:127]
	v_mfma_f32_16x16x32_bf16 v[120:123], v[152:155], v[176:179], v[120:123]
	v_mfma_f32_16x16x32_bf16 v[108:111], v[138:141], v[196:199], v[108:111]
	v_mfma_f32_16x16x32_bf16 v[104:107], v[152:155], v[196:199], v[104:107]
	v_mfma_f32_16x16x32_bf16 v[92:95], v[138:141], v[204:207], v[92:95]
	v_mfma_f32_16x16x32_bf16 v[88:91], v[152:155], v[204:207], v[88:91]
	v_mfma_f32_16x16x32_bf16 v[76:79], v[138:141], v[212:215], v[76:79]
	v_mfma_f32_16x16x32_bf16 v[72:75], v[152:155], v[212:215], v[72:75]
	v_mfma_f32_16x16x32_bf16 v[124:127], v[148:151], v[180:183], v[124:127]
	v_mfma_f32_16x16x32_bf16 v[120:123], v[156:159], v[180:183], v[120:123]
	v_mfma_f32_16x16x32_bf16 v[108:111], v[148:151], v[200:203], v[108:111]
	v_mfma_f32_16x16x32_bf16 v[104:107], v[156:159], v[200:203], v[104:107]
	v_mfma_f32_16x16x32_bf16 v[92:95], v[148:151], v[208:211], v[92:95]
	v_mfma_f32_16x16x32_bf16 v[88:91], v[156:159], v[208:211], v[88:91]
	v_mfma_f32_16x16x32_bf16 v[76:79], v[148:151], v[216:219], v[76:79]
	v_mfma_f32_16x16x32_bf16 v[72:75], v[156:159], v[216:219], v[72:75]
	v_mfma_f32_16x16x32_bf16 v[116:119], v[160:163], v[176:179], v[116:119]
	v_mfma_f32_16x16x32_bf16 v[112:115], v[168:171], v[176:179], v[112:115]
	v_mfma_f32_16x16x32_bf16 v[100:103], v[160:163], v[196:199], v[100:103]
	v_mfma_f32_16x16x32_bf16 v[96:99], v[168:171], v[196:199], v[96:99]
	v_mfma_f32_16x16x32_bf16 v[84:87], v[160:163], v[204:207], v[84:87]
	v_mfma_f32_16x16x32_bf16 v[80:83], v[168:171], v[204:207], v[80:83]
	v_mfma_f32_16x16x32_bf16 v[68:71], v[160:163], v[212:215], v[68:71]
	v_mfma_f32_16x16x32_bf16 v[64:67], v[168:171], v[212:215], v[64:67]
	v_mfma_f32_16x16x32_bf16 v[116:119], v[164:167], v[180:183], v[116:119]
	v_mfma_f32_16x16x32_bf16 v[112:115], v[172:175], v[180:183], v[112:115]
	v_mfma_f32_16x16x32_bf16 v[100:103], v[164:167], v[200:203], v[100:103]
	v_mfma_f32_16x16x32_bf16 v[96:99], v[172:175], v[200:203], v[96:99]
	v_mfma_f32_16x16x32_bf16 v[84:87], v[164:167], v[208:211], v[84:87]
	v_mfma_f32_16x16x32_bf16 v[80:83], v[172:175], v[208:211], v[80:83]
	v_mfma_f32_16x16x32_bf16 v[68:71], v[164:167], v[216:219], v[68:71]
	v_mfma_f32_16x16x32_bf16 v[64:67], v[172:175], v[216:219], v[64:67]
	s_barrier
	s_setprio 0
	s_nop 7
	s_add_i32 s10, s10, s36
	v_lshl_add_u64 v[188:189], v[188:189], 0, s[88:89]
	s_mov_b32 m0, s10
	ds_read_b128 v[176:179], v147 offset:49152
	ds_read_b128 v[180:183], v147 offset:50176
	ds_read_b128 v[196:199], v147 offset:51200
	ds_read_b128 v[200:203], v147 offset:52224
	ds_read_b128 v[204:207], v147 offset:53248
	ds_read_b128 v[208:211], v147 offset:54272
	ds_read_b128 v[212:215], v147 offset:55296
	ds_read_b128 v[216:219], v147 offset:56320
	global_load_lds_dwordx4 v[188:189], off
	s_add_i32 m0, s10, 0x2000
	s_add_u32 s26, s26, 0x100080
	v_lshl_add_u64 v[188:189], v[190:191], 0, s[88:89]
	s_addc_u32 s27, s27, 0
	s_add_i32 s10, s11, s36
	global_load_lds_dwordx4 v[188:189], off
	v_lshl_add_u64 v[188:189], s[26:27], 0, v[144:145]
	s_mov_b32 m0, s10
	s_nop 0
	global_load_lds_dwordx4 v[188:189], off
	v_lshl_add_u64 v[188:189], s[26:27], 0, v[128:129]
	s_add_i32 m0, s10, 0x2000
	s_nop 0
	global_load_lds_dwordx4 v[188:189], off
	v_lshl_add_u64 v[188:189], v[220:221], 0, s[88:89]
	s_mov_b32 m0, s41
	s_nop 0
	global_load_lds_dwordx4 v[188:189], off
	v_lshl_add_u64 v[188:189], v[222:223], 0, s[88:89]
	s_mov_b32 m0, s42
	s_nop 0
	global_load_lds_dwordx4 v[188:189], off
	s_waitcnt vmcnt(8)
	s_waitcnt lgkmcnt(0)
	s_setprio 1
	s_barrier
	v_mfma_f32_16x16x32_bf16 v[60:63], v[138:141], v[176:179], v[60:63]
	v_mfma_f32_16x16x32_bf16 v[56:59], v[152:155], v[176:179], v[56:59]
	v_mfma_f32_16x16x32_bf16 v[44:47], v[138:141], v[196:199], v[44:47]
	v_mfma_f32_16x16x32_bf16 v[40:43], v[152:155], v[196:199], v[40:43]
	v_mfma_f32_16x16x32_bf16 v[28:31], v[138:141], v[204:207], v[28:31]
	v_mfma_f32_16x16x32_bf16 v[24:27], v[152:155], v[204:207], v[24:27]
	v_mfma_f32_16x16x32_bf16 v[12:15], v[138:141], v[212:215], v[12:15]
	v_mfma_f32_16x16x32_bf16 v[8:11], v[152:155], v[212:215], v[8:11]
	v_mfma_f32_16x16x32_bf16 v[60:63], v[148:151], v[180:183], v[60:63]
	v_mfma_f32_16x16x32_bf16 v[56:59], v[156:159], v[180:183], v[56:59]
	v_mfma_f32_16x16x32_bf16 v[44:47], v[148:151], v[200:203], v[44:47]
	v_mfma_f32_16x16x32_bf16 v[40:43], v[156:159], v[200:203], v[40:43]
	v_mfma_f32_16x16x32_bf16 v[28:31], v[148:151], v[208:211], v[28:31]
	v_mfma_f32_16x16x32_bf16 v[24:27], v[156:159], v[208:211], v[24:27]
	v_mfma_f32_16x16x32_bf16 v[12:15], v[148:151], v[216:219], v[12:15]
	v_mfma_f32_16x16x32_bf16 v[8:11], v[156:159], v[216:219], v[8:11]
	v_mfma_f32_16x16x32_bf16 v[52:55], v[160:163], v[176:179], v[52:55]
	v_mfma_f32_16x16x32_bf16 v[48:51], v[168:171], v[176:179], v[48:51]
	v_mfma_f32_16x16x32_bf16 v[36:39], v[160:163], v[196:199], v[36:39]
	v_mfma_f32_16x16x32_bf16 v[32:35], v[168:171], v[196:199], v[32:35]
	v_mfma_f32_16x16x32_bf16 v[20:23], v[160:163], v[204:207], v[20:23]
	v_mfma_f32_16x16x32_bf16 v[16:19], v[168:171], v[204:207], v[16:19]
	v_mfma_f32_16x16x32_bf16 v[4:7], v[160:163], v[212:215], v[4:7]
	v_mfma_f32_16x16x32_bf16 v[0:3], v[168:171], v[212:215], v[0:3]
	v_mfma_f32_16x16x32_bf16 v[52:55], v[164:167], v[180:183], v[52:55]
	v_mfma_f32_16x16x32_bf16 v[48:51], v[172:175], v[180:183], v[48:51]
	v_mfma_f32_16x16x32_bf16 v[36:39], v[164:167], v[200:203], v[36:39]
	v_mfma_f32_16x16x32_bf16 v[32:35], v[172:175], v[200:203], v[32:35]
	v_mfma_f32_16x16x32_bf16 v[20:23], v[164:167], v[208:211], v[20:23]
	v_mfma_f32_16x16x32_bf16 v[16:19], v[172:175], v[208:211], v[16:19]
	v_mfma_f32_16x16x32_bf16 v[4:7], v[164:167], v[216:219], v[4:7]
	v_mfma_f32_16x16x32_bf16 v[0:3], v[172:175], v[216:219], v[0:3]
	s_barrier
	s_setprio 0
	s_nop 7
	s_add_i32 s50, s50, 2
	s_add_u32 s48, s48, 0x100
	s_addc_u32 s49, s49, 0
	s_add_u32 s24, s24, 0x100
	s_addc_u32 s25, s25, 0
	s_cmp_gt_u32 s50, 61
	s_cbranch_scc0 .LBB0_1758
	s_and_b64 vcc, exec, s[14:15]
	s_cbranch_vccz .LBB0_1761
	s_barrier

.LBB0_1771:
	s_add_u32 s10, s27, s8
	s_addc_u32 s11, s28, s9
	s_add_u32 s10, s10, 0x29000100
	s_addc_u32 s11, s11, 0
	s_add_u32 s12, s25, s8
	s_addc_u32 s13, s26, s9
	s_add_i32 s30, 0, 0x10000
	s_cmpk_eq_i32 s8, 0x1f00
	s_cselect_b32 s15, s7, s11
	s_cselect_b32 s14, s6, s10
	s_cselect_b32 s13, s3, s13
	s_cselect_b32 s12, s2, s12
	s_add_i32 s10, 0, 0x14000
	v_add_u32_e32 v90, s30, v76
	v_add_u32_e32 v106, s10, v76
	ds_read_b128 v[78:81], v90
	ds_read_b128 v[82:85], v90 offset:1024
	ds_read_b128 v[86:89], v90 offset:2048
	ds_read_b128 v[90:93], v90 offset:3072
	ds_read_b128 v[94:97], v106
	ds_read_b128 v[98:101], v106 offset:1024
	ds_read_b128 v[102:105], v106 offset:2048
	ds_read_b128 v[106:109], v106 offset:3072
	v_lshl_add_u64 v[142:143], v[72:73], 0, s[8:9]
	s_add_i32 m0, s18, 0xc000
	ds_read_b128 v[110:113], v77
	ds_read_b128 v[114:117], v77 offset:1024
	ds_read_b128 v[118:121], v77 offset:2048
	ds_read_b128 v[122:125], v77 offset:3072
	ds_read_b128 v[126:129], v77 offset:4096
	ds_read_b128 v[130:133], v77 offset:5120
	ds_read_b128 v[134:137], v77 offset:6144
	ds_read_b128 v[138:141], v77 offset:7168
	global_load_lds_dwordx4 v[142:143], off
	v_lshl_add_u64 v[142:143], v[70:71], 0, s[8:9]
	s_add_i32 m0, s18, 0xe000
	s_nop 0
	global_load_lds_dwordx4 v[142:143], off
	s_waitcnt vmcnt(8)
	s_waitcnt lgkmcnt(0)
	s_setprio 1
	s_barrier
	v_mfma_f32_16x16x32_bf16 v[60:63], v[78:81], v[110:113], v[60:63]
	v_mfma_f32_16x16x32_bf16 v[56:59], v[86:89], v[110:113], v[56:59]
	v_mfma_f32_16x16x32_bf16 v[44:47], v[78:81], v[118:121], v[44:47]
	v_mfma_f32_16x16x32_bf16 v[40:43], v[86:89], v[118:121], v[40:43]
	v_mfma_f32_16x16x32_bf16 v[28:31], v[78:81], v[126:129], v[28:31]
	v_mfma_f32_16x16x32_bf16 v[24:27], v[86:89], v[126:129], v[24:27]
	v_mfma_f32_16x16x32_bf16 v[12:15], v[78:81], v[134:137], v[12:15]
	v_mfma_f32_16x16x32_bf16 v[8:11], v[86:89], v[134:137], v[8:11]
	v_mfma_f32_16x16x32_bf16 v[60:63], v[82:85], v[114:117], v[60:63]
	v_mfma_f32_16x16x32_bf16 v[56:59], v[90:93], v[114:117], v[56:59]
	v_mfma_f32_16x16x32_bf16 v[44:47], v[82:85], v[122:125], v[44:47]
	v_mfma_f32_16x16x32_bf16 v[40:43], v[90:93], v[122:125], v[40:43]
	v_mfma_f32_16x16x32_bf16 v[28:31], v[82:85], v[130:133], v[28:31]
	v_mfma_f32_16x16x32_bf16 v[24:27], v[90:93], v[130:133], v[24:27]
	v_mfma_f32_16x16x32_bf16 v[12:15], v[82:85], v[138:141], v[12:15]
	v_mfma_f32_16x16x32_bf16 v[8:11], v[90:93], v[138:141], v[8:11]
	v_mfma_f32_16x16x32_bf16 v[52:55], v[94:97], v[110:113], v[52:55]
	v_mfma_f32_16x16x32_bf16 v[48:51], v[102:105], v[110:113], v[48:51]
	v_mfma_f32_16x16x32_bf16 v[36:39], v[94:97], v[118:121], v[36:39]
	v_mfma_f32_16x16x32_bf16 v[32:35], v[102:105], v[118:121], v[32:35]
	v_mfma_f32_16x16x32_bf16 v[20:23], v[94:97], v[126:129], v[20:23]
	v_mfma_f32_16x16x32_bf16 v[16:19], v[102:105], v[126:129], v[16:19]
	v_mfma_f32_16x16x32_bf16 v[4:7], v[94:97], v[134:137], v[4:7]
	v_mfma_f32_16x16x32_bf16 v[0:3], v[102:105], v[134:137], v[0:3]
	v_mfma_f32_16x16x32_bf16 v[52:55], v[98:101], v[114:117], v[52:55]
	v_mfma_f32_16x16x32_bf16 v[48:51], v[106:109], v[114:117], v[48:51]
	v_mfma_f32_16x16x32_bf16 v[36:39], v[98:101], v[122:125], v[36:39]
	v_mfma_f32_16x16x32_bf16 v[32:35], v[106:109], v[122:125], v[32:35]
	v_mfma_f32_16x16x32_bf16 v[20:23], v[98:101], v[130:133], v[20:23]
	v_mfma_f32_16x16x32_bf16 v[16:19], v[106:109], v[130:133], v[16:19]
	v_mfma_f32_16x16x32_bf16 v[4:7], v[98:101], v[138:141], v[4:7]
	v_mfma_f32_16x16x32_bf16 v[0:3], v[106:109], v[138:141], v[0:3]
	s_barrier
	s_setprio 0
	s_nop 7
	s_add_i32 s11, s30, s17
	v_lshl_add_u64 v[142:143], s[12:13], 0, v[144:145]
	s_mov_b32 m0, s11
	v_lshl_add_u64 v[146:147], s[12:13], 0, v[64:65]
	global_load_lds_dwordx4 v[142:143], off
	s_add_i32 m0, s11, 0x2000
	s_add_u32 s30, s12, 0x100000
	s_addc_u32 s31, s13, 0
	s_add_i32 s10, s10, s17
	global_load_lds_dwordx4 v[146:147], off
	v_lshl_add_u64 v[78:79], s[30:31], 0, v[144:145]
	s_mov_b32 m0, s10
	v_lshl_add_u64 v[148:149], s[14:15], 0, v[68:69]
	global_load_lds_dwordx4 v[78:79], off
	v_lshl_add_u64 v[78:79], s[30:31], 0, v[64:65]
	s_add_i32 m0, s10, 0x2000
	v_lshl_add_u64 v[150:151], s[14:15], 0, v[66:67]
	global_load_lds_dwordx4 v[78:79], off
	s_mov_b32 m0, s18
	s_nop 0
	global_load_lds_dwordx4 v[148:149], off
	s_mov_b32 m0, s19
	s_nop 0
	global_load_lds_dwordx4 v[150:151], off
	s_waitcnt vmcnt(8)
	s_waitcnt lgkmcnt(0)
	s_barrier
	s_barrier
	s_add_i32 s10, 0, 0x18000
	s_add_i32 s11, 0, 0x1c000
	v_add_u32_e32 v90, s10, v76
	v_add_u32_e32 v106, s11, v76
	ds_read_b128 v[78:81], v90
	ds_read_b128 v[82:85], v90 offset:1024
	ds_read_b128 v[86:89], v90 offset:2048
	ds_read_b128 v[90:93], v90 offset:3072
	ds_read_b128 v[94:97], v106
	ds_read_b128 v[98:101], v106 offset:1024
	ds_read_b128 v[102:105], v106 offset:2048
	ds_read_b128 v[106:109], v106 offset:3072
	s_mov_b32 m0, s20
	ds_read_b128 v[110:113], v77 offset:32768
	ds_read_b128 v[114:117], v77 offset:33792
	ds_read_b128 v[118:121], v77 offset:34816
	ds_read_b128 v[122:125], v77 offset:35840
	ds_read_b128 v[126:129], v77 offset:36864
	ds_read_b128 v[130:133], v77 offset:37888
	ds_read_b128 v[134:137], v77 offset:38912
	ds_read_b128 v[138:141], v77 offset:39936
	global_load_lds_dwordx4 v[148:149], off
	s_mov_b32 m0, s21
	s_nop 0
	global_load_lds_dwordx4 v[150:151], off
	s_waitcnt vmcnt(8)
	s_waitcnt lgkmcnt(0)
	s_setprio 1
	s_barrier
	v_mfma_f32_16x16x32_bf16 v[60:63], v[78:81], v[110:113], v[60:63]
	v_mfma_f32_16x16x32_bf16 v[56:59], v[86:89], v[110:113], v[56:59]
	v_mfma_f32_16x16x32_bf16 v[44:47], v[78:81], v[118:121], v[44:47]
	v_mfma_f32_16x16x32_bf16 v[40:43], v[86:89], v[118:121], v[40:43]
	v_mfma_f32_16x16x32_bf16 v[28:31], v[78:81], v[126:129], v[28:31]
	v_mfma_f32_16x16x32_bf16 v[24:27], v[86:89], v[126:129], v[24:27]
	v_mfma_f32_16x16x32_bf16 v[12:15], v[78:81], v[134:137], v[12:15]
	v_mfma_f32_16x16x32_bf16 v[8:11], v[86:89], v[134:137], v[8:11]
	v_mfma_f32_16x16x32_bf16 v[60:63], v[82:85], v[114:117], v[60:63]
	v_mfma_f32_16x16x32_bf16 v[56:59], v[90:93], v[114:117], v[56:59]
	v_mfma_f32_16x16x32_bf16 v[44:47], v[82:85], v[122:125], v[44:47]
	v_mfma_f32_16x16x32_bf16 v[40:43], v[90:93], v[122:125], v[40:43]
	v_mfma_f32_16x16x32_bf16 v[28:31], v[82:85], v[130:133], v[28:31]
	v_mfma_f32_16x16x32_bf16 v[24:27], v[90:93], v[130:133], v[24:27]
	v_mfma_f32_16x16x32_bf16 v[12:15], v[82:85], v[138:141], v[12:15]
	v_mfma_f32_16x16x32_bf16 v[8:11], v[90:93], v[138:141], v[8:11]
	v_mfma_f32_16x16x32_bf16 v[52:55], v[94:97], v[110:113], v[52:55]
	v_mfma_f32_16x16x32_bf16 v[48:51], v[102:105], v[110:113], v[48:51]
	v_mfma_f32_16x16x32_bf16 v[36:39], v[94:97], v[118:121], v[36:39]
	v_mfma_f32_16x16x32_bf16 v[32:35], v[102:105], v[118:121], v[32:35]
	v_mfma_f32_16x16x32_bf16 v[20:23], v[94:97], v[126:129], v[20:23]
	v_mfma_f32_16x16x32_bf16 v[16:19], v[102:105], v[126:129], v[16:19]
	v_mfma_f32_16x16x32_bf16 v[4:7], v[94:97], v[134:137], v[4:7]
	v_mfma_f32_16x16x32_bf16 v[0:3], v[102:105], v[134:137], v[0:3]
	v_mfma_f32_16x16x32_bf16 v[52:55], v[98:101], v[114:117], v[52:55]
	v_mfma_f32_16x16x32_bf16 v[48:51], v[106:109], v[114:117], v[48:51]
	v_mfma_f32_16x16x32_bf16 v[36:39], v[98:101], v[122:125], v[36:39]
	v_mfma_f32_16x16x32_bf16 v[32:35], v[106:109], v[122:125], v[32:35]
	v_mfma_f32_16x16x32_bf16 v[20:23], v[98:101], v[130:133], v[20:23]
	v_mfma_f32_16x16x32_bf16 v[16:19], v[106:109], v[130:133], v[16:19]
	v_mfma_f32_16x16x32_bf16 v[4:7], v[98:101], v[138:141], v[4:7]
	v_mfma_f32_16x16x32_bf16 v[0:3], v[106:109], v[138:141], v[0:3]
	s_barrier
	s_setprio 0
	s_nop 7
	s_add_i32 s10, s10, s17
	v_lshl_add_u64 v[78:79], v[142:143], 0, s[88:89]
	s_mov_b32 m0, s10
	s_nop 0
	global_load_lds_dwordx4 v[78:79], off
	s_add_i32 m0, s10, 0x2000
	s_add_u32 s12, s12, 0x100080
	v_lshl_add_u64 v[78:79], v[146:147], 0, s[88:89]
	s_addc_u32 s13, s13, 0
	s_add_i32 s10, s11, s17
	global_load_lds_dwordx4 v[78:79], off
	v_lshl_add_u64 v[78:79], s[12:13], 0, v[144:145]
	s_mov_b32 m0, s10
	s_nop 0
	global_load_lds_dwordx4 v[78:79], off
	v_lshl_add_u64 v[78:79], s[12:13], 0, v[64:65]
	s_add_i32 m0, s10, 0x2000
	s_nop 0
	global_load_lds_dwordx4 v[78:79], off
	v_lshl_add_u64 v[78:79], v[148:149], 0, s[88:89]
	s_mov_b32 m0, s23
	s_nop 0
	global_load_lds_dwordx4 v[78:79], off
	v_lshl_add_u64 v[78:79], v[150:151], 0, s[88:89]
	s_mov_b32 m0, s24
	s_nop 0
	global_load_lds_dwordx4 v[78:79], off
	s_waitcnt vmcnt(8)
	s_waitcnt lgkmcnt(0)
	s_barrier
	s_barrier
	s_add_i32 s29, s29, 2
	s_add_u32 s8, s8, 0x100
	s_addc_u32 s9, s9, 0
	s_cmp_gt_u32 s29, 61
	s_cbranch_scc0 .LBB0_1771
	s_cmpk_lt_u32 s16, 0x100
	s_cbranch_scc0 .LBB0_1774
	s_barrier

.LBB0_1790:
	s_add_u32 s10, s20, 0xfff00080
	s_addc_u32 s11, s21, -1
	s_add_i32 s33, 0, 0x10000
	s_cmp_eq_u32 s47, 60
	s_cselect_b32 s25, s15, s11
	s_cselect_b32 s24, s43, s10
	v_add_u32_e32 v139, s33, v141
	s_cselect_b32 s23, s13, s46
	s_cselect_b32 s22, s44, s45
	s_add_i32 s10, 0, 0x14000
	ds_read_b128 v[146:149], v139
	ds_read_b128 v[150:153], v139 offset:1024
	ds_read_b128 v[154:157], v139 offset:2048
	ds_read_b128 v[158:161], v139 offset:3072
	v_add_u32_e32 v139, s10, v141
	ds_read_b128 v[162:165], v139
	ds_read_b128 v[166:169], v139 offset:1024
	ds_read_b128 v[170:173], v139 offset:2048
	ds_read_b128 v[174:177], v139 offset:3072
	v_lshl_add_u64 v[182:183], s[20:21], 0, v[136:137]
	s_add_i32 m0, s31, 0xc000
	ds_read_b128 v[178:181], v143
	ds_read_b128 v[196:199], v143 offset:1024
	ds_read_b128 v[200:203], v143 offset:2048
	ds_read_b128 v[204:207], v143 offset:3072
	ds_read_b128 v[208:211], v143 offset:4096
	ds_read_b128 v[212:215], v143 offset:5120
	ds_read_b128 v[216:219], v143 offset:6144
	ds_read_b128 v[220:223], v143 offset:7168
	global_load_lds_dwordx4 v[182:183], off
	v_lshl_add_u64 v[182:183], s[20:21], 0, v[134:135]
	s_add_i32 m0, s31, 0xe000
	s_nop 0
	global_load_lds_dwordx4 v[182:183], off
	s_waitcnt vmcnt(8)
	s_waitcnt lgkmcnt(0)
	s_setprio 1
	s_barrier
	v_mfma_f32_16x16x32_bf16 v[124:127], v[146:149], v[178:181], v[124:127]
	v_mfma_f32_16x16x32_bf16 v[120:123], v[154:157], v[178:181], v[120:123]
	v_mfma_f32_16x16x32_bf16 v[116:119], v[146:149], v[200:203], v[116:119]
	v_mfma_f32_16x16x32_bf16 v[108:111], v[154:157], v[200:203], v[108:111]
	v_mfma_f32_16x16x32_bf16 v[100:103], v[146:149], v[208:211], v[100:103]
	v_mfma_f32_16x16x32_bf16 v[92:95], v[154:157], v[208:211], v[92:95]
	v_mfma_f32_16x16x32_bf16 v[84:87], v[146:149], v[216:219], v[84:87]
	v_mfma_f32_16x16x32_bf16 v[76:79], v[154:157], v[216:219], v[76:79]
	v_mfma_f32_16x16x32_bf16 v[124:127], v[150:153], v[196:199], v[124:127]
	v_mfma_f32_16x16x32_bf16 v[120:123], v[158:161], v[196:199], v[120:123]
	v_mfma_f32_16x16x32_bf16 v[116:119], v[150:153], v[204:207], v[116:119]
	v_mfma_f32_16x16x32_bf16 v[108:111], v[158:161], v[204:207], v[108:111]
	v_mfma_f32_16x16x32_bf16 v[100:103], v[150:153], v[212:215], v[100:103]
	v_mfma_f32_16x16x32_bf16 v[92:95], v[158:161], v[212:215], v[92:95]
	v_mfma_f32_16x16x32_bf16 v[84:87], v[150:153], v[220:223], v[84:87]
	v_mfma_f32_16x16x32_bf16 v[76:79], v[158:161], v[220:223], v[76:79]
	v_mfma_f32_16x16x32_bf16 v[112:115], v[162:165], v[178:181], v[112:115]
	v_mfma_f32_16x16x32_bf16 v[104:107], v[170:173], v[178:181], v[104:107]
	v_mfma_f32_16x16x32_bf16 v[96:99], v[162:165], v[200:203], v[96:99]
	v_mfma_f32_16x16x32_bf16 v[88:91], v[170:173], v[200:203], v[88:91]
	v_mfma_f32_16x16x32_bf16 v[80:83], v[162:165], v[208:211], v[80:83]
	v_mfma_f32_16x16x32_bf16 v[72:75], v[170:173], v[208:211], v[72:75]
	v_mfma_f32_16x16x32_bf16 v[68:71], v[162:165], v[216:219], v[68:71]
	v_mfma_f32_16x16x32_bf16 v[64:67], v[170:173], v[216:219], v[64:67]
	v_mfma_f32_16x16x32_bf16 v[112:115], v[166:169], v[196:199], v[112:115]
	v_mfma_f32_16x16x32_bf16 v[104:107], v[174:177], v[196:199], v[104:107]
	v_mfma_f32_16x16x32_bf16 v[96:99], v[166:169], v[204:207], v[96:99]
	v_mfma_f32_16x16x32_bf16 v[88:91], v[174:177], v[204:207], v[88:91]
	v_mfma_f32_16x16x32_bf16 v[80:83], v[166:169], v[212:215], v[80:83]
	v_mfma_f32_16x16x32_bf16 v[72:75], v[174:177], v[212:215], v[72:75]
	v_mfma_f32_16x16x32_bf16 v[68:71], v[166:169], v[220:223], v[68:71]
	v_mfma_f32_16x16x32_bf16 v[64:67], v[174:177], v[220:223], v[64:67]
	s_barrier
	s_setprio 0
	s_nop 7
	s_add_i32 s11, s33, s30
	v_lshl_add_u64 v[182:183], s[22:23], 0, v[144:145]
	s_mov_b32 m0, s11
	ds_read_b128 v[178:181], v143 offset:16384
	ds_read_b128 v[196:199], v143 offset:17408
	ds_read_b128 v[200:203], v143 offset:18432
	ds_read_b128 v[204:207], v143 offset:19456
	ds_read_b128 v[208:211], v143 offset:20480
	ds_read_b128 v[212:215], v143 offset:21504
	ds_read_b128 v[216:219], v143 offset:22528
	ds_read_b128 v[220:223], v143 offset:23552
	global_load_lds_dwordx4 v[182:183], off
	s_add_i32 m0, s11, 0x2000
	s_add_u32 s48, s22, 0x100000
	v_lshl_add_u64 v[188:189], s[22:23], 0, v[128:129]
	s_addc_u32 s49, s23, 0
	s_add_i32 s10, s10, s30
	global_load_lds_dwordx4 v[188:189], off
	v_lshl_add_u64 v[190:191], s[48:49], 0, v[144:145]
	s_mov_b32 m0, s10
	v_lshl_add_u64 v[224:225], s[24:25], 0, v[130:131]
	global_load_lds_dwordx4 v[190:191], off
	v_lshl_add_u64 v[190:191], s[48:49], 0, v[128:129]
	s_add_i32 m0, s10, 0x2000
	s_nop 0
	global_load_lds_dwordx4 v[190:191], off
	v_lshl_add_u64 v[190:191], s[24:25], 0, v[132:133]
	s_mov_b32 m0, s31
	s_nop 0
	global_load_lds_dwordx4 v[190:191], off
	s_mov_b32 m0, s34
	s_nop 0
	global_load_lds_dwordx4 v[224:225], off
	s_waitcnt vmcnt(8)
	s_waitcnt lgkmcnt(0)
	s_setprio 1
	s_barrier
	v_mfma_f32_16x16x32_bf16 v[60:63], v[146:149], v[178:181], v[60:63]
	v_mfma_f32_16x16x32_bf16 v[56:59], v[154:157], v[178:181], v[56:59]
	v_mfma_f32_16x16x32_bf16 v[52:55], v[146:149], v[200:203], v[52:55]
	v_mfma_f32_16x16x32_bf16 v[44:47], v[154:157], v[200:203], v[44:47]
	v_mfma_f32_16x16x32_bf16 v[36:39], v[146:149], v[208:211], v[36:39]
	v_mfma_f32_16x16x32_bf16 v[28:31], v[154:157], v[208:211], v[28:31]
	v_mfma_f32_16x16x32_bf16 v[20:23], v[146:149], v[216:219], v[20:23]
	v_mfma_f32_16x16x32_bf16 v[12:15], v[154:157], v[216:219], v[12:15]
	v_mfma_f32_16x16x32_bf16 v[60:63], v[150:153], v[196:199], v[60:63]
	v_mfma_f32_16x16x32_bf16 v[56:59], v[158:161], v[196:199], v[56:59]
	v_mfma_f32_16x16x32_bf16 v[52:55], v[150:153], v[204:207], v[52:55]
	v_mfma_f32_16x16x32_bf16 v[44:47], v[158:161], v[204:207], v[44:47]
	v_mfma_f32_16x16x32_bf16 v[36:39], v[150:153], v[212:215], v[36:39]
	v_mfma_f32_16x16x32_bf16 v[28:31], v[158:161], v[212:215], v[28:31]
	v_mfma_f32_16x16x32_bf16 v[20:23], v[150:153], v[220:223], v[20:23]
	v_mfma_f32_16x16x32_bf16 v[12:15], v[158:161], v[220:223], v[12:15]
	v_mfma_f32_16x16x32_bf16 v[48:51], v[162:165], v[178:181], v[48:51]
	v_mfma_f32_16x16x32_bf16 v[40:43], v[170:173], v[178:181], v[40:43]
	v_mfma_f32_16x16x32_bf16 v[32:35], v[162:165], v[200:203], v[32:35]
	v_mfma_f32_16x16x32_bf16 v[24:27], v[170:173], v[200:203], v[24:27]
	v_mfma_f32_16x16x32_bf16 v[16:19], v[162:165], v[208:211], v[16:19]
	v_mfma_f32_16x16x32_bf16 v[8:11], v[170:173], v[208:211], v[8:11]
	v_mfma_f32_16x16x32_bf16 v[4:7], v[162:165], v[216:219], v[4:7]
	v_mfma_f32_16x16x32_bf16 v[0:3], v[170:173], v[216:219], v[0:3]
	v_mfma_f32_16x16x32_bf16 v[48:51], v[166:169], v[196:199], v[48:51]
	v_mfma_f32_16x16x32_bf16 v[40:43], v[174:177], v[196:199], v[40:43]
	v_mfma_f32_16x16x32_bf16 v[32:35], v[166:169], v[204:207], v[32:35]
	v_mfma_f32_16x16x32_bf16 v[24:27], v[174:177], v[204:207], v[24:27]
	v_mfma_f32_16x16x32_bf16 v[16:19], v[166:169], v[212:215], v[16:19]
	v_mfma_f32_16x16x32_bf16 v[8:11], v[174:177], v[212:215], v[8:11]
	v_mfma_f32_16x16x32_bf16 v[4:7], v[166:169], v[220:223], v[4:7]
	v_mfma_f32_16x16x32_bf16 v[0:3], v[174:177], v[220:223], v[0:3]
	s_barrier
	s_setprio 0
	s_nop 7
	s_add_i32 s10, 0, 0x18000
	v_add_u32_e32 v139, s10, v141
	s_add_i32 s11, 0, 0x1c000
	ds_read_b128 v[146:149], v139
	ds_read_b128 v[150:153], v139 offset:1024
	ds_read_b128 v[154:157], v139 offset:2048
	ds_read_b128 v[158:161], v139 offset:3072
	v_add_u32_e32 v139, s11, v141
	ds_read_b128 v[162:165], v139
	ds_read_b128 v[166:169], v139 offset:1024
	ds_read_b128 v[170:173], v139 offset:2048
	ds_read_b128 v[174:177], v139 offset:3072
	s_add_u32 s24, s24, 0x100000
	s_addc_u32 s25, s25, 0
	s_mov_b32 m0, s35
	v_lshl_add_u64 v[232:233], s[24:25], 0, v[132:133]
	ds_read_b128 v[178:181], v143 offset:32768
	ds_read_b128 v[196:199], v143 offset:33792
	ds_read_b128 v[200:203], v143 offset:34816
	ds_read_b128 v[204:207], v143 offset:35840
	ds_read_b128 v[208:211], v143 offset:36864
	ds_read_b128 v[212:215], v143 offset:37888
	ds_read_b128 v[216:219], v143 offset:38912
	ds_read_b128 v[220:223], v143 offset:39936
	global_load_lds_dwordx4 v[232:233], off
	v_lshl_add_u64 v[232:233], s[24:25], 0, v[130:131]
	s_mov_b32 m0, s36
	s_nop 0
	global_load_lds_dwordx4 v[232:233], off
	s_waitcnt vmcnt(8)
	s_waitcnt lgkmcnt(0)
	s_setprio 1
	s_barrier
	v_mfma_f32_16x16x32_bf16 v[124:127], v[146:149], v[178:181], v[124:127]
	v_mfma_f32_16x16x32_bf16 v[120:123], v[154:157], v[178:181], v[120:123]
	v_mfma_f32_16x16x32_bf16 v[116:119], v[146:149], v[200:203], v[116:119]
	v_mfma_f32_16x16x32_bf16 v[108:111], v[154:157], v[200:203], v[108:111]
	v_mfma_f32_16x16x32_bf16 v[100:103], v[146:149], v[208:211], v[100:103]
	v_mfma_f32_16x16x32_bf16 v[92:95], v[154:157], v[208:211], v[92:95]
	v_mfma_f32_16x16x32_bf16 v[84:87], v[146:149], v[216:219], v[84:87]
	v_mfma_f32_16x16x32_bf16 v[76:79], v[154:157], v[216:219], v[76:79]
	v_mfma_f32_16x16x32_bf16 v[124:127], v[150:153], v[196:199], v[124:127]
	v_mfma_f32_16x16x32_bf16 v[120:123], v[158:161], v[196:199], v[120:123]
	v_mfma_f32_16x16x32_bf16 v[116:119], v[150:153], v[204:207], v[116:119]
	v_mfma_f32_16x16x32_bf16 v[108:111], v[158:161], v[204:207], v[108:111]
	v_mfma_f32_16x16x32_bf16 v[100:103], v[150:153], v[212:215], v[100:103]
	v_mfma_f32_16x16x32_bf16 v[92:95], v[158:161], v[212:215], v[92:95]
	v_mfma_f32_16x16x32_bf16 v[84:87], v[150:153], v[220:223], v[84:87]
	v_mfma_f32_16x16x32_bf16 v[76:79], v[158:161], v[220:223], v[76:79]
	v_mfma_f32_16x16x32_bf16 v[112:115], v[162:165], v[178:181], v[112:115]
	v_mfma_f32_16x16x32_bf16 v[104:107], v[170:173], v[178:181], v[104:107]
	v_mfma_f32_16x16x32_bf16 v[96:99], v[162:165], v[200:203], v[96:99]
	v_mfma_f32_16x16x32_bf16 v[88:91], v[170:173], v[200:203], v[88:91]
	v_mfma_f32_16x16x32_bf16 v[80:83], v[162:165], v[208:211], v[80:83]
	v_mfma_f32_16x16x32_bf16 v[72:75], v[170:173], v[208:211], v[72:75]
	v_mfma_f32_16x16x32_bf16 v[68:71], v[162:165], v[216:219], v[68:71]
	v_mfma_f32_16x16x32_bf16 v[64:67], v[170:173], v[216:219], v[64:67]
	v_mfma_f32_16x16x32_bf16 v[112:115], v[166:169], v[196:199], v[112:115]
	v_mfma_f32_16x16x32_bf16 v[104:107], v[174:177], v[196:199], v[104:107]
	v_mfma_f32_16x16x32_bf16 v[96:99], v[166:169], v[204:207], v[96:99]
	v_mfma_f32_16x16x32_bf16 v[88:91], v[174:177], v[204:207], v[88:91]
	v_mfma_f32_16x16x32_bf16 v[80:83], v[166:169], v[212:215], v[80:83]
	v_mfma_f32_16x16x32_bf16 v[72:75], v[174:177], v[212:215], v[72:75]
	v_mfma_f32_16x16x32_bf16 v[68:71], v[166:169], v[220:223], v[68:71]
	v_mfma_f32_16x16x32_bf16 v[64:67], v[174:177], v[220:223], v[64:67]
	s_barrier
	s_setprio 0
	s_nop 7
	s_add_i32 s10, s10, s30
	v_lshl_add_u64 v[182:183], v[182:183], 0, s[88:89]
	s_mov_b32 m0, s10
	ds_read_b128 v[178:181], v143 offset:49152
	ds_read_b128 v[196:199], v143 offset:50176
	ds_read_b128 v[200:203], v143 offset:51200
	ds_read_b128 v[204:207], v143 offset:52224
	ds_read_b128 v[208:211], v143 offset:53248
	ds_read_b128 v[212:215], v143 offset:54272
	ds_read_b128 v[216:219], v143 offset:55296
	ds_read_b128 v[220:223], v143 offset:56320
	global_load_lds_dwordx4 v[182:183], off
	s_add_i32 m0, s10, 0x2000
	s_add_u32 s22, s22, 0x100080
	v_lshl_add_u64 v[182:183], v[188:189], 0, s[88:89]
	s_addc_u32 s23, s23, 0
	s_add_i32 s10, s11, s30
	global_load_lds_dwordx4 v[182:183], off
	v_lshl_add_u64 v[182:183], s[22:23], 0, v[144:145]
	s_mov_b32 m0, s10
	s_nop 0
	global_load_lds_dwordx4 v[182:183], off
	v_lshl_add_u64 v[182:183], s[22:23], 0, v[128:129]
	s_add_i32 m0, s10, 0x2000
	s_nop 0
	global_load_lds_dwordx4 v[182:183], off
	v_lshl_add_u64 v[182:183], v[190:191], 0, s[88:89]
	s_mov_b32 m0, s39
	s_nop 0
	global_load_lds_dwordx4 v[182:183], off
	v_lshl_add_u64 v[182:183], v[224:225], 0, s[88:89]
	s_mov_b32 m0, s40
	s_nop 0
	global_load_lds_dwordx4 v[182:183], off
	s_waitcnt vmcnt(8)
	s_waitcnt lgkmcnt(0)
	s_setprio 1
	s_barrier
	v_mfma_f32_16x16x32_bf16 v[60:63], v[146:149], v[178:181], v[60:63]
	v_mfma_f32_16x16x32_bf16 v[56:59], v[154:157], v[178:181], v[56:59]
	v_mfma_f32_16x16x32_bf16 v[52:55], v[146:149], v[200:203], v[52:55]
	v_mfma_f32_16x16x32_bf16 v[44:47], v[154:157], v[200:203], v[44:47]
	v_mfma_f32_16x16x32_bf16 v[36:39], v[146:149], v[208:211], v[36:39]
	v_mfma_f32_16x16x32_bf16 v[28:31], v[154:157], v[208:211], v[28:31]
	v_mfma_f32_16x16x32_bf16 v[20:23], v[146:149], v[216:219], v[20:23]
	v_mfma_f32_16x16x32_bf16 v[12:15], v[154:157], v[216:219], v[12:15]
	v_mfma_f32_16x16x32_bf16 v[60:63], v[150:153], v[196:199], v[60:63]
	v_mfma_f32_16x16x32_bf16 v[56:59], v[158:161], v[196:199], v[56:59]
	v_mfma_f32_16x16x32_bf16 v[52:55], v[150:153], v[204:207], v[52:55]
	v_mfma_f32_16x16x32_bf16 v[44:47], v[158:161], v[204:207], v[44:47]
	v_mfma_f32_16x16x32_bf16 v[36:39], v[150:153], v[212:215], v[36:39]
	v_mfma_f32_16x16x32_bf16 v[28:31], v[158:161], v[212:215], v[28:31]
	v_mfma_f32_16x16x32_bf16 v[20:23], v[150:153], v[220:223], v[20:23]
	v_mfma_f32_16x16x32_bf16 v[12:15], v[158:161], v[220:223], v[12:15]
	v_mfma_f32_16x16x32_bf16 v[48:51], v[162:165], v[178:181], v[48:51]
	v_mfma_f32_16x16x32_bf16 v[40:43], v[170:173], v[178:181], v[40:43]
	v_mfma_f32_16x16x32_bf16 v[32:35], v[162:165], v[200:203], v[32:35]
	v_mfma_f32_16x16x32_bf16 v[24:27], v[170:173], v[200:203], v[24:27]
	v_mfma_f32_16x16x32_bf16 v[16:19], v[162:165], v[208:211], v[16:19]
	v_mfma_f32_16x16x32_bf16 v[8:11], v[170:173], v[208:211], v[8:11]
	v_mfma_f32_16x16x32_bf16 v[4:7], v[162:165], v[216:219], v[4:7]
	v_mfma_f32_16x16x32_bf16 v[0:3], v[170:173], v[216:219], v[0:3]
	v_mfma_f32_16x16x32_bf16 v[48:51], v[166:169], v[196:199], v[48:51]
	v_mfma_f32_16x16x32_bf16 v[40:43], v[174:177], v[196:199], v[40:43]
	v_mfma_f32_16x16x32_bf16 v[32:35], v[166:169], v[204:207], v[32:35]
	v_mfma_f32_16x16x32_bf16 v[24:27], v[174:177], v[204:207], v[24:27]
	v_mfma_f32_16x16x32_bf16 v[16:19], v[166:169], v[212:215], v[16:19]
	v_mfma_f32_16x16x32_bf16 v[8:11], v[174:177], v[212:215], v[8:11]
	v_mfma_f32_16x16x32_bf16 v[4:7], v[166:169], v[220:223], v[4:7]
	v_mfma_f32_16x16x32_bf16 v[0:3], v[174:177], v[220:223], v[0:3]
	s_barrier
	s_setprio 0
	s_nop 7
	s_add_i32 s47, s47, 2
	s_add_u32 s45, s45, 0x100
	s_addc_u32 s46, s46, 0
	s_add_u32 s20, s20, 0x100
	s_addc_u32 s21, s21, 0
	s_cmp_gt_u32 s47, 61
	s_cbranch_scc0 .LBB0_1790
	v_readlane_b32 s44, v251, 59
	s_and_b64 vcc, exec, s[6:7]
	v_readlane_b32 s45, v251, 60
	s_cbranch_vccz .LBB0_1793
	s_barrier

.LBB0_2006:
	s_add_u32 s10, s26, 0xfffe0080
	s_addc_u32 s11, s27, -1
	s_add_i32 s33, 0, 0x10000
	s_cmp_eq_u32 s53, 4
	s_cselect_b32 s31, s19, s11
	s_cselect_b32 s30, s49, s10
	s_cselect_b32 s29, s21, s52
	s_cselect_b32 s28, s50, s51
	s_add_i32 s10, 0, 0x14000
	v_add_u32_e32 v156, s33, v143
	v_add_u32_e32 v172, s10, v143
	ds_read_b128 v[138:141], v156
	ds_read_b128 v[148:151], v156 offset:1024
	ds_read_b128 v[152:155], v156 offset:2048
	ds_read_b128 v[156:159], v156 offset:3072
	ds_read_b128 v[160:163], v172
	ds_read_b128 v[164:167], v172 offset:1024
	ds_read_b128 v[168:171], v172 offset:2048
	ds_read_b128 v[172:175], v172 offset:3072
	v_lshl_add_u64 v[216:217], s[26:27], 0, v[136:137]
	s_add_i32 m0, s39, 0xc000
	ds_read_b128 v[176:179], v147
	ds_read_b128 v[180:183], v147 offset:1024
	ds_read_b128 v[188:191], v147 offset:2048
	ds_read_b128 v[196:199], v147 offset:3072
	ds_read_b128 v[200:203], v147 offset:4096
	ds_read_b128 v[204:207], v147 offset:5120
	ds_read_b128 v[208:211], v147 offset:6144
	ds_read_b128 v[212:215], v147 offset:7168
	global_load_lds_dwordx4 v[216:217], off
	v_lshl_add_u64 v[216:217], s[26:27], 0, v[134:135]
	s_add_i32 m0, s39, 0xe000
	s_nop 0
	global_load_lds_dwordx4 v[216:217], off
	s_waitcnt vmcnt(8)
	s_waitcnt lgkmcnt(0)
	s_setprio 1
	s_barrier
	v_mfma_f32_16x16x32_bf16 v[124:127], v[138:141], v[176:179], v[124:127]
	v_mfma_f32_16x16x32_bf16 v[120:123], v[152:155], v[176:179], v[120:123]
	v_mfma_f32_16x16x32_bf16 v[108:111], v[138:141], v[188:191], v[108:111]
	v_mfma_f32_16x16x32_bf16 v[104:107], v[152:155], v[188:191], v[104:107]
	v_mfma_f32_16x16x32_bf16 v[92:95], v[138:141], v[200:203], v[92:95]
	v_mfma_f32_16x16x32_bf16 v[88:91], v[152:155], v[200:203], v[88:91]
	v_mfma_f32_16x16x32_bf16 v[76:79], v[138:141], v[208:211], v[76:79]
	v_mfma_f32_16x16x32_bf16 v[72:75], v[152:155], v[208:211], v[72:75]
	v_mfma_f32_16x16x32_bf16 v[124:127], v[148:151], v[180:183], v[124:127]
	v_mfma_f32_16x16x32_bf16 v[120:123], v[156:159], v[180:183], v[120:123]
	v_mfma_f32_16x16x32_bf16 v[108:111], v[148:151], v[196:199], v[108:111]
	v_mfma_f32_16x16x32_bf16 v[104:107], v[156:159], v[196:199], v[104:107]
	v_mfma_f32_16x16x32_bf16 v[92:95], v[148:151], v[204:207], v[92:95]
	v_mfma_f32_16x16x32_bf16 v[88:91], v[156:159], v[204:207], v[88:91]
	v_mfma_f32_16x16x32_bf16 v[76:79], v[148:151], v[212:215], v[76:79]
	v_mfma_f32_16x16x32_bf16 v[72:75], v[156:159], v[212:215], v[72:75]
	v_mfma_f32_16x16x32_bf16 v[116:119], v[160:163], v[176:179], v[116:119]
	v_mfma_f32_16x16x32_bf16 v[112:115], v[168:171], v[176:179], v[112:115]
	v_mfma_f32_16x16x32_bf16 v[100:103], v[160:163], v[188:191], v[100:103]
	v_mfma_f32_16x16x32_bf16 v[96:99], v[168:171], v[188:191], v[96:99]
	v_mfma_f32_16x16x32_bf16 v[84:87], v[160:163], v[200:203], v[84:87]
	v_mfma_f32_16x16x32_bf16 v[80:83], v[168:171], v[200:203], v[80:83]
	v_mfma_f32_16x16x32_bf16 v[68:71], v[160:163], v[208:211], v[68:71]
	v_mfma_f32_16x16x32_bf16 v[64:67], v[168:171], v[208:211], v[64:67]
	v_mfma_f32_16x16x32_bf16 v[116:119], v[164:167], v[180:183], v[116:119]
	v_mfma_f32_16x16x32_bf16 v[112:115], v[172:175], v[180:183], v[112:115]
	v_mfma_f32_16x16x32_bf16 v[100:103], v[164:167], v[196:199], v[100:103]
	v_mfma_f32_16x16x32_bf16 v[96:99], v[172:175], v[196:199], v[96:99]
	v_mfma_f32_16x16x32_bf16 v[84:87], v[164:167], v[204:207], v[84:87]
	v_mfma_f32_16x16x32_bf16 v[80:83], v[172:175], v[204:207], v[80:83]
	v_mfma_f32_16x16x32_bf16 v[68:71], v[164:167], v[212:215], v[68:71]
	v_mfma_f32_16x16x32_bf16 v[64:67], v[172:175], v[212:215], v[64:67]
	s_barrier
	s_setprio 0
	s_nop 7
	s_add_i32 s11, s33, s38
	v_lshl_add_u64 v[216:217], s[28:29], 0, v[144:145]
	s_mov_b32 m0, s11
	ds_read_b128 v[176:179], v147 offset:16384
	ds_read_b128 v[180:183], v147 offset:17408
	ds_read_b128 v[188:191], v147 offset:18432
	ds_read_b128 v[196:199], v147 offset:19456
	ds_read_b128 v[200:203], v147 offset:20480
	ds_read_b128 v[204:207], v147 offset:21504
	ds_read_b128 v[208:211], v147 offset:22528
	ds_read_b128 v[212:215], v147 offset:23552
	global_load_lds_dwordx4 v[216:217], off
	s_add_i32 m0, s11, 0x2000
	s_add_u32 s54, s28, 0x20000
	v_lshl_add_u64 v[218:219], s[28:29], 0, v[128:129]
	s_addc_u32 s55, s29, 0
	s_add_i32 s10, s10, s38
	global_load_lds_dwordx4 v[218:219], off
	v_lshl_add_u64 v[220:221], s[54:55], 0, v[144:145]
	s_mov_b32 m0, s10
	v_lshl_add_u64 v[222:223], s[30:31], 0, v[130:131]
	global_load_lds_dwordx4 v[220:221], off
	v_lshl_add_u64 v[220:221], s[54:55], 0, v[128:129]
	s_add_i32 m0, s10, 0x2000
	s_nop 0
	global_load_lds_dwordx4 v[220:221], off
	v_lshl_add_u64 v[220:221], s[30:31], 0, v[132:133]
	s_mov_b32 m0, s39
	s_nop 0
	global_load_lds_dwordx4 v[220:221], off
	s_mov_b32 m0, s40
	s_nop 0
	global_load_lds_dwordx4 v[222:223], off
	s_waitcnt vmcnt(8)
	s_waitcnt lgkmcnt(0)
	s_setprio 1
	s_barrier
	v_mfma_f32_16x16x32_bf16 v[60:63], v[138:141], v[176:179], v[60:63]
	v_mfma_f32_16x16x32_bf16 v[56:59], v[152:155], v[176:179], v[56:59]
	v_mfma_f32_16x16x32_bf16 v[44:47], v[138:141], v[188:191], v[44:47]
	v_mfma_f32_16x16x32_bf16 v[40:43], v[152:155], v[188:191], v[40:43]
	v_mfma_f32_16x16x32_bf16 v[28:31], v[138:141], v[200:203], v[28:31]
	v_mfma_f32_16x16x32_bf16 v[24:27], v[152:155], v[200:203], v[24:27]
	v_mfma_f32_16x16x32_bf16 v[12:15], v[138:141], v[208:211], v[12:15]
	v_mfma_f32_16x16x32_bf16 v[8:11], v[152:155], v[208:211], v[8:11]
	v_mfma_f32_16x16x32_bf16 v[60:63], v[148:151], v[180:183], v[60:63]
	v_mfma_f32_16x16x32_bf16 v[56:59], v[156:159], v[180:183], v[56:59]
	v_mfma_f32_16x16x32_bf16 v[44:47], v[148:151], v[196:199], v[44:47]
	v_mfma_f32_16x16x32_bf16 v[40:43], v[156:159], v[196:199], v[40:43]
	v_mfma_f32_16x16x32_bf16 v[28:31], v[148:151], v[204:207], v[28:31]
	v_mfma_f32_16x16x32_bf16 v[24:27], v[156:159], v[204:207], v[24:27]
	v_mfma_f32_16x16x32_bf16 v[12:15], v[148:151], v[212:215], v[12:15]
	v_mfma_f32_16x16x32_bf16 v[8:11], v[156:159], v[212:215], v[8:11]
	v_mfma_f32_16x16x32_bf16 v[52:55], v[160:163], v[176:179], v[52:55]
	v_mfma_f32_16x16x32_bf16 v[48:51], v[168:171], v[176:179], v[48:51]
	v_mfma_f32_16x16x32_bf16 v[36:39], v[160:163], v[188:191], v[36:39]
	v_mfma_f32_16x16x32_bf16 v[32:35], v[168:171], v[188:191], v[32:35]
	v_mfma_f32_16x16x32_bf16 v[20:23], v[160:163], v[200:203], v[20:23]
	v_mfma_f32_16x16x32_bf16 v[16:19], v[168:171], v[200:203], v[16:19]
	v_mfma_f32_16x16x32_bf16 v[4:7], v[160:163], v[208:211], v[4:7]
	v_mfma_f32_16x16x32_bf16 v[0:3], v[168:171], v[208:211], v[0:3]
	v_mfma_f32_16x16x32_bf16 v[52:55], v[164:167], v[180:183], v[52:55]
	v_mfma_f32_16x16x32_bf16 v[48:51], v[172:175], v[180:183], v[48:51]
	v_mfma_f32_16x16x32_bf16 v[36:39], v[164:167], v[196:199], v[36:39]
	v_mfma_f32_16x16x32_bf16 v[32:35], v[172:175], v[196:199], v[32:35]
	v_mfma_f32_16x16x32_bf16 v[20:23], v[164:167], v[204:207], v[20:23]
	v_mfma_f32_16x16x32_bf16 v[16:19], v[172:175], v[204:207], v[16:19]
	v_mfma_f32_16x16x32_bf16 v[4:7], v[164:167], v[212:215], v[4:7]
	v_mfma_f32_16x16x32_bf16 v[0:3], v[172:175], v[212:215], v[0:3]
	s_barrier
	s_setprio 0
	s_nop 7
	s_add_i32 s10, 0, 0x18000
	s_add_i32 s11, 0, 0x1c000
	v_add_u32_e32 v156, s10, v143
	v_add_u32_e32 v172, s11, v143
	ds_read_b128 v[138:141], v156
	ds_read_b128 v[148:151], v156 offset:1024
	ds_read_b128 v[152:155], v156 offset:2048
	ds_read_b128 v[156:159], v156 offset:3072
	ds_read_b128 v[160:163], v172
	ds_read_b128 v[164:167], v172 offset:1024
	ds_read_b128 v[168:171], v172 offset:2048
	ds_read_b128 v[172:175], v172 offset:3072
	s_add_u32 s30, s30, 0x20000
	s_addc_u32 s31, s31, 0
	s_mov_b32 m0, s41
	v_lshl_add_u64 v[224:225], s[30:31], 0, v[132:133]
	ds_read_b128 v[176:179], v147 offset:32768
	ds_read_b128 v[180:183], v147 offset:33792
	ds_read_b128 v[188:191], v147 offset:34816
	ds_read_b128 v[196:199], v147 offset:35840
	ds_read_b128 v[200:203], v147 offset:36864
	ds_read_b128 v[204:207], v147 offset:37888
	ds_read_b128 v[208:211], v147 offset:38912
	ds_read_b128 v[212:215], v147 offset:39936
	global_load_lds_dwordx4 v[224:225], off
	v_lshl_add_u64 v[224:225], s[30:31], 0, v[130:131]
	s_mov_b32 m0, s42
	s_nop 0
	global_load_lds_dwordx4 v[224:225], off
	s_waitcnt vmcnt(8)
	s_waitcnt lgkmcnt(0)
	s_setprio 1
	s_barrier
	v_mfma_f32_16x16x32_bf16 v[124:127], v[138:141], v[176:179], v[124:127]
	v_mfma_f32_16x16x32_bf16 v[120:123], v[152:155], v[176:179], v[120:123]
	v_mfma_f32_16x16x32_bf16 v[108:111], v[138:141], v[188:191], v[108:111]
	v_mfma_f32_16x16x32_bf16 v[104:107], v[152:155], v[188:191], v[104:107]
	v_mfma_f32_16x16x32_bf16 v[92:95], v[138:141], v[200:203], v[92:95]
	v_mfma_f32_16x16x32_bf16 v[88:91], v[152:155], v[200:203], v[88:91]
	v_mfma_f32_16x16x32_bf16 v[76:79], v[138:141], v[208:211], v[76:79]
	v_mfma_f32_16x16x32_bf16 v[72:75], v[152:155], v[208:211], v[72:75]
	v_mfma_f32_16x16x32_bf16 v[124:127], v[148:151], v[180:183], v[124:127]
	v_mfma_f32_16x16x32_bf16 v[120:123], v[156:159], v[180:183], v[120:123]
	v_mfma_f32_16x16x32_bf16 v[108:111], v[148:151], v[196:199], v[108:111]
	v_mfma_f32_16x16x32_bf16 v[104:107], v[156:159], v[196:199], v[104:107]
	v_mfma_f32_16x16x32_bf16 v[92:95], v[148:151], v[204:207], v[92:95]
	v_mfma_f32_16x16x32_bf16 v[88:91], v[156:159], v[204:207], v[88:91]
	v_mfma_f32_16x16x32_bf16 v[76:79], v[148:151], v[212:215], v[76:79]
	v_mfma_f32_16x16x32_bf16 v[72:75], v[156:159], v[212:215], v[72:75]
	v_mfma_f32_16x16x32_bf16 v[116:119], v[160:163], v[176:179], v[116:119]
	v_mfma_f32_16x16x32_bf16 v[112:115], v[168:171], v[176:179], v[112:115]
	v_mfma_f32_16x16x32_bf16 v[100:103], v[160:163], v[188:191], v[100:103]
	v_mfma_f32_16x16x32_bf16 v[96:99], v[168:171], v[188:191], v[96:99]
	v_mfma_f32_16x16x32_bf16 v[84:87], v[160:163], v[200:203], v[84:87]
	v_mfma_f32_16x16x32_bf16 v[80:83], v[168:171], v[200:203], v[80:83]
	v_mfma_f32_16x16x32_bf16 v[68:71], v[160:163], v[208:211], v[68:71]
	v_mfma_f32_16x16x32_bf16 v[64:67], v[168:171], v[208:211], v[64:67]
	v_mfma_f32_16x16x32_bf16 v[116:119], v[164:167], v[180:183], v[116:119]
	v_mfma_f32_16x16x32_bf16 v[112:115], v[172:175], v[180:183], v[112:115]
	v_mfma_f32_16x16x32_bf16 v[100:103], v[164:167], v[196:199], v[100:103]
	v_mfma_f32_16x16x32_bf16 v[96:99], v[172:175], v[196:199], v[96:99]
	v_mfma_f32_16x16x32_bf16 v[84:87], v[164:167], v[204:207], v[84:87]
	v_mfma_f32_16x16x32_bf16 v[80:83], v[172:175], v[204:207], v[80:83]
	v_mfma_f32_16x16x32_bf16 v[68:71], v[164:167], v[212:215], v[68:71]
	v_mfma_f32_16x16x32_bf16 v[64:67], v[172:175], v[212:215], v[64:67]
	s_barrier
	s_setprio 0
	s_nop 7
	s_add_i32 s10, s10, s38
	v_lshl_add_u64 v[216:217], v[216:217], 0, s[88:89]
	s_mov_b32 m0, s10
	ds_read_b128 v[176:179], v147 offset:49152
	ds_read_b128 v[180:183], v147 offset:50176
	ds_read_b128 v[188:191], v147 offset:51200
	ds_read_b128 v[196:199], v147 offset:52224
	ds_read_b128 v[200:203], v147 offset:53248
	ds_read_b128 v[204:207], v147 offset:54272
	ds_read_b128 v[208:211], v147 offset:55296
	ds_read_b128 v[212:215], v147 offset:56320
	global_load_lds_dwordx4 v[216:217], off
	s_add_i32 m0, s10, 0x2000
	s_add_u32 s28, s28, 0x20080
	v_lshl_add_u64 v[216:217], v[218:219], 0, s[88:89]
	s_addc_u32 s29, s29, 0
	s_add_i32 s10, s11, s38
	global_load_lds_dwordx4 v[216:217], off
	v_lshl_add_u64 v[216:217], s[28:29], 0, v[144:145]
	s_mov_b32 m0, s10
	s_nop 0
	global_load_lds_dwordx4 v[216:217], off
	v_lshl_add_u64 v[216:217], s[28:29], 0, v[128:129]
	s_add_i32 m0, s10, 0x2000
	s_nop 0
	global_load_lds_dwordx4 v[216:217], off
	v_lshl_add_u64 v[216:217], v[220:221], 0, s[88:89]
	s_mov_b32 m0, s44
	s_nop 0
	global_load_lds_dwordx4 v[216:217], off
	v_lshl_add_u64 v[216:217], v[222:223], 0, s[88:89]
	s_mov_b32 m0, s45
	s_nop 0
	global_load_lds_dwordx4 v[216:217], off
	s_waitcnt vmcnt(8)
	s_waitcnt lgkmcnt(0)
	s_setprio 1
	s_barrier
	v_mfma_f32_16x16x32_bf16 v[60:63], v[138:141], v[176:179], v[60:63]
	v_mfma_f32_16x16x32_bf16 v[56:59], v[152:155], v[176:179], v[56:59]
	v_mfma_f32_16x16x32_bf16 v[44:47], v[138:141], v[188:191], v[44:47]
	v_mfma_f32_16x16x32_bf16 v[40:43], v[152:155], v[188:191], v[40:43]
	v_mfma_f32_16x16x32_bf16 v[28:31], v[138:141], v[200:203], v[28:31]
	v_mfma_f32_16x16x32_bf16 v[24:27], v[152:155], v[200:203], v[24:27]
	v_mfma_f32_16x16x32_bf16 v[12:15], v[138:141], v[208:211], v[12:15]
	v_mfma_f32_16x16x32_bf16 v[8:11], v[152:155], v[208:211], v[8:11]
	v_mfma_f32_16x16x32_bf16 v[60:63], v[148:151], v[180:183], v[60:63]
	v_mfma_f32_16x16x32_bf16 v[56:59], v[156:159], v[180:183], v[56:59]
	v_mfma_f32_16x16x32_bf16 v[44:47], v[148:151], v[196:199], v[44:47]
	v_mfma_f32_16x16x32_bf16 v[40:43], v[156:159], v[196:199], v[40:43]
	v_mfma_f32_16x16x32_bf16 v[28:31], v[148:151], v[204:207], v[28:31]
	v_mfma_f32_16x16x32_bf16 v[24:27], v[156:159], v[204:207], v[24:27]
	v_mfma_f32_16x16x32_bf16 v[12:15], v[148:151], v[212:215], v[12:15]
	v_mfma_f32_16x16x32_bf16 v[8:11], v[156:159], v[212:215], v[8:11]
	v_mfma_f32_16x16x32_bf16 v[52:55], v[160:163], v[176:179], v[52:55]
	v_mfma_f32_16x16x32_bf16 v[48:51], v[168:171], v[176:179], v[48:51]
	v_mfma_f32_16x16x32_bf16 v[36:39], v[160:163], v[188:191], v[36:39]
	v_mfma_f32_16x16x32_bf16 v[32:35], v[168:171], v[188:191], v[32:35]
	v_mfma_f32_16x16x32_bf16 v[20:23], v[160:163], v[200:203], v[20:23]
	v_mfma_f32_16x16x32_bf16 v[16:19], v[168:171], v[200:203], v[16:19]
	v_mfma_f32_16x16x32_bf16 v[4:7], v[160:163], v[208:211], v[4:7]
	v_mfma_f32_16x16x32_bf16 v[0:3], v[168:171], v[208:211], v[0:3]
	v_mfma_f32_16x16x32_bf16 v[52:55], v[164:167], v[180:183], v[52:55]
	v_mfma_f32_16x16x32_bf16 v[48:51], v[172:175], v[180:183], v[48:51]
	v_mfma_f32_16x16x32_bf16 v[36:39], v[164:167], v[196:199], v[36:39]
	v_mfma_f32_16x16x32_bf16 v[32:35], v[172:175], v[196:199], v[32:35]
	v_mfma_f32_16x16x32_bf16 v[20:23], v[164:167], v[204:207], v[20:23]
	v_mfma_f32_16x16x32_bf16 v[16:19], v[172:175], v[204:207], v[16:19]
	v_mfma_f32_16x16x32_bf16 v[4:7], v[164:167], v[212:215], v[4:7]
	v_mfma_f32_16x16x32_bf16 v[0:3], v[172:175], v[212:215], v[0:3]
	s_barrier
	s_setprio 0
	s_nop 7
	s_add_i32 s53, s53, 2
	s_add_u32 s51, s51, 0x100
	s_addc_u32 s52, s52, 0
	s_add_u32 s26, s26, 0x100
	s_addc_u32 s27, s27, 0
	s_cmp_gt_u32 s53, 5
	s_cbranch_scc0 .LBB0_2006
	s_and_b64 vcc, exec, s[16:17]
	s_cbranch_vccz .LBB0_2009
	s_barrier

.LBB0_2146:
	s_ashr_i32 s51, s50, 31
	s_lshl_b64 s[52:53], s[50:51], 21
	s_add_u32 s52, s63, s52
	s_addc_u32 s53, s66, s53
	s_and_b64 s[54:55], s[8:9], exec
	s_cselect_b32 s51, s53, s59
	s_cselect_b32 s64, s52, s58
	s_ashr_i32 s49, s48, 31
	s_lshl_b64 s[54:55], s[48:49], 21
	s_add_u32 s54, s67, s54
	s_addc_u32 s55, s69, s55
	s_and_b64 s[60:61], s[8:9], exec
	s_cselect_b32 s49, s55, s57
	s_cselect_b32 s65, s54, s56
	s_add_u32 s95, s56, 0x100
	s_addc_u32 s97, s57, 0
	s_add_u32 s56, s58, 0x100080
	v_mov_b32_e32 v8, 0
	s_addc_u32 s57, s59, 0
	s_mov_b32 vcc_lo, -2
	v_mov_b32_e32 v9, v8
	v_mov_b32_e32 v10, v8
	v_mov_b32_e32 v11, v8
	v_mov_b32_e32 v20, v8
	v_mov_b32_e32 v21, v8
	v_mov_b32_e32 v22, v8
	v_mov_b32_e32 v23, v8
	v_mov_b32_e32 v12, v8
	v_mov_b32_e32 v13, v8
	v_mov_b32_e32 v14, v8
	v_mov_b32_e32 v15, v8
	v_mov_b32_e32 v16, v8
	v_mov_b32_e32 v17, v8
	v_mov_b32_e32 v18, v8
	v_mov_b32_e32 v19, v8
	v_mov_b32_e32 v0, v8
	v_mov_b32_e32 v1, v8
	v_mov_b32_e32 v2, v8
	v_mov_b32_e32 v3, v8
	v_mov_b32_e32 v4, v8
	v_mov_b32_e32 v5, v8
	v_mov_b32_e32 v6, v8
	v_mov_b32_e32 v7, v8
	v_mov_b32_e32 v40, v8
	v_mov_b32_e32 v41, v8
	v_mov_b32_e32 v42, v8
	v_mov_b32_e32 v43, v8
	v_mov_b32_e32 v44, v8
	v_mov_b32_e32 v45, v8
	v_mov_b32_e32 v46, v8
	v_mov_b32_e32 v47, v8
	v_mov_b32_e32 v56, v8
	v_mov_b32_e32 v57, v8
	v_mov_b32_e32 v58, v8
	v_mov_b32_e32 v59, v8
	v_mov_b32_e32 v60, v8
	v_mov_b32_e32 v61, v8
	v_mov_b32_e32 v62, v8
	v_mov_b32_e32 v63, v8
	v_mov_b32_e32 v32, v8
	v_mov_b32_e32 v33, v8
	v_mov_b32_e32 v34, v8
	v_mov_b32_e32 v35, v8
	v_mov_b32_e32 v36, v8
	v_mov_b32_e32 v37, v8
	v_mov_b32_e32 v38, v8
	v_mov_b32_e32 v39, v8
	v_mov_b32_e32 v24, v8
	v_mov_b32_e32 v25, v8
	v_mov_b32_e32 v26, v8
	v_mov_b32_e32 v27, v8
	v_mov_b32_e32 v28, v8
	v_mov_b32_e32 v29, v8
	v_mov_b32_e32 v30, v8
	v_mov_b32_e32 v31, v8
	v_mov_b32_e32 v48, v8
	v_mov_b32_e32 v49, v8
	v_mov_b32_e32 v50, v8
	v_mov_b32_e32 v51, v8
	v_mov_b32_e32 v52, v8
	v_mov_b32_e32 v53, v8
	v_mov_b32_e32 v54, v8
	v_mov_b32_e32 v55, v8
	v_mov_b32_e32 v96, v8
	v_mov_b32_e32 v97, v8
	v_mov_b32_e32 v98, v8
	v_mov_b32_e32 v99, v8
	v_mov_b32_e32 v100, v8
	v_mov_b32_e32 v101, v8
	v_mov_b32_e32 v102, v8
	v_mov_b32_e32 v103, v8
	v_mov_b32_e32 v104, v8
	v_mov_b32_e32 v105, v8
	v_mov_b32_e32 v106, v8
	v_mov_b32_e32 v107, v8
	v_mov_b32_e32 v108, v8
	v_mov_b32_e32 v109, v8
	v_mov_b32_e32 v110, v8
	v_mov_b32_e32 v111, v8
	v_mov_b32_e32 v112, v8
	v_mov_b32_e32 v113, v8
	v_mov_b32_e32 v114, v8
	v_mov_b32_e32 v115, v8
	v_mov_b32_e32 v116, v8
	v_mov_b32_e32 v117, v8
	v_mov_b32_e32 v118, v8
	v_mov_b32_e32 v119, v8
	v_mov_b32_e32 v136, v8
	v_mov_b32_e32 v137, v8
	v_mov_b32_e32 v138, v8
	v_mov_b32_e32 v139, v8
	v_mov_b32_e32 v140, v8
	v_mov_b32_e32 v141, v8
	v_mov_b32_e32 v142, v8
	v_mov_b32_e32 v143, v8
	v_mov_b32_e32 v64, v8
	v_mov_b32_e32 v65, v8
	v_mov_b32_e32 v66, v8
	v_mov_b32_e32 v67, v8
	v_mov_b32_e32 v68, v8
	v_mov_b32_e32 v69, v8
	v_mov_b32_e32 v70, v8
	v_mov_b32_e32 v71, v8
	v_mov_b32_e32 v120, v8
	v_mov_b32_e32 v121, v8
	v_mov_b32_e32 v122, v8
	v_mov_b32_e32 v123, v8
	v_mov_b32_e32 v124, v8
	v_mov_b32_e32 v125, v8
	v_mov_b32_e32 v126, v8
	v_mov_b32_e32 v127, v8
	v_mov_b32_e32 v128, v8
	v_mov_b32_e32 v129, v8
	v_mov_b32_e32 v130, v8
	v_mov_b32_e32 v131, v8
	v_mov_b32_e32 v132, v8
	v_mov_b32_e32 v133, v8
	v_mov_b32_e32 v134, v8
	v_mov_b32_e32 v135, v8
	v_mov_b32_e32 v146, v8
	v_mov_b32_e32 v147, v8
	v_mov_b32_e32 v148, v8
	v_mov_b32_e32 v149, v8
	v_mov_b32_e32 v150, v8
	v_mov_b32_e32 v151, v8
	v_mov_b32_e32 v152, v8
	v_mov_b32_e32 v153, v8
	v_add_u32_e32 v244, 0x10000, v207
.LBB0_2147:
	s_add_u32 s10, s56, 0xfff00080
	s_addc_u32 s11, s57, -1
	s_add_i32 s33, 0, 0x10000
	s_cmp_eq_u32 vcc_lo, 60
	s_cselect_b32 s61, s51, s11
	s_cselect_b32 s60, s64, s10
	s_cselect_b32 s59, s49, s97
	s_cselect_b32 s58, s65, s95
	s_add_i32 vcc_hi, 0, 0x14000
	ds_read_b128 v[72:75], v244
	ds_read_b128 v[76:79], v244 offset:1024
	ds_read_b128 v[80:83], v244 offset:2048
	ds_read_b128 v[84:87], v244 offset:3072
	ds_read_b128 v[88:91], v244 offset:16384
	ds_read_b128 v[92:95], v244 offset:17408
	ds_read_b128 v[154:157], v244 offset:18432
	ds_read_b128 v[158:161], v244 offset:19456
	s_add_i32 m0, s73, 0xc000
	ds_read_b128 v[162:165], v232
	ds_read_b128 v[166:169], v232 offset:1024
	ds_read_b128 v[170:173], v232 offset:2048
	ds_read_b128 v[174:177], v232 offset:3072
	ds_read_b128 v[180:183], v232 offset:4096
	ds_read_b128 v[188:191], v232 offset:5120
	ds_read_b128 v[208:211], v232 offset:6144
	ds_read_b128 v[234:237], v232 offset:7168
	global_load_lds_dwordx4 v202, s[56:57]
	s_add_i32 m0, s73, 0xe000
	s_nop 0
	global_load_lds_dwordx4 v200, s[56:57]
	s_waitcnt vmcnt(8)
	s_waitcnt lgkmcnt(0)
	s_setprio 1
	s_barrier
	v_mfma_f32_16x16x32_bf16 v[150:153], v[72:75], v[162:165], v[150:153]
	v_mfma_f32_16x16x32_bf16 v[146:149], v[80:83], v[162:165], v[146:149]
	v_mfma_f32_16x16x32_bf16 v[132:135], v[72:75], v[170:173], v[132:135]
	v_mfma_f32_16x16x32_bf16 v[128:131], v[80:83], v[170:173], v[128:131]
	v_mfma_f32_16x16x32_bf16 v[124:127], v[72:75], v[180:183], v[124:127]
	v_mfma_f32_16x16x32_bf16 v[120:123], v[80:83], v[180:183], v[120:123]
	v_mfma_f32_16x16x32_bf16 v[68:71], v[72:75], v[208:211], v[68:71]
	v_mfma_f32_16x16x32_bf16 v[64:67], v[80:83], v[208:211], v[64:67]
	v_mfma_f32_16x16x32_bf16 v[150:153], v[76:79], v[166:169], v[150:153]
	v_mfma_f32_16x16x32_bf16 v[146:149], v[84:87], v[166:169], v[146:149]
	v_mfma_f32_16x16x32_bf16 v[132:135], v[76:79], v[174:177], v[132:135]
	v_mfma_f32_16x16x32_bf16 v[128:131], v[84:87], v[174:177], v[128:131]
	v_mfma_f32_16x16x32_bf16 v[124:127], v[76:79], v[188:191], v[124:127]
	v_mfma_f32_16x16x32_bf16 v[120:123], v[84:87], v[188:191], v[120:123]
	v_mfma_f32_16x16x32_bf16 v[68:71], v[76:79], v[234:237], v[68:71]
	v_mfma_f32_16x16x32_bf16 v[64:67], v[84:87], v[234:237], v[64:67]
	v_mfma_f32_16x16x32_bf16 v[140:143], v[88:91], v[162:165], v[140:143]
	v_mfma_f32_16x16x32_bf16 v[136:139], v[154:157], v[162:165], v[136:139]
	v_mfma_f32_16x16x32_bf16 v[116:119], v[88:91], v[170:173], v[116:119]
	v_mfma_f32_16x16x32_bf16 v[112:115], v[154:157], v[170:173], v[112:115]
	v_mfma_f32_16x16x32_bf16 v[108:111], v[88:91], v[180:183], v[108:111]
	v_mfma_f32_16x16x32_bf16 v[104:107], v[154:157], v[180:183], v[104:107]
	v_mfma_f32_16x16x32_bf16 v[100:103], v[88:91], v[208:211], v[100:103]
	v_mfma_f32_16x16x32_bf16 v[96:99], v[154:157], v[208:211], v[96:99]
	v_mfma_f32_16x16x32_bf16 v[140:143], v[92:95], v[166:169], v[140:143]
	v_mfma_f32_16x16x32_bf16 v[136:139], v[158:161], v[166:169], v[136:139]
	v_mfma_f32_16x16x32_bf16 v[116:119], v[92:95], v[174:177], v[116:119]
	v_mfma_f32_16x16x32_bf16 v[112:115], v[158:161], v[174:177], v[112:115]
	v_mfma_f32_16x16x32_bf16 v[108:111], v[92:95], v[188:191], v[108:111]
	v_mfma_f32_16x16x32_bf16 v[104:107], v[158:161], v[188:191], v[104:107]
	v_mfma_f32_16x16x32_bf16 v[100:103], v[92:95], v[234:237], v[100:103]
	v_mfma_f32_16x16x32_bf16 v[96:99], v[158:161], v[234:237], v[96:99]
	s_barrier
	s_setprio 0
	s_nop 7
	s_add_i32 s10, s33, s72
	s_mov_b32 m0, s10
	ds_read_b128 v[162:165], v232 offset:16384
	ds_read_b128 v[166:169], v232 offset:17408
	ds_read_b128 v[170:173], v232 offset:18432
	ds_read_b128 v[174:177], v232 offset:19456
	ds_read_b128 v[180:183], v232 offset:20480
	ds_read_b128 v[188:191], v232 offset:21504
	ds_read_b128 v[208:211], v232 offset:22528
	ds_read_b128 v[234:237], v232 offset:23552
	global_load_lds_dwordx4 v144, s[58:59]
	s_add_i32 m0, s10, 0x2000
	s_add_u32 s10, s58, 0x100000
	s_addc_u32 s11, s59, 0
	s_add_i32 s33, vcc_hi, s72
	global_load_lds_dwordx4 v178, s[58:59]
	s_mov_b32 m0, s33
	s_nop 0
	global_load_lds_dwordx4 v144, s[10:11]
	s_add_i32 m0, s33, 0x2000
	s_nop 0
	global_load_lds_dwordx4 v178, s[10:11]
	s_mov_b32 m0, s73
	s_nop 0
	global_load_lds_dwordx4 v198, s[60:61]
	s_mov_b32 m0, s76
	s_nop 0
	global_load_lds_dwordx4 v196, s[60:61]
	s_waitcnt vmcnt(8)
	s_waitcnt lgkmcnt(0)
	s_setprio 1
	s_barrier
	v_mfma_f32_16x16x32_bf16 v[52:55], v[72:75], v[162:165], v[52:55]
	v_mfma_f32_16x16x32_bf16 v[48:51], v[80:83], v[162:165], v[48:51]
	v_mfma_f32_16x16x32_bf16 v[28:31], v[72:75], v[170:173], v[28:31]
	v_mfma_f32_16x16x32_bf16 v[24:27], v[80:83], v[170:173], v[24:27]
	v_mfma_f32_16x16x32_bf16 v[36:39], v[72:75], v[180:183], v[36:39]
	v_mfma_f32_16x16x32_bf16 v[32:35], v[80:83], v[180:183], v[32:35]
	v_mfma_f32_16x16x32_bf16 v[60:63], v[72:75], v[208:211], v[60:63]
	v_mfma_f32_16x16x32_bf16 v[56:59], v[80:83], v[208:211], v[56:59]
	v_mfma_f32_16x16x32_bf16 v[52:55], v[76:79], v[166:169], v[52:55]
	v_mfma_f32_16x16x32_bf16 v[48:51], v[84:87], v[166:169], v[48:51]
	v_mfma_f32_16x16x32_bf16 v[28:31], v[76:79], v[174:177], v[28:31]
	v_mfma_f32_16x16x32_bf16 v[24:27], v[84:87], v[174:177], v[24:27]
	v_mfma_f32_16x16x32_bf16 v[36:39], v[76:79], v[188:191], v[36:39]
	v_mfma_f32_16x16x32_bf16 v[32:35], v[84:87], v[188:191], v[32:35]
	v_mfma_f32_16x16x32_bf16 v[60:63], v[76:79], v[234:237], v[60:63]
	v_mfma_f32_16x16x32_bf16 v[56:59], v[84:87], v[234:237], v[56:59]
	v_mfma_f32_16x16x32_bf16 v[44:47], v[88:91], v[162:165], v[44:47]
	v_mfma_f32_16x16x32_bf16 v[40:43], v[154:157], v[162:165], v[40:43]
	v_mfma_f32_16x16x32_bf16 v[4:7], v[88:91], v[170:173], v[4:7]
	v_mfma_f32_16x16x32_bf16 v[0:3], v[154:157], v[170:173], v[0:3]
	v_mfma_f32_16x16x32_bf16 v[16:19], v[88:91], v[180:183], v[16:19]
	v_mfma_f32_16x16x32_bf16 v[12:15], v[154:157], v[180:183], v[12:15]
	v_mfma_f32_16x16x32_bf16 v[20:23], v[88:91], v[208:211], v[20:23]
	v_mfma_f32_16x16x32_bf16 v[8:11], v[154:157], v[208:211], v[8:11]
	v_mfma_f32_16x16x32_bf16 v[44:47], v[92:95], v[166:169], v[44:47]
	v_mfma_f32_16x16x32_bf16 v[40:43], v[158:161], v[166:169], v[40:43]
	v_mfma_f32_16x16x32_bf16 v[4:7], v[92:95], v[174:177], v[4:7]
	v_mfma_f32_16x16x32_bf16 v[0:3], v[158:161], v[174:177], v[0:3]
	v_mfma_f32_16x16x32_bf16 v[16:19], v[92:95], v[188:191], v[16:19]
	v_mfma_f32_16x16x32_bf16 v[12:15], v[158:161], v[188:191], v[12:15]
	v_mfma_f32_16x16x32_bf16 v[20:23], v[92:95], v[234:237], v[20:23]
	v_mfma_f32_16x16x32_bf16 v[8:11], v[158:161], v[234:237], v[8:11]
	s_barrier
	s_setprio 0
	s_nop 7
	s_add_i32 s33, 0, 0x18000
	s_add_i32 vcc_hi, 0, 0x1c000
	ds_read_b128 v[72:75], v244 offset:32768
	ds_read_b128 v[76:79], v244 offset:33792
	ds_read_b128 v[80:83], v244 offset:34816
	ds_read_b128 v[84:87], v244 offset:35840
	ds_read_b128 v[88:91], v244 offset:49152
	ds_read_b128 v[92:95], v244 offset:50176
	ds_read_b128 v[154:157], v244 offset:51200
	ds_read_b128 v[158:161], v244 offset:52224
	s_add_u32 s10, s60, 0x100000
	s_addc_u32 s11, s61, 0
	s_mov_b32 m0, s79
	ds_read_b128 v[162:165], v232 offset:32768
	ds_read_b128 v[166:169], v232 offset:33792
	ds_read_b128 v[170:173], v232 offset:34816
	ds_read_b128 v[174:177], v232 offset:35840
	ds_read_b128 v[180:183], v232 offset:36864
	ds_read_b128 v[188:191], v232 offset:37888
	ds_read_b128 v[208:211], v232 offset:38912
	ds_read_b128 v[234:237], v232 offset:39936
	global_load_lds_dwordx4 v198, s[10:11]
	s_mov_b32 m0, s80
	s_nop 0
	global_load_lds_dwordx4 v196, s[10:11]
	s_waitcnt vmcnt(8)
	s_waitcnt lgkmcnt(0)
	s_setprio 1
	s_barrier
	v_mfma_f32_16x16x32_bf16 v[150:153], v[72:75], v[162:165], v[150:153]
	v_mfma_f32_16x16x32_bf16 v[146:149], v[80:83], v[162:165], v[146:149]
	v_mfma_f32_16x16x32_bf16 v[132:135], v[72:75], v[170:173], v[132:135]
	v_mfma_f32_16x16x32_bf16 v[128:131], v[80:83], v[170:173], v[128:131]
	v_mfma_f32_16x16x32_bf16 v[124:127], v[72:75], v[180:183], v[124:127]
	v_mfma_f32_16x16x32_bf16 v[120:123], v[80:83], v[180:183], v[120:123]
	v_mfma_f32_16x16x32_bf16 v[68:71], v[72:75], v[208:211], v[68:71]
	v_mfma_f32_16x16x32_bf16 v[64:67], v[80:83], v[208:211], v[64:67]
	v_mfma_f32_16x16x32_bf16 v[150:153], v[76:79], v[166:169], v[150:153]
	v_mfma_f32_16x16x32_bf16 v[146:149], v[84:87], v[166:169], v[146:149]
	v_mfma_f32_16x16x32_bf16 v[132:135], v[76:79], v[174:177], v[132:135]
	v_mfma_f32_16x16x32_bf16 v[128:131], v[84:87], v[174:177], v[128:131]
	v_mfma_f32_16x16x32_bf16 v[124:127], v[76:79], v[188:191], v[124:127]
	v_mfma_f32_16x16x32_bf16 v[120:123], v[84:87], v[188:191], v[120:123]
	v_mfma_f32_16x16x32_bf16 v[68:71], v[76:79], v[234:237], v[68:71]
	v_mfma_f32_16x16x32_bf16 v[64:67], v[84:87], v[234:237], v[64:67]
	v_mfma_f32_16x16x32_bf16 v[140:143], v[88:91], v[162:165], v[140:143]
	v_mfma_f32_16x16x32_bf16 v[136:139], v[154:157], v[162:165], v[136:139]
	v_mfma_f32_16x16x32_bf16 v[116:119], v[88:91], v[170:173], v[116:119]
	v_mfma_f32_16x16x32_bf16 v[112:115], v[154:157], v[170:173], v[112:115]
	v_mfma_f32_16x16x32_bf16 v[108:111], v[88:91], v[180:183], v[108:111]
	v_mfma_f32_16x16x32_bf16 v[104:107], v[154:157], v[180:183], v[104:107]
	v_mfma_f32_16x16x32_bf16 v[100:103], v[88:91], v[208:211], v[100:103]
	v_mfma_f32_16x16x32_bf16 v[96:99], v[154:157], v[208:211], v[96:99]
	v_mfma_f32_16x16x32_bf16 v[140:143], v[92:95], v[166:169], v[140:143]
	v_mfma_f32_16x16x32_bf16 v[136:139], v[158:161], v[166:169], v[136:139]
	v_mfma_f32_16x16x32_bf16 v[116:119], v[92:95], v[174:177], v[116:119]
	v_mfma_f32_16x16x32_bf16 v[112:115], v[158:161], v[174:177], v[112:115]
	v_mfma_f32_16x16x32_bf16 v[108:111], v[92:95], v[188:191], v[108:111]
	v_mfma_f32_16x16x32_bf16 v[104:107], v[158:161], v[188:191], v[104:107]
	v_mfma_f32_16x16x32_bf16 v[100:103], v[92:95], v[234:237], v[100:103]
	v_mfma_f32_16x16x32_bf16 v[96:99], v[158:161], v[234:237], v[96:99]
	s_barrier
	s_setprio 0
	s_nop 7
	s_add_i32 s32, s33, s72
	s_mov_b32 m0, s32
	s_add_u32 s10, s58, 0x80
	s_addc_u32 s11, s59, 0
	ds_read_b128 v[162:165], v232 offset:49152
	ds_read_b128 v[166:169], v232 offset:50176
	ds_read_b128 v[170:173], v232 offset:51200
	ds_read_b128 v[174:177], v232 offset:52224
	ds_read_b128 v[180:183], v232 offset:53248
	ds_read_b128 v[188:191], v232 offset:54272
	ds_read_b128 v[208:211], v232 offset:55296
	ds_read_b128 v[234:237], v232 offset:56320
	global_load_lds_dwordx4 v144, s[10:11]
	s_add_i32 m0, s32, 0x2000
	s_add_i32 s33, vcc_hi, s72
	s_nop 0
	global_load_lds_dwordx4 v178, s[10:11]
	s_add_u32 s10, s58, 0x100080
	s_addc_u32 s11, s59, 0
	s_mov_b32 m0, s33
	s_nop 0
	global_load_lds_dwordx4 v144, s[10:11]
	s_add_i32 m0, s33, 0x2000
	s_nop 0
	global_load_lds_dwordx4 v178, s[10:11]
	s_add_u32 s10, s60, 0x80
	s_addc_u32 s11, s61, 0
	s_mov_b32 m0, s81
	s_nop 0
	global_load_lds_dwordx4 v198, s[10:11]
	s_mov_b32 m0, s91
	s_nop 0
	global_load_lds_dwordx4 v196, s[10:11]
	s_waitcnt vmcnt(8)
	s_waitcnt lgkmcnt(0)
	s_setprio 1
	s_barrier
	v_mfma_f32_16x16x32_bf16 v[52:55], v[72:75], v[162:165], v[52:55]
	v_mfma_f32_16x16x32_bf16 v[48:51], v[80:83], v[162:165], v[48:51]
	v_mfma_f32_16x16x32_bf16 v[28:31], v[72:75], v[170:173], v[28:31]
	v_mfma_f32_16x16x32_bf16 v[24:27], v[80:83], v[170:173], v[24:27]
	v_mfma_f32_16x16x32_bf16 v[36:39], v[72:75], v[180:183], v[36:39]
	v_mfma_f32_16x16x32_bf16 v[32:35], v[80:83], v[180:183], v[32:35]
	v_mfma_f32_16x16x32_bf16 v[60:63], v[72:75], v[208:211], v[60:63]
	v_mfma_f32_16x16x32_bf16 v[56:59], v[80:83], v[208:211], v[56:59]
	v_mfma_f32_16x16x32_bf16 v[52:55], v[76:79], v[166:169], v[52:55]
	v_mfma_f32_16x16x32_bf16 v[48:51], v[84:87], v[166:169], v[48:51]
	v_mfma_f32_16x16x32_bf16 v[28:31], v[76:79], v[174:177], v[28:31]
	v_mfma_f32_16x16x32_bf16 v[24:27], v[84:87], v[174:177], v[24:27]
	v_mfma_f32_16x16x32_bf16 v[36:39], v[76:79], v[188:191], v[36:39]
	v_mfma_f32_16x16x32_bf16 v[32:35], v[84:87], v[188:191], v[32:35]
	v_mfma_f32_16x16x32_bf16 v[60:63], v[76:79], v[234:237], v[60:63]
	v_mfma_f32_16x16x32_bf16 v[56:59], v[84:87], v[234:237], v[56:59]
	v_mfma_f32_16x16x32_bf16 v[44:47], v[88:91], v[162:165], v[44:47]
	v_mfma_f32_16x16x32_bf16 v[40:43], v[154:157], v[162:165], v[40:43]
	v_mfma_f32_16x16x32_bf16 v[4:7], v[88:91], v[170:173], v[4:7]
	v_mfma_f32_16x16x32_bf16 v[0:3], v[154:157], v[170:173], v[0:3]
	v_mfma_f32_16x16x32_bf16 v[16:19], v[88:91], v[180:183], v[16:19]
	v_mfma_f32_16x16x32_bf16 v[12:15], v[154:157], v[180:183], v[12:15]
	v_mfma_f32_16x16x32_bf16 v[20:23], v[88:91], v[208:211], v[20:23]
	v_mfma_f32_16x16x32_bf16 v[8:11], v[154:157], v[208:211], v[8:11]
	v_mfma_f32_16x16x32_bf16 v[44:47], v[92:95], v[166:169], v[44:47]
	v_mfma_f32_16x16x32_bf16 v[40:43], v[158:161], v[166:169], v[40:43]
	v_mfma_f32_16x16x32_bf16 v[4:7], v[92:95], v[174:177], v[4:7]
	v_mfma_f32_16x16x32_bf16 v[0:3], v[158:161], v[174:177], v[0:3]
	v_mfma_f32_16x16x32_bf16 v[16:19], v[92:95], v[188:191], v[16:19]
	v_mfma_f32_16x16x32_bf16 v[12:15], v[158:161], v[188:191], v[12:15]
	v_mfma_f32_16x16x32_bf16 v[20:23], v[92:95], v[234:237], v[20:23]
	v_mfma_f32_16x16x32_bf16 v[8:11], v[158:161], v[234:237], v[8:11]
	s_barrier
	s_setprio 0
	s_nop 7
	s_add_i32 vcc_lo, vcc_lo, 2
	s_add_u32 s95, s95, 0x100
	s_addc_u32 s97, s97, 0
	s_add_u32 s56, s56, 0x100
	s_addc_u32 s57, s57, 0
	s_cmp_gt_u32 vcc_lo, 61
	s_cbranch_scc0 .LBB0_2147
	s_and_b64 vcc, exec, s[34:35]
	s_cbranch_vccz .LBB0_2150
	s_barrier

.LBB0_2353:
	s_add_u32 s47, s22, 0x100
	v_mov_b32_e32 v0, 0
	s_addc_u32 s48, s23, 0
	s_mov_b32 s49, -2
	v_mov_b32_e32 v1, v0
	v_mov_b32_e32 v2, v0
	v_mov_b32_e32 v3, v0
	v_mov_b32_e32 v4, v0
	v_mov_b32_e32 v5, v0
	v_mov_b32_e32 v6, v0
	v_mov_b32_e32 v7, v0
	v_mov_b32_e32 v16, v0
	v_mov_b32_e32 v17, v0
	v_mov_b32_e32 v18, v0
	v_mov_b32_e32 v19, v0
	v_mov_b32_e32 v20, v0
	v_mov_b32_e32 v21, v0
	v_mov_b32_e32 v22, v0
	v_mov_b32_e32 v23, v0
	v_mov_b32_e32 v32, v0
	v_mov_b32_e32 v33, v0
	v_mov_b32_e32 v34, v0
	v_mov_b32_e32 v35, v0
	v_mov_b32_e32 v36, v0
	v_mov_b32_e32 v37, v0
	v_mov_b32_e32 v38, v0
	v_mov_b32_e32 v39, v0
	v_mov_b32_e32 v48, v0
	v_mov_b32_e32 v49, v0
	v_mov_b32_e32 v50, v0
	v_mov_b32_e32 v51, v0
	v_mov_b32_e32 v52, v0
	v_mov_b32_e32 v53, v0
	v_mov_b32_e32 v54, v0
	v_mov_b32_e32 v55, v0
	v_mov_b32_e32 v8, v0
	v_mov_b32_e32 v9, v0
	v_mov_b32_e32 v10, v0
	v_mov_b32_e32 v11, v0
	v_mov_b32_e32 v12, v0
	v_mov_b32_e32 v13, v0
	v_mov_b32_e32 v14, v0
	v_mov_b32_e32 v15, v0
	v_mov_b32_e32 v24, v0
	v_mov_b32_e32 v25, v0
	v_mov_b32_e32 v26, v0
	v_mov_b32_e32 v27, v0
	v_mov_b32_e32 v28, v0
	v_mov_b32_e32 v29, v0
	v_mov_b32_e32 v30, v0
	v_mov_b32_e32 v31, v0
	v_mov_b32_e32 v40, v0
	v_mov_b32_e32 v41, v0
	v_mov_b32_e32 v42, v0
	v_mov_b32_e32 v43, v0
	v_mov_b32_e32 v44, v0
	v_mov_b32_e32 v45, v0
	v_mov_b32_e32 v46, v0
	v_mov_b32_e32 v47, v0
	v_mov_b32_e32 v56, v0
	v_mov_b32_e32 v57, v0
	v_mov_b32_e32 v58, v0
	v_mov_b32_e32 v59, v0
	v_mov_b32_e32 v60, v0
	v_mov_b32_e32 v61, v0
	v_mov_b32_e32 v62, v0
	v_mov_b32_e32 v63, v0
	v_mov_b32_e32 v64, v0
	v_mov_b32_e32 v65, v0
	v_mov_b32_e32 v66, v0
	v_mov_b32_e32 v67, v0
	v_mov_b32_e32 v68, v0
	v_mov_b32_e32 v69, v0
	v_mov_b32_e32 v70, v0
	v_mov_b32_e32 v71, v0
	v_mov_b32_e32 v80, v0
	v_mov_b32_e32 v81, v0
	v_mov_b32_e32 v82, v0
	v_mov_b32_e32 v83, v0
	v_mov_b32_e32 v84, v0
	v_mov_b32_e32 v85, v0
	v_mov_b32_e32 v86, v0
	v_mov_b32_e32 v87, v0
	v_mov_b32_e32 v96, v0
	v_mov_b32_e32 v97, v0
	v_mov_b32_e32 v98, v0
	v_mov_b32_e32 v99, v0
	v_mov_b32_e32 v100, v0
	v_mov_b32_e32 v101, v0
	v_mov_b32_e32 v102, v0
	v_mov_b32_e32 v103, v0
	v_mov_b32_e32 v112, v0
	v_mov_b32_e32 v113, v0
	v_mov_b32_e32 v114, v0
	v_mov_b32_e32 v115, v0
	v_mov_b32_e32 v116, v0
	v_mov_b32_e32 v117, v0
	v_mov_b32_e32 v118, v0
	v_mov_b32_e32 v119, v0
	v_mov_b32_e32 v72, v0
	v_mov_b32_e32 v73, v0
	v_mov_b32_e32 v74, v0
	v_mov_b32_e32 v75, v0
	v_mov_b32_e32 v76, v0
	v_mov_b32_e32 v77, v0
	v_mov_b32_e32 v78, v0
	v_mov_b32_e32 v79, v0
	v_mov_b32_e32 v88, v0
	v_mov_b32_e32 v89, v0
	v_mov_b32_e32 v90, v0
	v_mov_b32_e32 v91, v0
	v_mov_b32_e32 v92, v0
	v_mov_b32_e32 v93, v0
	v_mov_b32_e32 v94, v0
	v_mov_b32_e32 v95, v0
	v_mov_b32_e32 v104, v0
	v_mov_b32_e32 v105, v0
	v_mov_b32_e32 v106, v0
	v_mov_b32_e32 v107, v0
	v_mov_b32_e32 v108, v0
	v_mov_b32_e32 v109, v0
	v_mov_b32_e32 v110, v0
	v_mov_b32_e32 v111, v0
	v_mov_b32_e32 v120, v0
	v_mov_b32_e32 v121, v0
	v_mov_b32_e32 v122, v0
	v_mov_b32_e32 v123, v0
	v_mov_b32_e32 v124, v0
	v_mov_b32_e32 v125, v0
	v_mov_b32_e32 v126, v0
	v_mov_b32_e32 v127, v0
	v_add_u32_e32 v244, 0x10000, v143
.LBB0_2354:
	s_add_u32 s22, s20, 0x100
	s_addc_u32 s23, s21, 0
	s_add_i32 s10, 0, 0x10000
	s_cmpk_eq_i32 s49, 0xa8
	s_cselect_b32 s27, s7, s23
	s_cselect_b32 s26, s6, s22
	s_cselect_b32 s25, s19, s48
	s_cselect_b32 s24, s18, s47
	s_add_i32 s33, 0, 0x14000
	ds_read_b128 v[138:141], v244
	ds_read_b128 v[148:151], v244 offset:1024
	ds_read_b128 v[152:155], v244 offset:2048
	ds_read_b128 v[156:159], v244 offset:3072
	ds_read_b128 v[160:163], v244 offset:16384
	ds_read_b128 v[164:167], v244 offset:17408
	ds_read_b128 v[168:171], v244 offset:18432
	ds_read_b128 v[172:175], v244 offset:19456
	s_add_i32 m0, s35, 0xc000
	ds_read_b128 v[176:179], v147
	ds_read_b128 v[180:183], v147 offset:1024
	ds_read_b128 v[188:191], v147 offset:2048
	ds_read_b128 v[196:199], v147 offset:3072
	ds_read_b128 v[200:203], v147 offset:4096
	ds_read_b128 v[204:207], v147 offset:5120
	ds_read_b128 v[208:211], v147 offset:6144
	ds_read_b128 v[212:215], v147 offset:7168
	global_load_lds_dwordx4 v136, s[20:21]
	s_add_i32 m0, s35, 0xe000
	s_nop 0
	global_load_lds_dwordx4 v134, s[20:21]
	s_waitcnt vmcnt(8)
	s_waitcnt lgkmcnt(0)
	s_setprio 1
	s_barrier
	v_mfma_f32_16x16x32_bf16 v[124:127], v[138:141], v[176:179], v[124:127]
	v_mfma_f32_16x16x32_bf16 v[120:123], v[152:155], v[176:179], v[120:123]
	v_mfma_f32_16x16x32_bf16 v[108:111], v[138:141], v[188:191], v[108:111]
	v_mfma_f32_16x16x32_bf16 v[104:107], v[152:155], v[188:191], v[104:107]
	v_mfma_f32_16x16x32_bf16 v[92:95], v[138:141], v[200:203], v[92:95]
	v_mfma_f32_16x16x32_bf16 v[88:91], v[152:155], v[200:203], v[88:91]
	v_mfma_f32_16x16x32_bf16 v[76:79], v[138:141], v[208:211], v[76:79]
	v_mfma_f32_16x16x32_bf16 v[72:75], v[152:155], v[208:211], v[72:75]
	v_mfma_f32_16x16x32_bf16 v[124:127], v[148:151], v[180:183], v[124:127]
	v_mfma_f32_16x16x32_bf16 v[120:123], v[156:159], v[180:183], v[120:123]
	v_mfma_f32_16x16x32_bf16 v[108:111], v[148:151], v[196:199], v[108:111]
	v_mfma_f32_16x16x32_bf16 v[104:107], v[156:159], v[196:199], v[104:107]
	v_mfma_f32_16x16x32_bf16 v[92:95], v[148:151], v[204:207], v[92:95]
	v_mfma_f32_16x16x32_bf16 v[88:91], v[156:159], v[204:207], v[88:91]
	v_mfma_f32_16x16x32_bf16 v[76:79], v[148:151], v[212:215], v[76:79]
	v_mfma_f32_16x16x32_bf16 v[72:75], v[156:159], v[212:215], v[72:75]
	v_mfma_f32_16x16x32_bf16 v[116:119], v[160:163], v[176:179], v[116:119]
	v_mfma_f32_16x16x32_bf16 v[112:115], v[168:171], v[176:179], v[112:115]
	v_mfma_f32_16x16x32_bf16 v[100:103], v[160:163], v[188:191], v[100:103]
	v_mfma_f32_16x16x32_bf16 v[96:99], v[168:171], v[188:191], v[96:99]
	v_mfma_f32_16x16x32_bf16 v[84:87], v[160:163], v[200:203], v[84:87]
	v_mfma_f32_16x16x32_bf16 v[80:83], v[168:171], v[200:203], v[80:83]
	v_mfma_f32_16x16x32_bf16 v[68:71], v[160:163], v[208:211], v[68:71]
	v_mfma_f32_16x16x32_bf16 v[64:67], v[168:171], v[208:211], v[64:67]
	v_mfma_f32_16x16x32_bf16 v[116:119], v[164:167], v[180:183], v[116:119]
	v_mfma_f32_16x16x32_bf16 v[112:115], v[172:175], v[180:183], v[112:115]
	v_mfma_f32_16x16x32_bf16 v[100:103], v[164:167], v[196:199], v[100:103]
	v_mfma_f32_16x16x32_bf16 v[96:99], v[172:175], v[196:199], v[96:99]
	v_mfma_f32_16x16x32_bf16 v[84:87], v[164:167], v[204:207], v[84:87]
	v_mfma_f32_16x16x32_bf16 v[80:83], v[172:175], v[204:207], v[80:83]
	v_mfma_f32_16x16x32_bf16 v[68:71], v[164:167], v[212:215], v[68:71]
	v_mfma_f32_16x16x32_bf16 v[64:67], v[172:175], v[212:215], v[64:67]
	s_barrier
	s_setprio 0
	s_nop 7
	s_add_i32 s10, s10, s34
	s_mov_b32 m0, s10
	ds_read_b128 v[176:179], v147 offset:16384
	ds_read_b128 v[180:183], v147 offset:17408
	ds_read_b128 v[188:191], v147 offset:18432
	ds_read_b128 v[196:199], v147 offset:19456
	ds_read_b128 v[200:203], v147 offset:20480
	ds_read_b128 v[204:207], v147 offset:21504
	ds_read_b128 v[208:211], v147 offset:22528
	ds_read_b128 v[212:215], v147 offset:23552
	global_load_lds_dwordx4 v144, s[24:25]
	s_add_i32 m0, s10, 0x2000
	s_add_u32 s10, s24, 0x2b0000
	s_addc_u32 s11, s25, 0
	s_add_i32 s20, s33, s34
	global_load_lds_dwordx4 v128, s[24:25]
	s_mov_b32 m0, s20
	s_nop 0
	global_load_lds_dwordx4 v144, s[10:11]
	s_add_i32 m0, s20, 0x2000
	s_nop 0
	global_load_lds_dwordx4 v128, s[10:11]
	s_mov_b32 m0, s35
	s_nop 0
	global_load_lds_dwordx4 v132, s[26:27]
	s_mov_b32 m0, s36
	s_nop 0
	global_load_lds_dwordx4 v130, s[26:27]
	s_waitcnt vmcnt(8)
	s_waitcnt lgkmcnt(0)
	s_setprio 1
	s_barrier
	v_mfma_f32_16x16x32_bf16 v[60:63], v[138:141], v[176:179], v[60:63]
	v_mfma_f32_16x16x32_bf16 v[56:59], v[152:155], v[176:179], v[56:59]
	v_mfma_f32_16x16x32_bf16 v[44:47], v[138:141], v[188:191], v[44:47]
	v_mfma_f32_16x16x32_bf16 v[40:43], v[152:155], v[188:191], v[40:43]
	v_mfma_f32_16x16x32_bf16 v[28:31], v[138:141], v[200:203], v[28:31]
	v_mfma_f32_16x16x32_bf16 v[24:27], v[152:155], v[200:203], v[24:27]
	v_mfma_f32_16x16x32_bf16 v[12:15], v[138:141], v[208:211], v[12:15]
	v_mfma_f32_16x16x32_bf16 v[8:11], v[152:155], v[208:211], v[8:11]
	v_mfma_f32_16x16x32_bf16 v[60:63], v[148:151], v[180:183], v[60:63]
	v_mfma_f32_16x16x32_bf16 v[56:59], v[156:159], v[180:183], v[56:59]
	v_mfma_f32_16x16x32_bf16 v[44:47], v[148:151], v[196:199], v[44:47]
	v_mfma_f32_16x16x32_bf16 v[40:43], v[156:159], v[196:199], v[40:43]
	v_mfma_f32_16x16x32_bf16 v[28:31], v[148:151], v[204:207], v[28:31]
	v_mfma_f32_16x16x32_bf16 v[24:27], v[156:159], v[204:207], v[24:27]
	v_mfma_f32_16x16x32_bf16 v[12:15], v[148:151], v[212:215], v[12:15]
	v_mfma_f32_16x16x32_bf16 v[8:11], v[156:159], v[212:215], v[8:11]
	v_mfma_f32_16x16x32_bf16 v[52:55], v[160:163], v[176:179], v[52:55]
	v_mfma_f32_16x16x32_bf16 v[48:51], v[168:171], v[176:179], v[48:51]
	v_mfma_f32_16x16x32_bf16 v[36:39], v[160:163], v[188:191], v[36:39]
	v_mfma_f32_16x16x32_bf16 v[32:35], v[168:171], v[188:191], v[32:35]
	v_mfma_f32_16x16x32_bf16 v[20:23], v[160:163], v[200:203], v[20:23]
	v_mfma_f32_16x16x32_bf16 v[16:19], v[168:171], v[200:203], v[16:19]
	v_mfma_f32_16x16x32_bf16 v[4:7], v[160:163], v[208:211], v[4:7]
	v_mfma_f32_16x16x32_bf16 v[0:3], v[168:171], v[208:211], v[0:3]
	v_mfma_f32_16x16x32_bf16 v[52:55], v[164:167], v[180:183], v[52:55]
	v_mfma_f32_16x16x32_bf16 v[48:51], v[172:175], v[180:183], v[48:51]
	v_mfma_f32_16x16x32_bf16 v[36:39], v[164:167], v[196:199], v[36:39]
	v_mfma_f32_16x16x32_bf16 v[32:35], v[172:175], v[196:199], v[32:35]
	v_mfma_f32_16x16x32_bf16 v[20:23], v[164:167], v[204:207], v[20:23]
	v_mfma_f32_16x16x32_bf16 v[16:19], v[172:175], v[204:207], v[16:19]
	v_mfma_f32_16x16x32_bf16 v[4:7], v[164:167], v[212:215], v[4:7]
	v_mfma_f32_16x16x32_bf16 v[0:3], v[172:175], v[212:215], v[0:3]
	s_barrier
	s_setprio 0
	s_nop 7
	s_add_i32 s20, 0, 0x18000
	s_add_i32 s21, 0, 0x1c000
	ds_read_b128 v[138:141], v244 offset:32768
	ds_read_b128 v[148:151], v244 offset:33792
	ds_read_b128 v[152:155], v244 offset:34816
	ds_read_b128 v[156:159], v244 offset:35840
	ds_read_b128 v[160:163], v244 offset:49152
	ds_read_b128 v[164:167], v244 offset:50176
	ds_read_b128 v[168:171], v244 offset:51200
	ds_read_b128 v[172:175], v244 offset:52224
	s_add_u32 s10, s26, 0x2b0000
	s_addc_u32 s11, s27, 0
	s_mov_b32 m0, s37
	ds_read_b128 v[176:179], v147 offset:32768
	ds_read_b128 v[180:183], v147 offset:33792
	ds_read_b128 v[188:191], v147 offset:34816
	ds_read_b128 v[196:199], v147 offset:35840
	ds_read_b128 v[200:203], v147 offset:36864
	ds_read_b128 v[204:207], v147 offset:37888
	ds_read_b128 v[208:211], v147 offset:38912
	ds_read_b128 v[212:215], v147 offset:39936
	global_load_lds_dwordx4 v132, s[10:11]
	s_mov_b32 m0, s38
	s_nop 0
	global_load_lds_dwordx4 v130, s[10:11]
	s_waitcnt vmcnt(8)
	s_waitcnt lgkmcnt(0)
	s_setprio 1
	s_barrier
	v_mfma_f32_16x16x32_bf16 v[124:127], v[138:141], v[176:179], v[124:127]
	v_mfma_f32_16x16x32_bf16 v[120:123], v[152:155], v[176:179], v[120:123]
	v_mfma_f32_16x16x32_bf16 v[108:111], v[138:141], v[188:191], v[108:111]
	v_mfma_f32_16x16x32_bf16 v[104:107], v[152:155], v[188:191], v[104:107]
	v_mfma_f32_16x16x32_bf16 v[92:95], v[138:141], v[200:203], v[92:95]
	v_mfma_f32_16x16x32_bf16 v[88:91], v[152:155], v[200:203], v[88:91]
	v_mfma_f32_16x16x32_bf16 v[76:79], v[138:141], v[208:211], v[76:79]
	v_mfma_f32_16x16x32_bf16 v[72:75], v[152:155], v[208:211], v[72:75]
	v_mfma_f32_16x16x32_bf16 v[124:127], v[148:151], v[180:183], v[124:127]
	v_mfma_f32_16x16x32_bf16 v[120:123], v[156:159], v[180:183], v[120:123]
	v_mfma_f32_16x16x32_bf16 v[108:111], v[148:151], v[196:199], v[108:111]
	v_mfma_f32_16x16x32_bf16 v[104:107], v[156:159], v[196:199], v[104:107]
	v_mfma_f32_16x16x32_bf16 v[92:95], v[148:151], v[204:207], v[92:95]
	v_mfma_f32_16x16x32_bf16 v[88:91], v[156:159], v[204:207], v[88:91]
	v_mfma_f32_16x16x32_bf16 v[76:79], v[148:151], v[212:215], v[76:79]
	v_mfma_f32_16x16x32_bf16 v[72:75], v[156:159], v[212:215], v[72:75]
	v_mfma_f32_16x16x32_bf16 v[116:119], v[160:163], v[176:179], v[116:119]
	v_mfma_f32_16x16x32_bf16 v[112:115], v[168:171], v[176:179], v[112:115]
	v_mfma_f32_16x16x32_bf16 v[100:103], v[160:163], v[188:191], v[100:103]
	v_mfma_f32_16x16x32_bf16 v[96:99], v[168:171], v[188:191], v[96:99]
	v_mfma_f32_16x16x32_bf16 v[84:87], v[160:163], v[200:203], v[84:87]
	v_mfma_f32_16x16x32_bf16 v[80:83], v[168:171], v[200:203], v[80:83]
	v_mfma_f32_16x16x32_bf16 v[68:71], v[160:163], v[208:211], v[68:71]
	v_mfma_f32_16x16x32_bf16 v[64:67], v[168:171], v[208:211], v[64:67]
	v_mfma_f32_16x16x32_bf16 v[116:119], v[164:167], v[180:183], v[116:119]
	v_mfma_f32_16x16x32_bf16 v[112:115], v[172:175], v[180:183], v[112:115]
	v_mfma_f32_16x16x32_bf16 v[100:103], v[164:167], v[196:199], v[100:103]
	v_mfma_f32_16x16x32_bf16 v[96:99], v[172:175], v[196:199], v[96:99]
	v_mfma_f32_16x16x32_bf16 v[84:87], v[164:167], v[204:207], v[84:87]
	v_mfma_f32_16x16x32_bf16 v[80:83], v[172:175], v[204:207], v[80:83]
	v_mfma_f32_16x16x32_bf16 v[68:71], v[164:167], v[212:215], v[68:71]
	v_mfma_f32_16x16x32_bf16 v[64:67], v[172:175], v[212:215], v[64:67]
	s_barrier
	s_setprio 0
	s_nop 7
	s_add_i32 s32, s20, s34
	s_mov_b32 m0, s32
	s_add_u32 s10, s24, 0x80
	s_addc_u32 s11, s25, 0
	ds_read_b128 v[176:179], v147 offset:49152
	ds_read_b128 v[180:183], v147 offset:50176
	ds_read_b128 v[188:191], v147 offset:51200
	ds_read_b128 v[196:199], v147 offset:52224
	ds_read_b128 v[200:203], v147 offset:53248
	ds_read_b128 v[204:207], v147 offset:54272
	ds_read_b128 v[208:211], v147 offset:55296
	ds_read_b128 v[212:215], v147 offset:56320
	global_load_lds_dwordx4 v144, s[10:11]
	s_add_i32 m0, s32, 0x2000
	s_add_i32 s20, s21, s34
	s_nop 0
	global_load_lds_dwordx4 v128, s[10:11]
	s_add_u32 s10, s24, 0x2b0080
	s_addc_u32 s11, s25, 0
	s_mov_b32 m0, s20
	s_nop 0
	global_load_lds_dwordx4 v144, s[10:11]
	s_add_i32 m0, s20, 0x2000
	s_nop 0
	global_load_lds_dwordx4 v128, s[10:11]
	s_add_u32 s10, s26, 0x80
	s_addc_u32 s11, s27, 0
	s_mov_b32 m0, s40
	s_nop 0
	global_load_lds_dwordx4 v132, s[10:11]
	s_mov_b32 m0, s41
	s_nop 0
	global_load_lds_dwordx4 v130, s[10:11]
	s_waitcnt vmcnt(8)
	s_waitcnt lgkmcnt(0)
	s_setprio 1
	s_barrier
	v_mfma_f32_16x16x32_bf16 v[60:63], v[138:141], v[176:179], v[60:63]
	v_mfma_f32_16x16x32_bf16 v[56:59], v[152:155], v[176:179], v[56:59]
	v_mfma_f32_16x16x32_bf16 v[44:47], v[138:141], v[188:191], v[44:47]
	v_mfma_f32_16x16x32_bf16 v[40:43], v[152:155], v[188:191], v[40:43]
	v_mfma_f32_16x16x32_bf16 v[28:31], v[138:141], v[200:203], v[28:31]
	v_mfma_f32_16x16x32_bf16 v[24:27], v[152:155], v[200:203], v[24:27]
	v_mfma_f32_16x16x32_bf16 v[12:15], v[138:141], v[208:211], v[12:15]
	v_mfma_f32_16x16x32_bf16 v[8:11], v[152:155], v[208:211], v[8:11]
	v_mfma_f32_16x16x32_bf16 v[60:63], v[148:151], v[180:183], v[60:63]
	v_mfma_f32_16x16x32_bf16 v[56:59], v[156:159], v[180:183], v[56:59]
	v_mfma_f32_16x16x32_bf16 v[44:47], v[148:151], v[196:199], v[44:47]
	v_mfma_f32_16x16x32_bf16 v[40:43], v[156:159], v[196:199], v[40:43]
	v_mfma_f32_16x16x32_bf16 v[28:31], v[148:151], v[204:207], v[28:31]
	v_mfma_f32_16x16x32_bf16 v[24:27], v[156:159], v[204:207], v[24:27]
	v_mfma_f32_16x16x32_bf16 v[12:15], v[148:151], v[212:215], v[12:15]
	v_mfma_f32_16x16x32_bf16 v[8:11], v[156:159], v[212:215], v[8:11]
	v_mfma_f32_16x16x32_bf16 v[52:55], v[160:163], v[176:179], v[52:55]
	v_mfma_f32_16x16x32_bf16 v[48:51], v[168:171], v[176:179], v[48:51]
	v_mfma_f32_16x16x32_bf16 v[36:39], v[160:163], v[188:191], v[36:39]
	v_mfma_f32_16x16x32_bf16 v[32:35], v[168:171], v[188:191], v[32:35]
	v_mfma_f32_16x16x32_bf16 v[20:23], v[160:163], v[200:203], v[20:23]
	v_mfma_f32_16x16x32_bf16 v[16:19], v[168:171], v[200:203], v[16:19]
	v_mfma_f32_16x16x32_bf16 v[4:7], v[160:163], v[208:211], v[4:7]
	v_mfma_f32_16x16x32_bf16 v[0:3], v[168:171], v[208:211], v[0:3]
	v_mfma_f32_16x16x32_bf16 v[52:55], v[164:167], v[180:183], v[52:55]
	v_mfma_f32_16x16x32_bf16 v[48:51], v[172:175], v[180:183], v[48:51]
	v_mfma_f32_16x16x32_bf16 v[36:39], v[164:167], v[196:199], v[36:39]
	v_mfma_f32_16x16x32_bf16 v[32:35], v[172:175], v[196:199], v[32:35]
	v_mfma_f32_16x16x32_bf16 v[20:23], v[164:167], v[204:207], v[20:23]
	v_mfma_f32_16x16x32_bf16 v[16:19], v[172:175], v[204:207], v[16:19]
	v_mfma_f32_16x16x32_bf16 v[4:7], v[164:167], v[212:215], v[4:7]
	v_mfma_f32_16x16x32_bf16 v[0:3], v[172:175], v[212:215], v[0:3]
	s_barrier
	s_setprio 0
	s_nop 7
	s_add_i32 s49, s49, 2
	s_add_u32 s47, s47, 0x100
	s_addc_u32 s48, s48, 0
	s_cmpk_gt_u32 s49, 0xa9
	s_mov_b64 s[20:21], s[22:23]
	s_cbranch_scc0 .LBB0_2354
	s_and_b64 vcc, exec, s[16:17]
	s_cbranch_vccz .LBB0_2357
	s_barrier
